# GEMM K-loops: back edge rotated - counter updates and next-iteration address selects moved in front of the loop-back barrier (exit path keeps its own barrier)
# baseline (speedup 1.0000x reference)
; #define PG8_STAGE(bufoff, gbase, voff) do { _Pragma("unroll") for (int _i = 0; _i < 2; ++_i) \
;         __builtin_amdgcn_global_load_lds((const unsigned*)((const char*)(gbase) + (voff)[_i]), (PG8_LAS unsigned*)(lds + (bufoff) + ldsw + _i * 8192), 16, 0, 0); } while (0)
; #define PG8_LDA(dst, b, h) do { _Pragma("unroll") for (int m = 0; m < 4; ++m) _Pragma("unroll") for (int k = 0; k < 2; ++k) dst[m][k] = *(const PG8_LAS bf16x8*)(lds + PG8_SA(b, h) + aoff + m * 2048 + k * 1024); } while (0)
; #define PG8_LDB(dst, b, h) do { _Pragma("unroll") for (int n = 0; n < 2; ++n) _Pragma("unroll") for (int k = 0; k < 2; ++k) dst[n][k] = *(const PG8_LAS bf16x8*)(lds + PG8_SB(b, h) + boff + n * 2048 + k * 1024); } while (0)
; #define PG8_MMA(ai, bj, At, Bt) do { __builtin_amdgcn_s_setprio(1); _Pragma("unroll") for (int m = 0; m < 4; ++m) _Pragma("unroll") for (int n = 0; n < 2; ++n) _Pragma("unroll") for (int k = 0; k < 2; ++k) \
;         acc[ai][bj][m][n] = __builtin_amdgcn_mfma_f32_16x16x32_bf16(Bt[n][k], At[m][k], acc[ai][bj][m][n], 0, 0, 0); __builtin_amdgcn_s_setprio(0); } while (0)
; #define PG8_WAIT_V(n) asm volatile("s_waitcnt vmcnt(" #n ")" ::: "memory")
; #define PG8_BAR __builtin_amdgcn_s_barrier()
; template <class Epi, class Sched, bool ALIGN_EPI = false, bool SP2 = false>
; __device__ __forceinline__ void gemm_phase(PG8_LAS unsigned char* lds, const Gemm g, const Sched& S, const Epi& E) {
;     ...
;         for (int t = 0; t < nt; t += 2) {
;             const bool last = (t == nt - 2);
;             const char* a1 = cA + (size_t)(t + 1) * kstep;
;             const char* a2 = last ? nA : cA + (size_t)(t + 2) * kstep; const char* b2 = last ? nB : cB + (size_t)(t + 2) * kstep;
;             const char* a3 = a2 + kstep; const char* b3 = b2 + kstep;
;             if (last && has_next) S.a_ready(nxt);
;             if constexpr (SP2) {
;             PG8_LDB(B0, 0, 0); PG8_LDB(B1, 0, 1); PG8_SCHED; PG8_LDA(At, 0, 0); PG8_STAGE(PG8_SA(1, 1), a1 + hstep, voffA);
;             PG8_WAIT_V(8); PG8_WAIT_L(0); PG8_BAR; PG8_MMA(0, 0, At, B0); PG8_MMA(0, 1, At, B1); PG8_BAR; PG8_SCHED;
;             PG8_LDA(At, 0, 1); PG8_STAGE(PG8_SB(0, 0), b2, voffB); PG8_STAGE(PG8_SB(0, 1), b2 + hstep, voffB); PG8_STAGE(PG8_SA(0, 0), a2, voffA);
;             PG8_WAIT_V(8); PG8_WAIT_L(0); PG8_BAR; PG8_MMA(1, 0, At, B0); PG8_MMA(1, 1, At, B1); PG8_BAR; PG8_SCHED;
.Lpeel_p1:
	s_add_u32 s10, s8, 0xfffc0080
	s_addc_u32 s11, s9, -1
	s_add_i32 s30, 0, 0x10000
	s_cmp_eq_u32 s43, 12
	s_cselect_b32 s15, s33, s11
	s_cselect_b32 s14, s34, s10
	v_add_u32_e32 v0, s30, v204
	s_cselect_b32 s11, s35, s42
	s_cselect_b32 s10, s40, s41
	s_add_i32 s51, 0, 0x14000
	ds_read_b128 v[18:21], v0
	ds_read_b128 v[22:25], v0 offset:1024
	ds_read_b128 v[26:29], v0 offset:2048
	ds_read_b128 v[30:33], v0 offset:3072
	v_add_u32_e32 v0, s51, v204
	ds_read_b128 v[46:49], v0
	ds_read_b128 v[54:57], v0 offset:1024
	ds_read_b128 v[170:173], v0 offset:2048
	ds_read_b128 v[174:177], v0 offset:3072
	v_lshl_add_u64 v[190:191], s[8:9], 0, v[166:167]
	s_add_i32 m0, s21, 0xc000
	ds_read_b128 v[178:181], v225
	ds_read_b128 v[182:185], v225 offset:1024
	ds_read_b128 v[186:189], v225 offset:2048
	ds_read_b128 v[226:229], v225 offset:3072
	ds_read_b128 v[230:233], v225 offset:4096
	ds_read_b128 v[234:237], v225 offset:5120
	ds_read_b128 v[238:241], v225 offset:6144
	ds_read_b128 v[242:245], v225 offset:7168
	global_load_lds_dwordx4 v[190:191], off
	v_lshl_add_u64 v[190:191], s[8:9], 0, v[168:169]
	s_add_i32 m0, s21, 0xe000
	s_nop 0
	global_load_lds_dwordx4 v[190:191], off
	s_waitcnt vmcnt(8)
	s_waitcnt lgkmcnt(0)
	s_barrier
	s_setprio 1
	s_waitcnt lgkmcnt(0)
	v_mfma_f32_16x16x32_bf16 v[150:153], v[18:21], v[178:181], 0
	v_mfma_f32_16x16x32_bf16 v[146:149], v[26:29], v[178:181], 0
	v_mfma_f32_16x16x32_bf16 v[134:137], v[18:21], v[186:189], 0
	v_mfma_f32_16x16x32_bf16 v[130:133], v[26:29], v[186:189], 0
	v_mfma_f32_16x16x32_bf16 v[118:121], v[18:21], v[230:233], 0
	v_mfma_f32_16x16x32_bf16 v[114:117], v[26:29], v[230:233], 0
	v_mfma_f32_16x16x32_bf16 v[102:105], v[18:21], v[238:241], 0
	v_mfma_f32_16x16x32_bf16 v[98:101], v[26:29], v[238:241], 0
	v_mfma_f32_16x16x32_bf16 v[150:153], v[22:25], v[182:185], v[150:153]
	v_mfma_f32_16x16x32_bf16 v[146:149], v[30:33], v[182:185], v[146:149]
	v_mfma_f32_16x16x32_bf16 v[134:137], v[22:25], v[226:229], v[134:137]
	v_mfma_f32_16x16x32_bf16 v[130:133], v[30:33], v[226:229], v[130:133]
	v_mfma_f32_16x16x32_bf16 v[118:121], v[22:25], v[234:237], v[118:121]
	v_mfma_f32_16x16x32_bf16 v[114:117], v[30:33], v[234:237], v[114:117]
	v_mfma_f32_16x16x32_bf16 v[102:105], v[22:25], v[242:245], v[102:105]
	v_mfma_f32_16x16x32_bf16 v[98:101], v[30:33], v[242:245], v[98:101]
	s_setprio 0
	s_setprio 1
	v_mfma_f32_16x16x32_bf16 v[142:145], v[46:49], v[178:181], 0
	v_mfma_f32_16x16x32_bf16 v[138:141], v[170:173], v[178:181], 0
	v_mfma_f32_16x16x32_bf16 v[126:129], v[46:49], v[186:189], 0
	v_mfma_f32_16x16x32_bf16 v[122:125], v[170:173], v[186:189], 0
	v_mfma_f32_16x16x32_bf16 v[110:113], v[46:49], v[230:233], 0
	v_mfma_f32_16x16x32_bf16 v[106:109], v[170:173], v[230:233], 0
	v_mfma_f32_16x16x32_bf16 v[94:97], v[46:49], v[238:241], 0
	v_mfma_f32_16x16x32_bf16 v[90:93], v[170:173], v[238:241], 0
	v_mfma_f32_16x16x32_bf16 v[142:145], v[54:57], v[182:185], v[142:145]
	v_mfma_f32_16x16x32_bf16 v[138:141], v[174:177], v[182:185], v[138:141]
	v_mfma_f32_16x16x32_bf16 v[126:129], v[54:57], v[226:229], v[126:129]
	v_mfma_f32_16x16x32_bf16 v[122:125], v[174:177], v[226:229], v[122:125]
	v_mfma_f32_16x16x32_bf16 v[110:113], v[54:57], v[234:237], v[110:113]
	v_mfma_f32_16x16x32_bf16 v[106:109], v[174:177], v[234:237], v[106:109]
	v_mfma_f32_16x16x32_bf16 v[94:97], v[54:57], v[242:245], v[94:97]
	v_mfma_f32_16x16x32_bf16 v[90:93], v[174:177], v[242:245], v[90:93]
	s_setprio 0
	s_barrier
	s_add_i32 s30, s30, s20
	v_lshl_add_u64 v[190:191], s[10:11], 0, v[156:157]
	s_mov_b32 m0, s30
	ds_read_b128 v[178:181], v225 offset:16384
	ds_read_b128 v[182:185], v225 offset:17408
	ds_read_b128 v[186:189], v225 offset:18432
	ds_read_b128 v[226:229], v225 offset:19456
	ds_read_b128 v[230:233], v225 offset:20480
	ds_read_b128 v[234:237], v225 offset:21504
	ds_read_b128 v[238:241], v225 offset:22528
	ds_read_b128 v[242:245], v225 offset:23552
	global_load_lds_dwordx4 v[190:191], off
	s_add_i32 m0, s30, 0x2000
	s_add_u32 s30, s10, 0x40000
	v_lshl_add_u64 v[198:199], s[10:11], 0, v[160:161]
	s_addc_u32 s31, s11, 0
	s_add_i32 s51, s51, s20
	global_load_lds_dwordx4 v[198:199], off
	v_lshl_add_u64 v[200:201], s[30:31], 0, v[156:157]
	s_mov_b32 m0, s51
	v_lshl_add_u64 v[250:251], s[14:15], 0, v[158:159]
	global_load_lds_dwordx4 v[200:201], off
	v_lshl_add_u64 v[200:201], s[30:31], 0, v[160:161]
	s_add_i32 m0, s51, 0x2000
	s_nop 0
	global_load_lds_dwordx4 v[200:201], off
	v_lshl_add_u64 v[200:201], s[14:15], 0, v[154:155]
	s_mov_b32 m0, s21
	s_nop 0
	global_load_lds_dwordx4 v[200:201], off
	s_mov_b32 m0, s45
	s_nop 0
	global_load_lds_dwordx4 v[250:251], off
	s_waitcnt vmcnt(8)
	s_waitcnt lgkmcnt(0)
	s_barrier
; #define PG8_STAGE(bufoff, gbase, voff) do { _Pragma("unroll") for (int _i = 0; _i < 2; ++_i) \
;         __builtin_amdgcn_global_load_lds((const unsigned*)((const char*)(gbase) + (voff)[_i]), (PG8_LAS unsigned*)(lds + (bufoff) + ldsw + _i * 8192), 16, 0, 0); } while (0)
; #define PG8_LDA(dst, b, h) do { _Pragma("unroll") for (int m = 0; m < 4; ++m) _Pragma("unroll") for (int k = 0; k < 2; ++k) dst[m][k] = *(const PG8_LAS bf16x8*)(lds + PG8_SA(b, h) + aoff + m * 2048 + k * 1024); } while (0)
; #define PG8_LDB(dst, b, h) do { _Pragma("unroll") for (int n = 0; n < 2; ++n) _Pragma("unroll") for (int k = 0; k < 2; ++k) dst[n][k] = *(const PG8_LAS bf16x8*)(lds + PG8_SB(b, h) + boff + n * 2048 + k * 1024); } while (0)
; #define PG8_MMA(ai, bj, At, Bt) do { __builtin_amdgcn_s_setprio(1); _Pragma("unroll") for (int m = 0; m < 4; ++m) _Pragma("unroll") for (int n = 0; n < 2; ++n) _Pragma("unroll") for (int k = 0; k < 2; ++k) \
;         acc[ai][bj][m][n] = __builtin_amdgcn_mfma_f32_16x16x32_bf16(Bt[n][k], At[m][k], acc[ai][bj][m][n], 0, 0, 0); __builtin_amdgcn_s_setprio(0); } while (0)
; #define PG8_WAIT_V(n) asm volatile("s_waitcnt vmcnt(" #n ")" ::: "memory")
; #define PG8_WAIT_L(n) asm volatile("s_waitcnt lgkmcnt(" #n ")" ::: "memory")
; #define PG8_BAR __builtin_amdgcn_s_barrier()
; #define PG8_SCHED __builtin_amdgcn_sched_barrier(0)
; template <class Epi, class Sched, bool ALIGN_EPI = false, bool SP2 = false>
; __device__ __forceinline__ void gemm_phase(PG8_LAS unsigned char* lds, const Gemm g, const Sched& S, const Epi& E) {
;     ...
;             PG8_WAIT_V(8); PG8_WAIT_L(0); PG8_BAR; PG8_MMA(1, 0, At, B0); PG8_MMA(1, 1, At, B1); PG8_BAR; PG8_SCHED;
;             PG8_LDB(B0, 1, 0); PG8_LDB(B1, 1, 1); PG8_SCHED; PG8_LDA(At, 1, 0); PG8_STAGE(PG8_SA(0, 1), a2 + hstep, voffA);
;             PG8_WAIT_V(8); PG8_WAIT_L(0); PG8_BAR; PG8_MMA(0, 0, At, B0); PG8_MMA(0, 1, At, B1); PG8_BAR; PG8_SCHED;
;             PG8_LDA(At, 1, 1); PG8_STAGE(PG8_SB(1, 0), b3, voffB); PG8_STAGE(PG8_SB(1, 1), b3 + hstep, voffB); PG8_STAGE(PG8_SA(1, 0), a3, voffA);
	s_setprio 1
	s_waitcnt lgkmcnt(0)
	v_mfma_f32_16x16x32_bf16 v[86:89], v[18:21], v[178:181], 0
	v_mfma_f32_16x16x32_bf16 v[82:85], v[26:29], v[178:181], 0
	v_mfma_f32_16x16x32_bf16 v[70:73], v[18:21], v[186:189], 0
	v_mfma_f32_16x16x32_bf16 v[66:69], v[26:29], v[186:189], 0
	v_mfma_f32_16x16x32_bf16 v[50:53], v[18:21], v[230:233], 0
	v_mfma_f32_16x16x32_bf16 v[42:45], v[26:29], v[230:233], 0
	v_mfma_f32_16x16x32_bf16 v[14:17], v[18:21], v[238:241], 0
	v_mfma_f32_16x16x32_bf16 v[10:13], v[26:29], v[238:241], 0
	v_mfma_f32_16x16x32_bf16 v[86:89], v[22:25], v[182:185], v[86:89]
	v_mfma_f32_16x16x32_bf16 v[82:85], v[30:33], v[182:185], v[82:85]
	v_mfma_f32_16x16x32_bf16 v[70:73], v[22:25], v[226:229], v[70:73]
	v_mfma_f32_16x16x32_bf16 v[66:69], v[30:33], v[226:229], v[66:69]
	v_mfma_f32_16x16x32_bf16 v[50:53], v[22:25], v[234:237], v[50:53]
	v_mfma_f32_16x16x32_bf16 v[42:45], v[30:33], v[234:237], v[42:45]
	v_mfma_f32_16x16x32_bf16 v[14:17], v[22:25], v[242:245], v[14:17]
	v_mfma_f32_16x16x32_bf16 v[10:13], v[30:33], v[242:245], v[10:13]
	s_setprio 0
	s_setprio 1
	v_mfma_f32_16x16x32_bf16 v[38:41], v[46:49], v[230:233], 0
	v_mfma_f32_16x16x32_bf16 v[34:37], v[170:173], v[230:233], 0
	v_mfma_f32_16x16x32_bf16 v[6:9], v[46:49], v[238:241], 0
	v_mfma_f32_16x16x32_bf16 v[2:5], v[170:173], v[238:241], 0
	v_mfma_f32_16x16x32_bf16 v[18:21], v[46:49], v[178:181], 0
	v_mfma_f32_16x16x32_bf16 v[22:25], v[170:173], v[178:181], 0
	v_mfma_f32_16x16x32_bf16 v[26:29], v[46:49], v[186:189], 0
	v_mfma_f32_16x16x32_bf16 v[30:33], v[170:173], v[186:189], 0
	v_mfma_f32_16x16x32_bf16 v[38:41], v[54:57], v[234:237], v[38:41]
	v_mfma_f32_16x16x32_bf16 v[34:37], v[174:177], v[234:237], v[34:37]
	v_mfma_f32_16x16x32_bf16 v[6:9], v[54:57], v[242:245], v[6:9]
	v_mfma_f32_16x16x32_bf16 v[2:5], v[174:177], v[242:245], v[2:5]
	v_mfma_f32_16x16x32_bf16 v[18:21], v[54:57], v[182:185], v[18:21]
	v_mfma_f32_16x16x32_bf16 v[22:25], v[174:177], v[182:185], v[22:25]
	v_mfma_f32_16x16x32_bf16 v[26:29], v[54:57], v[226:229], v[26:29]
	v_mfma_f32_16x16x32_bf16 v[30:33], v[174:177], v[226:229], v[30:33]
	s_setprio 0
	s_barrier
	s_add_i32 s30, 0, 0x18000
	v_add_u32_e32 v0, s30, v204
	s_add_i32 s31, 0, 0x1c000
	ds_read_b128 v[46:49], v0
	ds_read_b128 v[54:57], v0 offset:1024
	ds_read_b128 v[58:61], v0 offset:2048
	ds_read_b128 v[62:65], v0 offset:3072
	v_add_u32_e32 v0, s31, v204
	ds_read_b128 v[170:173], v0
	ds_read_b128 v[174:177], v0 offset:1024
	ds_read_b128 v[178:181], v0 offset:2048
	ds_read_b128 v[182:185], v0 offset:3072
	s_add_u32 s14, s14, 0x40000
	s_addc_u32 s15, s15, 0
	s_mov_b32 m0, s62
	v_lshl_add_u64 v[246:247], s[14:15], 0, v[154:155]
	ds_read_b128 v[74:77], v225 offset:32768
	ds_read_b128 v[78:81], v225 offset:33792
	ds_read_b128 v[186:189], v225 offset:34816
	ds_read_b128 v[226:229], v225 offset:35840
	ds_read_b128 v[230:233], v225 offset:36864
	ds_read_b128 v[234:237], v225 offset:37888
	ds_read_b128 v[238:241], v225 offset:38912
	ds_read_b128 v[242:245], v225 offset:39936
	global_load_lds_dwordx4 v[246:247], off
	v_lshl_add_u64 v[246:247], s[14:15], 0, v[158:159]
	s_mov_b32 m0, s63
	s_nop 0
	global_load_lds_dwordx4 v[246:247], off
	s_waitcnt vmcnt(8)
	s_waitcnt lgkmcnt(0)
	s_barrier
	s_setprio 1
	s_waitcnt lgkmcnt(0)
	v_mfma_f32_16x16x32_bf16 v[150:153], v[46:49], v[74:77], v[150:153]
	v_mfma_f32_16x16x32_bf16 v[146:149], v[58:61], v[74:77], v[146:149]
	v_mfma_f32_16x16x32_bf16 v[134:137], v[46:49], v[186:189], v[134:137]
	v_mfma_f32_16x16x32_bf16 v[130:133], v[58:61], v[186:189], v[130:133]
	v_mfma_f32_16x16x32_bf16 v[118:121], v[46:49], v[230:233], v[118:121]
	v_mfma_f32_16x16x32_bf16 v[114:117], v[58:61], v[230:233], v[114:117]
	v_mfma_f32_16x16x32_bf16 v[102:105], v[46:49], v[238:241], v[102:105]
	v_mfma_f32_16x16x32_bf16 v[98:101], v[58:61], v[238:241], v[98:101]
	v_mfma_f32_16x16x32_bf16 v[150:153], v[54:57], v[78:81], v[150:153]
	v_mfma_f32_16x16x32_bf16 v[146:149], v[62:65], v[78:81], v[146:149]
	v_mfma_f32_16x16x32_bf16 v[134:137], v[54:57], v[226:229], v[134:137]
	v_mfma_f32_16x16x32_bf16 v[130:133], v[62:65], v[226:229], v[130:133]
	v_mfma_f32_16x16x32_bf16 v[118:121], v[54:57], v[234:237], v[118:121]
	v_mfma_f32_16x16x32_bf16 v[114:117], v[62:65], v[234:237], v[114:117]
	v_mfma_f32_16x16x32_bf16 v[102:105], v[54:57], v[242:245], v[102:105]
	v_mfma_f32_16x16x32_bf16 v[98:101], v[62:65], v[242:245], v[98:101]
	s_setprio 0
	s_setprio 1
	v_mfma_f32_16x16x32_bf16 v[142:145], v[170:173], v[74:77], v[142:145]
	v_mfma_f32_16x16x32_bf16 v[74:77], v[178:181], v[74:77], v[138:141]
	v_mfma_f32_16x16x32_bf16 v[138:141], v[182:185], v[78:81], v[74:77]
	v_mfma_f32_16x16x32_bf16 v[74:77], v[170:173], v[186:189], v[126:129]
	v_mfma_f32_16x16x32_bf16 v[126:129], v[174:177], v[226:229], v[74:77]
	v_mfma_f32_16x16x32_bf16 v[74:77], v[178:181], v[186:189], v[122:125]
	v_mfma_f32_16x16x32_bf16 v[122:125], v[182:185], v[226:229], v[74:77]
	v_mfma_f32_16x16x32_bf16 v[74:77], v[170:173], v[230:233], v[110:113]
	v_mfma_f32_16x16x32_bf16 v[110:113], v[174:177], v[234:237], v[74:77]
	v_mfma_f32_16x16x32_bf16 v[74:77], v[178:181], v[230:233], v[106:109]
	v_mfma_f32_16x16x32_bf16 v[106:109], v[182:185], v[234:237], v[74:77]
	v_mfma_f32_16x16x32_bf16 v[74:77], v[170:173], v[238:241], v[94:97]
	v_mfma_f32_16x16x32_bf16 v[94:97], v[174:177], v[242:245], v[74:77]
	v_mfma_f32_16x16x32_bf16 v[74:77], v[178:181], v[238:241], v[90:93]
	v_mfma_f32_16x16x32_bf16 v[142:145], v[174:177], v[78:81], v[142:145]
	v_mfma_f32_16x16x32_bf16 v[90:93], v[182:185], v[242:245], v[74:77]
	s_setprio 0
	s_barrier
; #define PG8_STAGE(bufoff, gbase, voff) do { _Pragma("unroll") for (int _i = 0; _i < 2; ++_i) \
;         __builtin_amdgcn_global_load_lds((const unsigned*)((const char*)(gbase) + (voff)[_i]), (PG8_LAS unsigned*)(lds + (bufoff) + ldsw + _i * 8192), 16, 0, 0); } while (0)
; #define PG8_LDA(dst, b, h) do { _Pragma("unroll") for (int m = 0; m < 4; ++m) _Pragma("unroll") for (int k = 0; k < 2; ++k) dst[m][k] = *(const PG8_LAS bf16x8*)(lds + PG8_SA(b, h) + aoff + m * 2048 + k * 1024); } while (0)
; #define PG8_MMA(ai, bj, At, Bt) do { __builtin_amdgcn_s_setprio(1); _Pragma("unroll") for (int m = 0; m < 4; ++m) _Pragma("unroll") for (int n = 0; n < 2; ++n) _Pragma("unroll") for (int k = 0; k < 2; ++k) \
;         acc[ai][bj][m][n] = __builtin_amdgcn_mfma_f32_16x16x32_bf16(Bt[n][k], At[m][k], acc[ai][bj][m][n], 0, 0, 0); __builtin_amdgcn_s_setprio(0); } while (0)
; #define PG8_WAIT_V(n) asm volatile("s_waitcnt vmcnt(" #n ")" ::: "memory")
; #define PG8_WAIT_L(n) asm volatile("s_waitcnt lgkmcnt(" #n ")" ::: "memory")
; #define PG8_BAR __builtin_amdgcn_s_barrier()
; #define PG8_SCHED __builtin_amdgcn_sched_barrier(0)
; template <class Epi, class Sched, bool ALIGN_EPI = false, bool SP2 = false>
; __device__ __forceinline__ void gemm_phase(PG8_LAS unsigned char* lds, const Gemm g, const Sched& S, const Epi& E) {
;     ...
;         for (int t = 0; t < nt; t += 2) {
;             const bool last = (t == nt - 2);
;             const char* a1 = cA + (size_t)(t + 1) * kstep;
;             const char* a2 = last ? nA : cA + (size_t)(t + 2) * kstep; const char* b2 = last ? nB : cB + (size_t)(t + 2) * kstep;
;             const char* a3 = a2 + kstep; const char* b3 = b2 + kstep;
;             if (last && has_next) S.a_ready(nxt);
;     ...
;             PG8_LDA(At, 1, 1); PG8_STAGE(PG8_SB(1, 0), b3, voffB); PG8_STAGE(PG8_SB(1, 1), b3 + hstep, voffB); PG8_STAGE(PG8_SA(1, 0), a3, voffA);
;             PG8_WAIT_V(8); PG8_WAIT_L(0); PG8_BAR; PG8_MMA(1, 0, At, B0); PG8_MMA(1, 1, At, B1); PG8_BAR; PG8_SCHED;
	s_add_i32 s14, s30, s20
	v_lshl_add_u64 v[78:79], v[190:191], 0, s[0:1]
	s_mov_b32 m0, s14
	s_nop 0
	ds_read_b128 v[74:77], v225 offset:49152
	ds_read_b128 v[186:189], v225 offset:50176
	ds_read_b128 v[226:229], v225 offset:51200
	ds_read_b128 v[230:233], v225 offset:52224
	ds_read_b128 v[234:237], v225 offset:53248
	ds_read_b128 v[238:241], v225 offset:54272
	ds_read_b128 v[242:245], v225 offset:55296
	ds_read_b128 v[246:249], v225 offset:56320
	global_load_lds_dwordx4 v[78:79], off
	s_add_i32 m0, s14, 0x2000
	s_add_u32 s10, s10, 0x40080
	v_lshl_add_u64 v[78:79], v[198:199], 0, s[0:1]
	s_addc_u32 s11, s11, 0
	s_add_i32 s14, s31, s20
	global_load_lds_dwordx4 v[78:79], off
	v_lshl_add_u64 v[78:79], s[10:11], 0, v[156:157]
	s_mov_b32 m0, s14
	s_nop 0
	global_load_lds_dwordx4 v[78:79], off
	v_lshl_add_u64 v[78:79], s[10:11], 0, v[160:161]
	s_add_i32 m0, s14, 0x2000
	s_nop 0
	global_load_lds_dwordx4 v[78:79], off
	v_lshl_add_u64 v[78:79], v[200:201], 0, s[0:1]
	s_mov_b32 m0, s64
	s_nop 0
	global_load_lds_dwordx4 v[78:79], off
	v_lshl_add_u64 v[78:79], v[250:251], 0, s[0:1]
	s_mov_b32 m0, s65
	s_nop 0
	global_load_lds_dwordx4 v[78:79], off
	s_waitcnt vmcnt(8)
	s_waitcnt lgkmcnt(0)
	s_barrier
	s_setprio 1
	s_waitcnt lgkmcnt(0)
	v_mfma_f32_16x16x32_bf16 v[78:81], v[46:49], v[74:77], v[86:89]
	v_mfma_f32_16x16x32_bf16 v[86:89], v[54:57], v[186:189], v[78:81]
	v_mfma_f32_16x16x32_bf16 v[78:81], v[58:61], v[74:77], v[82:85]
	v_mfma_f32_16x16x32_bf16 v[70:73], v[46:49], v[226:229], v[70:73]
	v_mfma_f32_16x16x32_bf16 v[66:69], v[58:61], v[226:229], v[66:69]
	v_mfma_f32_16x16x32_bf16 v[50:53], v[46:49], v[234:237], v[50:53]
	v_mfma_f32_16x16x32_bf16 v[42:45], v[58:61], v[234:237], v[42:45]
	v_mfma_f32_16x16x32_bf16 v[14:17], v[46:49], v[242:245], v[14:17]
	v_mfma_f32_16x16x32_bf16 v[10:13], v[58:61], v[242:245], v[10:13]
	v_mfma_f32_16x16x32_bf16 v[82:85], v[62:65], v[186:189], v[78:81]
	v_mfma_f32_16x16x32_bf16 v[70:73], v[54:57], v[230:233], v[70:73]
	v_mfma_f32_16x16x32_bf16 v[66:69], v[62:65], v[230:233], v[66:69]
	v_mfma_f32_16x16x32_bf16 v[50:53], v[54:57], v[238:241], v[50:53]
	v_mfma_f32_16x16x32_bf16 v[42:45], v[62:65], v[238:241], v[42:45]
	v_mfma_f32_16x16x32_bf16 v[14:17], v[54:57], v[246:249], v[14:17]
	v_mfma_f32_16x16x32_bf16 v[10:13], v[62:65], v[246:249], v[10:13]
	s_setprio 0
	s_setprio 1
	v_mfma_f32_16x16x32_bf16 v[18:21], v[170:173], v[74:77], v[18:21]
	v_mfma_f32_16x16x32_bf16 v[78:81], v[174:177], v[186:189], v[18:21]
	v_mfma_f32_16x16x32_bf16 v[18:21], v[178:181], v[74:77], v[22:25]
	v_mfma_f32_16x16x32_bf16 v[74:77], v[182:185], v[186:189], v[18:21]
	v_mfma_f32_16x16x32_bf16 v[18:21], v[170:173], v[226:229], v[26:29]
	v_mfma_f32_16x16x32_bf16 v[62:65], v[174:177], v[230:233], v[18:21]
	v_mfma_f32_16x16x32_bf16 v[18:21], v[178:181], v[226:229], v[30:33]
	v_mfma_f32_16x16x32_bf16 v[58:61], v[182:185], v[230:233], v[18:21]
	v_mfma_f32_16x16x32_bf16 v[18:21], v[170:173], v[234:237], v[38:41]
	v_mfma_f32_16x16x32_bf16 v[38:41], v[174:177], v[238:241], v[18:21]
	v_mfma_f32_16x16x32_bf16 v[18:21], v[178:181], v[234:237], v[34:37]
	v_mfma_f32_16x16x32_bf16 v[6:9], v[170:173], v[242:245], v[6:9]
	v_mfma_f32_16x16x32_bf16 v[2:5], v[178:181], v[242:245], v[2:5]
	v_mfma_f32_16x16x32_bf16 v[34:37], v[182:185], v[238:241], v[18:21]
	v_mfma_f32_16x16x32_bf16 v[6:9], v[174:177], v[246:249], v[6:9]
	v_mfma_f32_16x16x32_bf16 v[2:5], v[182:185], v[246:249], v[2:5]
	s_setprio 0
	s_add_i32 s43, s43, 2
	s_add_u32 s8, s8, 0x100
	s_addc_u32 s9, s9, 0
	s_add_u32 s41, s41, 0x100
	s_addc_u32 s42, s42, 0
	s_cmp_gt_u32 s43, 13
	s_cbranch_scc1 .Lrot_exit_peel_p1
	s_add_u32 s10, s8, 0xfffc0080
	s_addc_u32 s11, s9, -1
	s_add_i32 s30, 0, 0x10000
	s_cmp_eq_u32 s43, 12
	s_cselect_b32 s15, s33, s11
	s_cselect_b32 s14, s34, s10
	v_add_u32_e32 v0, s30, v204
	s_cselect_b32 s11, s35, s42
	s_cselect_b32 s10, s40, s41
	s_add_i32 s51, 0, 0x14000
	s_barrier
	s_branch .LBB0_188
.Lrot_exit_peel_p1:
	s_barrier
	s_branch .Lpeel_exit_p1
.LBB0_188:
	ds_read_b128 v[18:21], v0
	ds_read_b128 v[22:25], v0 offset:1024
	ds_read_b128 v[26:29], v0 offset:2048
	ds_read_b128 v[30:33], v0 offset:3072
	v_add_u32_e32 v0, s51, v204
	ds_read_b128 v[46:49], v0
	ds_read_b128 v[54:57], v0 offset:1024
	ds_read_b128 v[170:173], v0 offset:2048
	ds_read_b128 v[174:177], v0 offset:3072
	v_lshl_add_u64 v[190:191], s[8:9], 0, v[166:167]
	s_add_i32 m0, s21, 0xc000
	ds_read_b128 v[178:181], v225
	ds_read_b128 v[182:185], v225 offset:1024
	ds_read_b128 v[186:189], v225 offset:2048
	ds_read_b128 v[226:229], v225 offset:3072
	ds_read_b128 v[230:233], v225 offset:4096
	ds_read_b128 v[234:237], v225 offset:5120
	ds_read_b128 v[238:241], v225 offset:6144
	ds_read_b128 v[242:245], v225 offset:7168
	global_load_lds_dwordx4 v[190:191], off
	v_lshl_add_u64 v[190:191], s[8:9], 0, v[168:169]
	s_add_i32 m0, s21, 0xe000
	s_nop 0
	global_load_lds_dwordx4 v[190:191], off
	s_waitcnt vmcnt(8)
	s_waitcnt lgkmcnt(0)
	s_barrier
; #define PG8_STAGE(bufoff, gbase, voff) do { _Pragma("unroll") for (int _i = 0; _i < 2; ++_i) \
;         __builtin_amdgcn_global_load_lds((const unsigned*)((const char*)(gbase) + (voff)[_i]), (PG8_LAS unsigned*)(lds + (bufoff) + ldsw + _i * 8192), 16, 0, 0); } while (0)
; #define PG8_LDA(dst, b, h) do { _Pragma("unroll") for (int m = 0; m < 4; ++m) _Pragma("unroll") for (int k = 0; k < 2; ++k) dst[m][k] = *(const PG8_LAS bf16x8*)(lds + PG8_SA(b, h) + aoff + m * 2048 + k * 1024); } while (0)
; #define PG8_LDB(dst, b, h) do { _Pragma("unroll") for (int n = 0; n < 2; ++n) _Pragma("unroll") for (int k = 0; k < 2; ++k) dst[n][k] = *(const PG8_LAS bf16x8*)(lds + PG8_SB(b, h) + boff + n * 2048 + k * 1024); } while (0)
; #define PG8_MMA(ai, bj, At, Bt) do { __builtin_amdgcn_s_setprio(1); _Pragma("unroll") for (int m = 0; m < 4; ++m) _Pragma("unroll") for (int n = 0; n < 2; ++n) _Pragma("unroll") for (int k = 0; k < 2; ++k) \
;         acc[ai][bj][m][n] = __builtin_amdgcn_mfma_f32_16x16x32_bf16(Bt[n][k], At[m][k], acc[ai][bj][m][n], 0, 0, 0); __builtin_amdgcn_s_setprio(0); } while (0)
; #define PG8_WAIT_V(n) asm volatile("s_waitcnt vmcnt(" #n ")" ::: "memory")
; #define PG8_WAIT_L(n) asm volatile("s_waitcnt lgkmcnt(" #n ")" ::: "memory")
; #define PG8_BAR __builtin_amdgcn_s_barrier()
; #define PG8_SCHED __builtin_amdgcn_sched_barrier(0)
; template <class Epi, class Sched, bool ALIGN_EPI = false, bool SP2 = false>
; __device__ __forceinline__ void gemm_phase(PG8_LAS unsigned char* lds, const Gemm g, const Sched& S, const Epi& E) {
;     ...
;             PG8_LDB(B0, 0, 0); PG8_LDB(B1, 0, 1); PG8_SCHED; PG8_LDA(At, 0, 0); PG8_STAGE(PG8_SA(1, 1), a1 + hstep, voffA);
;             PG8_WAIT_V(8); PG8_WAIT_L(0); PG8_BAR; PG8_MMA(0, 0, At, B0); PG8_MMA(0, 1, At, B1); PG8_BAR; PG8_SCHED;
;             PG8_LDA(At, 0, 1); PG8_STAGE(PG8_SB(0, 0), b2, voffB); PG8_STAGE(PG8_SB(0, 1), b2 + hstep, voffB); PG8_STAGE(PG8_SA(0, 0), a2, voffA);
;             PG8_WAIT_V(8); PG8_WAIT_L(0); PG8_BAR; PG8_MMA(1, 0, At, B0); PG8_MMA(1, 1, At, B1); PG8_BAR; PG8_SCHED;
;             PG8_LDB(B0, 1, 0); PG8_LDB(B1, 1, 1); PG8_SCHED; PG8_LDA(At, 1, 0); PG8_STAGE(PG8_SA(0, 1), a2 + hstep, voffA);
;             PG8_WAIT_V(8); PG8_WAIT_L(0); PG8_BAR; PG8_MMA(0, 0, At, B0); PG8_MMA(0, 1, At, B1); PG8_BAR; PG8_SCHED;
	s_setprio 1
	s_waitcnt lgkmcnt(0)
	v_mfma_f32_16x16x32_bf16 v[150:153], v[18:21], v[178:181], v[150:153]
	v_mfma_f32_16x16x32_bf16 v[146:149], v[26:29], v[178:181], v[146:149]
	v_mfma_f32_16x16x32_bf16 v[134:137], v[18:21], v[186:189], v[134:137]
	v_mfma_f32_16x16x32_bf16 v[130:133], v[26:29], v[186:189], v[130:133]
	v_mfma_f32_16x16x32_bf16 v[118:121], v[18:21], v[230:233], v[118:121]
	v_mfma_f32_16x16x32_bf16 v[114:117], v[26:29], v[230:233], v[114:117]
	v_mfma_f32_16x16x32_bf16 v[102:105], v[18:21], v[238:241], v[102:105]
	v_mfma_f32_16x16x32_bf16 v[98:101], v[26:29], v[238:241], v[98:101]
	v_mfma_f32_16x16x32_bf16 v[150:153], v[22:25], v[182:185], v[150:153]
	v_mfma_f32_16x16x32_bf16 v[146:149], v[30:33], v[182:185], v[146:149]
	v_mfma_f32_16x16x32_bf16 v[134:137], v[22:25], v[226:229], v[134:137]
	v_mfma_f32_16x16x32_bf16 v[130:133], v[30:33], v[226:229], v[130:133]
	v_mfma_f32_16x16x32_bf16 v[118:121], v[22:25], v[234:237], v[118:121]
	v_mfma_f32_16x16x32_bf16 v[114:117], v[30:33], v[234:237], v[114:117]
	v_mfma_f32_16x16x32_bf16 v[102:105], v[22:25], v[242:245], v[102:105]
	v_mfma_f32_16x16x32_bf16 v[98:101], v[30:33], v[242:245], v[98:101]
	s_setprio 0
	s_setprio 1
	v_mfma_f32_16x16x32_bf16 v[142:145], v[46:49], v[178:181], v[142:145]
	v_mfma_f32_16x16x32_bf16 v[138:141], v[170:173], v[178:181], v[138:141]
	v_mfma_f32_16x16x32_bf16 v[126:129], v[46:49], v[186:189], v[126:129]
	v_mfma_f32_16x16x32_bf16 v[122:125], v[170:173], v[186:189], v[122:125]
	v_mfma_f32_16x16x32_bf16 v[110:113], v[46:49], v[230:233], v[110:113]
	v_mfma_f32_16x16x32_bf16 v[106:109], v[170:173], v[230:233], v[106:109]
	v_mfma_f32_16x16x32_bf16 v[94:97], v[46:49], v[238:241], v[94:97]
	v_mfma_f32_16x16x32_bf16 v[90:93], v[170:173], v[238:241], v[90:93]
	v_mfma_f32_16x16x32_bf16 v[142:145], v[54:57], v[182:185], v[142:145]
	v_mfma_f32_16x16x32_bf16 v[138:141], v[174:177], v[182:185], v[138:141]
	v_mfma_f32_16x16x32_bf16 v[126:129], v[54:57], v[226:229], v[126:129]
	v_mfma_f32_16x16x32_bf16 v[122:125], v[174:177], v[226:229], v[122:125]
	v_mfma_f32_16x16x32_bf16 v[110:113], v[54:57], v[234:237], v[110:113]
	v_mfma_f32_16x16x32_bf16 v[106:109], v[174:177], v[234:237], v[106:109]
	v_mfma_f32_16x16x32_bf16 v[94:97], v[54:57], v[242:245], v[94:97]
	v_mfma_f32_16x16x32_bf16 v[90:93], v[174:177], v[242:245], v[90:93]
	s_setprio 0
	s_barrier
	s_add_i32 s30, s30, s20
	v_lshl_add_u64 v[190:191], s[10:11], 0, v[156:157]
	s_mov_b32 m0, s30
	ds_read_b128 v[178:181], v225 offset:16384
	ds_read_b128 v[182:185], v225 offset:17408
	ds_read_b128 v[186:189], v225 offset:18432
	ds_read_b128 v[226:229], v225 offset:19456
	ds_read_b128 v[230:233], v225 offset:20480
	ds_read_b128 v[234:237], v225 offset:21504
	ds_read_b128 v[238:241], v225 offset:22528
	ds_read_b128 v[242:245], v225 offset:23552
	global_load_lds_dwordx4 v[190:191], off
	s_add_i32 m0, s30, 0x2000
	s_add_u32 s30, s10, 0x40000
	v_lshl_add_u64 v[198:199], s[10:11], 0, v[160:161]
	s_addc_u32 s31, s11, 0
	s_add_i32 s51, s51, s20
	global_load_lds_dwordx4 v[198:199], off
	v_lshl_add_u64 v[200:201], s[30:31], 0, v[156:157]
	s_mov_b32 m0, s51
	v_lshl_add_u64 v[250:251], s[14:15], 0, v[158:159]
	global_load_lds_dwordx4 v[200:201], off
	v_lshl_add_u64 v[200:201], s[30:31], 0, v[160:161]
	s_add_i32 m0, s51, 0x2000
	s_nop 0
	global_load_lds_dwordx4 v[200:201], off
	v_lshl_add_u64 v[200:201], s[14:15], 0, v[154:155]
	s_mov_b32 m0, s21
	s_nop 0
	global_load_lds_dwordx4 v[200:201], off
	s_mov_b32 m0, s45
	s_nop 0
	global_load_lds_dwordx4 v[250:251], off
	s_waitcnt vmcnt(8)
	s_waitcnt lgkmcnt(0)
	s_barrier
	s_setprio 1
	s_waitcnt lgkmcnt(0)
	v_mfma_f32_16x16x32_bf16 v[86:89], v[18:21], v[178:181], v[86:89]
	v_mfma_f32_16x16x32_bf16 v[82:85], v[26:29], v[178:181], v[82:85]
	v_mfma_f32_16x16x32_bf16 v[70:73], v[18:21], v[186:189], v[70:73]
	v_mfma_f32_16x16x32_bf16 v[66:69], v[26:29], v[186:189], v[66:69]
	v_mfma_f32_16x16x32_bf16 v[50:53], v[18:21], v[230:233], v[50:53]
	v_mfma_f32_16x16x32_bf16 v[42:45], v[26:29], v[230:233], v[42:45]
	v_mfma_f32_16x16x32_bf16 v[14:17], v[18:21], v[238:241], v[14:17]
	v_mfma_f32_16x16x32_bf16 v[10:13], v[26:29], v[238:241], v[10:13]
	v_mfma_f32_16x16x32_bf16 v[86:89], v[22:25], v[182:185], v[86:89]
	v_mfma_f32_16x16x32_bf16 v[82:85], v[30:33], v[182:185], v[82:85]
	v_mfma_f32_16x16x32_bf16 v[70:73], v[22:25], v[226:229], v[70:73]
	v_mfma_f32_16x16x32_bf16 v[66:69], v[30:33], v[226:229], v[66:69]
	v_mfma_f32_16x16x32_bf16 v[50:53], v[22:25], v[234:237], v[50:53]
	v_mfma_f32_16x16x32_bf16 v[42:45], v[30:33], v[234:237], v[42:45]
	v_mfma_f32_16x16x32_bf16 v[14:17], v[22:25], v[242:245], v[14:17]
	v_mfma_f32_16x16x32_bf16 v[10:13], v[30:33], v[242:245], v[10:13]
	s_setprio 0
	s_setprio 1
	v_mfma_f32_16x16x32_bf16 v[38:41], v[46:49], v[230:233], v[38:41]
	v_mfma_f32_16x16x32_bf16 v[34:37], v[170:173], v[230:233], v[34:37]
	v_mfma_f32_16x16x32_bf16 v[6:9], v[46:49], v[238:241], v[6:9]
	v_mfma_f32_16x16x32_bf16 v[2:5], v[170:173], v[238:241], v[2:5]
	v_mfma_f32_16x16x32_bf16 v[18:21], v[46:49], v[178:181], v[78:81]
	v_mfma_f32_16x16x32_bf16 v[22:25], v[170:173], v[178:181], v[74:77]
	v_mfma_f32_16x16x32_bf16 v[26:29], v[46:49], v[186:189], v[62:65]
	v_mfma_f32_16x16x32_bf16 v[30:33], v[170:173], v[186:189], v[58:61]
	v_mfma_f32_16x16x32_bf16 v[38:41], v[54:57], v[234:237], v[38:41]
	v_mfma_f32_16x16x32_bf16 v[34:37], v[174:177], v[234:237], v[34:37]
	v_mfma_f32_16x16x32_bf16 v[6:9], v[54:57], v[242:245], v[6:9]
	v_mfma_f32_16x16x32_bf16 v[2:5], v[174:177], v[242:245], v[2:5]
	v_mfma_f32_16x16x32_bf16 v[18:21], v[54:57], v[182:185], v[18:21]
	v_mfma_f32_16x16x32_bf16 v[22:25], v[174:177], v[182:185], v[22:25]
	v_mfma_f32_16x16x32_bf16 v[26:29], v[54:57], v[226:229], v[26:29]
	v_mfma_f32_16x16x32_bf16 v[30:33], v[174:177], v[226:229], v[30:33]
	s_setprio 0
	s_barrier
; #define PG8_STAGE(bufoff, gbase, voff) do { _Pragma("unroll") for (int _i = 0; _i < 2; ++_i) \
;         __builtin_amdgcn_global_load_lds((const unsigned*)((const char*)(gbase) + (voff)[_i]), (PG8_LAS unsigned*)(lds + (bufoff) + ldsw + _i * 8192), 16, 0, 0); } while (0)
; #define PG8_LDA(dst, b, h) do { _Pragma("unroll") for (int m = 0; m < 4; ++m) _Pragma("unroll") for (int k = 0; k < 2; ++k) dst[m][k] = *(const PG8_LAS bf16x8*)(lds + PG8_SA(b, h) + aoff + m * 2048 + k * 1024); } while (0)
; #define PG8_LDB(dst, b, h) do { _Pragma("unroll") for (int n = 0; n < 2; ++n) _Pragma("unroll") for (int k = 0; k < 2; ++k) dst[n][k] = *(const PG8_LAS bf16x8*)(lds + PG8_SB(b, h) + boff + n * 2048 + k * 1024); } while (0)
; #define PG8_MMA(ai, bj, At, Bt) do { __builtin_amdgcn_s_setprio(1); _Pragma("unroll") for (int m = 0; m < 4; ++m) _Pragma("unroll") for (int n = 0; n < 2; ++n) _Pragma("unroll") for (int k = 0; k < 2; ++k) \
;         acc[ai][bj][m][n] = __builtin_amdgcn_mfma_f32_16x16x32_bf16(Bt[n][k], At[m][k], acc[ai][bj][m][n], 0, 0, 0); __builtin_amdgcn_s_setprio(0); } while (0)
; #define PG8_WAIT_V(n) asm volatile("s_waitcnt vmcnt(" #n ")" ::: "memory")
; #define PG8_WAIT_L(n) asm volatile("s_waitcnt lgkmcnt(" #n ")" ::: "memory")
; #define PG8_BAR __builtin_amdgcn_s_barrier()
; #define PG8_SCHED __builtin_amdgcn_sched_barrier(0)
; template <class Epi, class Sched, bool ALIGN_EPI = false, bool SP2 = false>
; __device__ __forceinline__ void gemm_phase(PG8_LAS unsigned char* lds, const Gemm g, const Sched& S, const Epi& E) {
;     ...
;             PG8_LDB(B0, 1, 0); PG8_LDB(B1, 1, 1); PG8_SCHED; PG8_LDA(At, 1, 0); PG8_STAGE(PG8_SA(0, 1), a2 + hstep, voffA);
;             PG8_WAIT_V(8); PG8_WAIT_L(0); PG8_BAR; PG8_MMA(0, 0, At, B0); PG8_MMA(0, 1, At, B1); PG8_BAR; PG8_SCHED;
	s_add_i32 s30, 0, 0x18000
	v_add_u32_e32 v0, s30, v204
	s_add_i32 s31, 0, 0x1c000
	ds_read_b128 v[46:49], v0
	ds_read_b128 v[54:57], v0 offset:1024
	ds_read_b128 v[58:61], v0 offset:2048
	ds_read_b128 v[62:65], v0 offset:3072
	v_add_u32_e32 v0, s31, v204
	ds_read_b128 v[170:173], v0
	ds_read_b128 v[174:177], v0 offset:1024
	ds_read_b128 v[178:181], v0 offset:2048
	ds_read_b128 v[182:185], v0 offset:3072
	s_add_u32 s14, s14, 0x40000
	s_addc_u32 s15, s15, 0
	s_mov_b32 m0, s62
	v_lshl_add_u64 v[246:247], s[14:15], 0, v[154:155]
	ds_read_b128 v[74:77], v225 offset:32768
	ds_read_b128 v[78:81], v225 offset:33792
	ds_read_b128 v[186:189], v225 offset:34816
	ds_read_b128 v[226:229], v225 offset:35840
	ds_read_b128 v[230:233], v225 offset:36864
	ds_read_b128 v[234:237], v225 offset:37888
	ds_read_b128 v[238:241], v225 offset:38912
	ds_read_b128 v[242:245], v225 offset:39936
	global_load_lds_dwordx4 v[246:247], off
	v_lshl_add_u64 v[246:247], s[14:15], 0, v[158:159]
	s_mov_b32 m0, s63
	s_nop 0
	global_load_lds_dwordx4 v[246:247], off
	s_waitcnt vmcnt(8)
	s_waitcnt lgkmcnt(0)
	s_barrier
	s_setprio 1
	s_waitcnt lgkmcnt(0)
	v_mfma_f32_16x16x32_bf16 v[150:153], v[46:49], v[74:77], v[150:153]
	v_mfma_f32_16x16x32_bf16 v[146:149], v[58:61], v[74:77], v[146:149]
	v_mfma_f32_16x16x32_bf16 v[134:137], v[46:49], v[186:189], v[134:137]
	v_mfma_f32_16x16x32_bf16 v[130:133], v[58:61], v[186:189], v[130:133]
	v_mfma_f32_16x16x32_bf16 v[118:121], v[46:49], v[230:233], v[118:121]
	v_mfma_f32_16x16x32_bf16 v[114:117], v[58:61], v[230:233], v[114:117]
	v_mfma_f32_16x16x32_bf16 v[102:105], v[46:49], v[238:241], v[102:105]
	v_mfma_f32_16x16x32_bf16 v[98:101], v[58:61], v[238:241], v[98:101]
	v_mfma_f32_16x16x32_bf16 v[150:153], v[54:57], v[78:81], v[150:153]
	v_mfma_f32_16x16x32_bf16 v[146:149], v[62:65], v[78:81], v[146:149]
	v_mfma_f32_16x16x32_bf16 v[134:137], v[54:57], v[226:229], v[134:137]
	v_mfma_f32_16x16x32_bf16 v[130:133], v[62:65], v[226:229], v[130:133]
	v_mfma_f32_16x16x32_bf16 v[118:121], v[54:57], v[234:237], v[118:121]
	v_mfma_f32_16x16x32_bf16 v[114:117], v[62:65], v[234:237], v[114:117]
	v_mfma_f32_16x16x32_bf16 v[102:105], v[54:57], v[242:245], v[102:105]
	v_mfma_f32_16x16x32_bf16 v[98:101], v[62:65], v[242:245], v[98:101]
	s_setprio 0
	s_setprio 1
	v_mfma_f32_16x16x32_bf16 v[142:145], v[170:173], v[74:77], v[142:145]
	v_mfma_f32_16x16x32_bf16 v[74:77], v[178:181], v[74:77], v[138:141]
	v_mfma_f32_16x16x32_bf16 v[138:141], v[182:185], v[78:81], v[74:77]
	v_mfma_f32_16x16x32_bf16 v[74:77], v[170:173], v[186:189], v[126:129]
	v_mfma_f32_16x16x32_bf16 v[126:129], v[174:177], v[226:229], v[74:77]
	v_mfma_f32_16x16x32_bf16 v[74:77], v[178:181], v[186:189], v[122:125]
	v_mfma_f32_16x16x32_bf16 v[122:125], v[182:185], v[226:229], v[74:77]
	v_mfma_f32_16x16x32_bf16 v[74:77], v[170:173], v[230:233], v[110:113]
	v_mfma_f32_16x16x32_bf16 v[110:113], v[174:177], v[234:237], v[74:77]
	v_mfma_f32_16x16x32_bf16 v[74:77], v[178:181], v[230:233], v[106:109]
	v_mfma_f32_16x16x32_bf16 v[106:109], v[182:185], v[234:237], v[74:77]
	v_mfma_f32_16x16x32_bf16 v[74:77], v[170:173], v[238:241], v[94:97]
	v_mfma_f32_16x16x32_bf16 v[94:97], v[174:177], v[242:245], v[74:77]
	v_mfma_f32_16x16x32_bf16 v[74:77], v[178:181], v[238:241], v[90:93]
	v_mfma_f32_16x16x32_bf16 v[142:145], v[174:177], v[78:81], v[142:145]
	v_mfma_f32_16x16x32_bf16 v[90:93], v[182:185], v[242:245], v[74:77]
	s_setprio 0
	s_barrier
; #define PG8_STAGE(bufoff, gbase, voff) do { _Pragma("unroll") for (int _i = 0; _i < 2; ++_i) \
;         __builtin_amdgcn_global_load_lds((const unsigned*)((const char*)(gbase) + (voff)[_i]), (PG8_LAS unsigned*)(lds + (bufoff) + ldsw + _i * 8192), 16, 0, 0); } while (0)
; #define PG8_LDA(dst, b, h) do { _Pragma("unroll") for (int m = 0; m < 4; ++m) _Pragma("unroll") for (int k = 0; k < 2; ++k) dst[m][k] = *(const PG8_LAS bf16x8*)(lds + PG8_SA(b, h) + aoff + m * 2048 + k * 1024); } while (0)
; #define PG8_MMA(ai, bj, At, Bt) do { __builtin_amdgcn_s_setprio(1); _Pragma("unroll") for (int m = 0; m < 4; ++m) _Pragma("unroll") for (int n = 0; n < 2; ++n) _Pragma("unroll") for (int k = 0; k < 2; ++k) \
;         acc[ai][bj][m][n] = __builtin_amdgcn_mfma_f32_16x16x32_bf16(Bt[n][k], At[m][k], acc[ai][bj][m][n], 0, 0, 0); __builtin_amdgcn_s_setprio(0); } while (0)
; #define PG8_WAIT_V(n) asm volatile("s_waitcnt vmcnt(" #n ")" ::: "memory")
; #define PG8_WAIT_L(n) asm volatile("s_waitcnt lgkmcnt(" #n ")" ::: "memory")
; #define PG8_BAR __builtin_amdgcn_s_barrier()
; #define PG8_SCHED __builtin_amdgcn_sched_barrier(0)
; template <class Epi, class Sched, bool ALIGN_EPI = false, bool SP2 = false>
; __device__ __forceinline__ void gemm_phase(PG8_LAS unsigned char* lds, const Gemm g, const Sched& S, const Epi& E) {
;     ...
;         for (int t = 0; t < nt; t += 2) {
;             const bool last = (t == nt - 2);
;             const char* a1 = cA + (size_t)(t + 1) * kstep;
;             const char* a2 = last ? nA : cA + (size_t)(t + 2) * kstep; const char* b2 = last ? nB : cB + (size_t)(t + 2) * kstep;
;             const char* a3 = a2 + kstep; const char* b3 = b2 + kstep;
;             if (last && has_next) S.a_ready(nxt);
;     ...
;             PG8_LDA(At, 1, 1); PG8_STAGE(PG8_SB(1, 0), b3, voffB); PG8_STAGE(PG8_SB(1, 1), b3 + hstep, voffB); PG8_STAGE(PG8_SA(1, 0), a3, voffA);
;             PG8_WAIT_V(8); PG8_WAIT_L(0); PG8_BAR; PG8_MMA(1, 0, At, B0); PG8_MMA(1, 1, At, B1); PG8_BAR; PG8_SCHED;
	s_add_i32 s14, s30, s20
	v_lshl_add_u64 v[78:79], v[190:191], 0, s[0:1]
	s_mov_b32 m0, s14
	s_nop 0
	ds_read_b128 v[74:77], v225 offset:49152
	ds_read_b128 v[186:189], v225 offset:50176
	ds_read_b128 v[226:229], v225 offset:51200
	ds_read_b128 v[230:233], v225 offset:52224
	ds_read_b128 v[234:237], v225 offset:53248
	ds_read_b128 v[238:241], v225 offset:54272
	ds_read_b128 v[242:245], v225 offset:55296
	ds_read_b128 v[246:249], v225 offset:56320
	global_load_lds_dwordx4 v[78:79], off
	s_add_i32 m0, s14, 0x2000
	s_add_u32 s10, s10, 0x40080
	v_lshl_add_u64 v[78:79], v[198:199], 0, s[0:1]
	s_addc_u32 s11, s11, 0
	s_add_i32 s14, s31, s20
	global_load_lds_dwordx4 v[78:79], off
	v_lshl_add_u64 v[78:79], s[10:11], 0, v[156:157]
	s_mov_b32 m0, s14
	s_nop 0
	global_load_lds_dwordx4 v[78:79], off
	v_lshl_add_u64 v[78:79], s[10:11], 0, v[160:161]
	s_add_i32 m0, s14, 0x2000
	s_nop 0
	global_load_lds_dwordx4 v[78:79], off
	v_lshl_add_u64 v[78:79], v[200:201], 0, s[0:1]
	s_mov_b32 m0, s64
	s_nop 0
	global_load_lds_dwordx4 v[78:79], off
	v_lshl_add_u64 v[78:79], v[250:251], 0, s[0:1]
	s_mov_b32 m0, s65
	s_nop 0
	global_load_lds_dwordx4 v[78:79], off
	s_waitcnt vmcnt(8)
	s_waitcnt lgkmcnt(0)
	s_barrier
	s_setprio 1
	s_waitcnt lgkmcnt(0)
	v_mfma_f32_16x16x32_bf16 v[78:81], v[46:49], v[74:77], v[86:89]
	v_mfma_f32_16x16x32_bf16 v[86:89], v[54:57], v[186:189], v[78:81]
	v_mfma_f32_16x16x32_bf16 v[78:81], v[58:61], v[74:77], v[82:85]
	v_mfma_f32_16x16x32_bf16 v[70:73], v[46:49], v[226:229], v[70:73]
	v_mfma_f32_16x16x32_bf16 v[66:69], v[58:61], v[226:229], v[66:69]
	v_mfma_f32_16x16x32_bf16 v[50:53], v[46:49], v[234:237], v[50:53]
	v_mfma_f32_16x16x32_bf16 v[42:45], v[58:61], v[234:237], v[42:45]
	v_mfma_f32_16x16x32_bf16 v[14:17], v[46:49], v[242:245], v[14:17]
	v_mfma_f32_16x16x32_bf16 v[10:13], v[58:61], v[242:245], v[10:13]
	v_mfma_f32_16x16x32_bf16 v[82:85], v[62:65], v[186:189], v[78:81]
	v_mfma_f32_16x16x32_bf16 v[70:73], v[54:57], v[230:233], v[70:73]
	v_mfma_f32_16x16x32_bf16 v[66:69], v[62:65], v[230:233], v[66:69]
	v_mfma_f32_16x16x32_bf16 v[50:53], v[54:57], v[238:241], v[50:53]
	v_mfma_f32_16x16x32_bf16 v[42:45], v[62:65], v[238:241], v[42:45]
	v_mfma_f32_16x16x32_bf16 v[14:17], v[54:57], v[246:249], v[14:17]
	v_mfma_f32_16x16x32_bf16 v[10:13], v[62:65], v[246:249], v[10:13]
	s_setprio 0
	s_setprio 1
	v_mfma_f32_16x16x32_bf16 v[18:21], v[170:173], v[74:77], v[18:21]
	v_mfma_f32_16x16x32_bf16 v[78:81], v[174:177], v[186:189], v[18:21]
	v_mfma_f32_16x16x32_bf16 v[18:21], v[178:181], v[74:77], v[22:25]
	v_mfma_f32_16x16x32_bf16 v[74:77], v[182:185], v[186:189], v[18:21]
	v_mfma_f32_16x16x32_bf16 v[18:21], v[170:173], v[226:229], v[26:29]
	v_mfma_f32_16x16x32_bf16 v[62:65], v[174:177], v[230:233], v[18:21]
	v_mfma_f32_16x16x32_bf16 v[18:21], v[178:181], v[226:229], v[30:33]
	v_mfma_f32_16x16x32_bf16 v[58:61], v[182:185], v[230:233], v[18:21]
	v_mfma_f32_16x16x32_bf16 v[18:21], v[170:173], v[234:237], v[38:41]
	v_mfma_f32_16x16x32_bf16 v[38:41], v[174:177], v[238:241], v[18:21]
	v_mfma_f32_16x16x32_bf16 v[18:21], v[178:181], v[234:237], v[34:37]
	v_mfma_f32_16x16x32_bf16 v[6:9], v[170:173], v[242:245], v[6:9]
	v_mfma_f32_16x16x32_bf16 v[2:5], v[178:181], v[242:245], v[2:5]
	v_mfma_f32_16x16x32_bf16 v[34:37], v[182:185], v[238:241], v[18:21]
	v_mfma_f32_16x16x32_bf16 v[6:9], v[174:177], v[246:249], v[6:9]
	v_mfma_f32_16x16x32_bf16 v[2:5], v[182:185], v[246:249], v[2:5]
	s_setprio 0
	s_add_i32 s43, s43, 2
	s_add_u32 s8, s8, 0x100
	s_addc_u32 s9, s9, 0
	s_add_u32 s41, s41, 0x100
	s_addc_u32 s42, s42, 0
	s_cmp_gt_u32 s43, 13
	s_cbranch_scc1 .Lrot_exit_p1
	s_add_u32 s10, s8, 0xfffc0080
	s_addc_u32 s11, s9, -1
	s_add_i32 s30, 0, 0x10000
	s_cmp_eq_u32 s43, 12
	s_cselect_b32 s15, s33, s11
	s_cselect_b32 s14, s34, s10
	v_add_u32_e32 v0, s30, v204
	s_cselect_b32 s11, s35, s42
	s_cselect_b32 s10, s40, s41
	s_add_i32 s51, 0, 0x14000
	s_barrier
	s_branch .LBB0_188
.Lrot_exit_p1:
	s_barrier

; #define PG8_STAGE(bufoff, gbase, voff) do { _Pragma("unroll") for (int _i = 0; _i < 2; ++_i) \
;         __builtin_amdgcn_global_load_lds((const unsigned*)((const char*)(gbase) + (voff)[_i]), (PG8_LAS unsigned*)(lds + (bufoff) + ldsw + _i * 8192), 16, 0, 0); } while (0)
; #define PG8_LDA(dst, b, h) do { _Pragma("unroll") for (int m = 0; m < 4; ++m) _Pragma("unroll") for (int k = 0; k < 2; ++k) dst[m][k] = *(const PG8_LAS bf16x8*)(lds + PG8_SA(b, h) + aoff + m * 2048 + k * 1024); } while (0)
; #define PG8_LDB(dst, b, h) do { _Pragma("unroll") for (int n = 0; n < 2; ++n) _Pragma("unroll") for (int k = 0; k < 2; ++k) dst[n][k] = *(const PG8_LAS bf16x8*)(lds + PG8_SB(b, h) + boff + n * 2048 + k * 1024); } while (0)
; #define PG8_MMA(ai, bj, At, Bt) do { __builtin_amdgcn_s_setprio(1); _Pragma("unroll") for (int m = 0; m < 4; ++m) _Pragma("unroll") for (int n = 0; n < 2; ++n) _Pragma("unroll") for (int k = 0; k < 2; ++k) \
;         acc[ai][bj][m][n] = __builtin_amdgcn_mfma_f32_16x16x32_bf16(Bt[n][k], At[m][k], acc[ai][bj][m][n], 0, 0, 0); __builtin_amdgcn_s_setprio(0); } while (0)
; #define PG8_WAIT_V(n) asm volatile("s_waitcnt vmcnt(" #n ")" ::: "memory")
; #define PG8_BAR __builtin_amdgcn_s_barrier()
; template <class Epi, class Sched, bool ALIGN_EPI = false, bool SP2 = false>
; __device__ __forceinline__ void gemm_phase(PG8_LAS unsigned char* lds, const Gemm g, const Sched& S, const Epi& E) {
;     ...
;         for (int t = 0; t < nt; t += 2) {
;             const bool last = (t == nt - 2);
;             const char* a1 = cA + (size_t)(t + 1) * kstep;
;             const char* a2 = last ? nA : cA + (size_t)(t + 2) * kstep; const char* b2 = last ? nB : cB + (size_t)(t + 2) * kstep;
;             const char* a3 = a2 + kstep; const char* b3 = b2 + kstep;
;             if (last && has_next) S.a_ready(nxt);
;             if constexpr (SP2) {
;             PG8_LDB(B0, 0, 0); PG8_LDB(B1, 0, 1); PG8_SCHED; PG8_LDA(At, 0, 0); PG8_STAGE(PG8_SA(1, 1), a1 + hstep, voffA);
;             PG8_WAIT_V(8); PG8_WAIT_L(0); PG8_BAR; PG8_MMA(0, 0, At, B0); PG8_MMA(0, 1, At, B1); PG8_BAR; PG8_SCHED;
;             PG8_LDA(At, 0, 1); PG8_STAGE(PG8_SB(0, 0), b2, voffB); PG8_STAGE(PG8_SB(0, 1), b2 + hstep, voffB); PG8_STAGE(PG8_SA(0, 0), a2, voffA);
;             PG8_WAIT_V(8); PG8_WAIT_L(0); PG8_BAR; PG8_MMA(1, 0, At, B0); PG8_MMA(1, 1, At, B1); PG8_BAR; PG8_SCHED;
.Lpeel_p3:
	s_add_u32 s30, s44, 0xfffc0080
	s_addc_u32 s31, s45, -1
	s_add_i32 s62, 0, 0x10000
	s_cmp_eq_u32 s61, 12
	s_cselect_b32 s49, s15, s31
	s_cselect_b32 s48, s34, s30
	s_cselect_b32 s47, s11, s60
	s_cselect_b32 s46, s35, s59
	s_add_i32 s63, 0, 0x14000
	v_add_u32_e32 v134, s62, v185
	v_add_u32_e32 v168, s63, v185
	ds_read_b128 v[114:117], v134
	ds_read_b128 v[118:121], v134 offset:1024
	ds_read_b128 v[126:129], v134 offset:2048
	ds_read_b128 v[134:137], v134 offset:3072
	ds_read_b128 v[146:149], v168
	ds_read_b128 v[150:153], v168 offset:1024
	ds_read_b128 v[164:167], v168 offset:2048
	ds_read_b128 v[168:171], v168 offset:3072
	v_lshl_add_u64 v[210:211], s[44:45], 0, v[160:161]
	s_add_i32 m0, s50, 0xc000
	ds_read_b128 v[172:175], v187
	ds_read_b128 v[176:179], v187 offset:1024
	ds_read_b128 v[180:183], v187 offset:2048
	ds_read_b128 v[188:191], v187 offset:3072
	ds_read_b128 v[198:201], v187 offset:4096
	ds_read_b128 v[202:205], v187 offset:5120
	ds_read_b128 v[206:209], v187 offset:6144
	ds_read_b128 v[222:225], v187 offset:7168
	global_load_lds_dwordx4 v[210:211], off
	v_lshl_add_u64 v[210:211], s[44:45], 0, v[162:163]
	s_add_i32 m0, s50, 0xe000
	s_nop 0
	global_load_lds_dwordx4 v[210:211], off
	s_waitcnt vmcnt(8)
	s_waitcnt lgkmcnt(0)
	s_barrier
	s_setprio 1
	s_waitcnt lgkmcnt(0)
	v_mfma_f32_16x16x32_bf16 v[142:145], v[114:117], v[172:175], 0
	v_mfma_f32_16x16x32_bf16 v[138:141], v[126:129], v[172:175], 0
	v_mfma_f32_16x16x32_bf16 v[110:113], v[114:117], v[180:183], 0
	v_mfma_f32_16x16x32_bf16 v[106:109], v[126:129], v[180:183], 0
	v_mfma_f32_16x16x32_bf16 v[94:97], v[114:117], v[198:201], 0
	v_mfma_f32_16x16x32_bf16 v[90:93], v[126:129], v[198:201], 0
	v_mfma_f32_16x16x32_bf16 v[78:81], v[114:117], v[206:209], 0
	v_mfma_f32_16x16x32_bf16 v[74:77], v[126:129], v[206:209], 0
	v_mfma_f32_16x16x32_bf16 v[142:145], v[118:121], v[176:179], v[142:145]
	v_mfma_f32_16x16x32_bf16 v[138:141], v[134:137], v[176:179], v[138:141]
	v_mfma_f32_16x16x32_bf16 v[110:113], v[118:121], v[188:191], v[110:113]
	v_mfma_f32_16x16x32_bf16 v[106:109], v[134:137], v[188:191], v[106:109]
	v_mfma_f32_16x16x32_bf16 v[94:97], v[118:121], v[202:205], v[94:97]
	v_mfma_f32_16x16x32_bf16 v[90:93], v[134:137], v[202:205], v[90:93]
	v_mfma_f32_16x16x32_bf16 v[78:81], v[118:121], v[222:225], v[78:81]
	v_mfma_f32_16x16x32_bf16 v[74:77], v[134:137], v[222:225], v[74:77]
	s_setprio 0
	s_setprio 1
	v_mfma_f32_16x16x32_bf16 v[130:133], v[146:149], v[172:175], 0
	v_mfma_f32_16x16x32_bf16 v[122:125], v[164:167], v[172:175], 0
	v_mfma_f32_16x16x32_bf16 v[102:105], v[146:149], v[180:183], 0
	v_mfma_f32_16x16x32_bf16 v[98:101], v[164:167], v[180:183], 0
	v_mfma_f32_16x16x32_bf16 v[86:89], v[146:149], v[198:201], 0
	v_mfma_f32_16x16x32_bf16 v[82:85], v[164:167], v[198:201], 0
	v_mfma_f32_16x16x32_bf16 v[70:73], v[146:149], v[206:209], 0
	v_mfma_f32_16x16x32_bf16 v[66:69], v[164:167], v[206:209], 0
	v_mfma_f32_16x16x32_bf16 v[130:133], v[150:153], v[176:179], v[130:133]
	v_mfma_f32_16x16x32_bf16 v[122:125], v[168:171], v[176:179], v[122:125]
	v_mfma_f32_16x16x32_bf16 v[102:105], v[150:153], v[188:191], v[102:105]
	v_mfma_f32_16x16x32_bf16 v[98:101], v[168:171], v[188:191], v[98:101]
	v_mfma_f32_16x16x32_bf16 v[86:89], v[150:153], v[202:205], v[86:89]
	v_mfma_f32_16x16x32_bf16 v[82:85], v[168:171], v[202:205], v[82:85]
	v_mfma_f32_16x16x32_bf16 v[70:73], v[150:153], v[222:225], v[70:73]
	v_mfma_f32_16x16x32_bf16 v[66:69], v[168:171], v[222:225], v[66:69]
	s_setprio 0
	s_barrier
	s_add_i32 s30, s62, s33
	v_lshl_add_u64 v[210:211], s[46:47], 0, v[0:1]
	s_mov_b32 m0, s30
	ds_read_b128 v[172:175], v187 offset:16384
	ds_read_b128 v[176:179], v187 offset:17408
	ds_read_b128 v[180:183], v187 offset:18432
	ds_read_b128 v[188:191], v187 offset:19456
	ds_read_b128 v[198:201], v187 offset:20480
	ds_read_b128 v[202:205], v187 offset:21504
	ds_read_b128 v[206:209], v187 offset:22528
	ds_read_b128 v[222:225], v187 offset:23552
	global_load_lds_dwordx4 v[210:211], off
	s_add_i32 m0, s30, 0x2000
	s_add_u32 s30, s46, 0x40000
	v_lshl_add_u64 v[226:227], s[46:47], 0, v[154:155]
	s_addc_u32 s31, s47, 0
	s_add_i32 s62, s63, s33
	global_load_lds_dwordx4 v[226:227], off
	v_lshl_add_u64 v[228:229], s[30:31], 0, v[0:1]
	s_mov_b32 m0, s62
	v_lshl_add_u64 v[230:231], s[48:49], 0, v[156:157]
	global_load_lds_dwordx4 v[228:229], off
	v_lshl_add_u64 v[228:229], s[30:31], 0, v[154:155]
	s_add_i32 m0, s62, 0x2000
	s_nop 0
	global_load_lds_dwordx4 v[228:229], off
	v_lshl_add_u64 v[228:229], s[48:49], 0, v[158:159]
	s_mov_b32 m0, s50
	s_nop 0
	global_load_lds_dwordx4 v[228:229], off
	s_mov_b32 m0, s51
	s_nop 0
	global_load_lds_dwordx4 v[230:231], off
	s_waitcnt vmcnt(8)
	s_waitcnt lgkmcnt(0)
	s_barrier
; #define PG8_STAGE(bufoff, gbase, voff) do { _Pragma("unroll") for (int _i = 0; _i < 2; ++_i) \
;         __builtin_amdgcn_global_load_lds((const unsigned*)((const char*)(gbase) + (voff)[_i]), (PG8_LAS unsigned*)(lds + (bufoff) + ldsw + _i * 8192), 16, 0, 0); } while (0)
; #define PG8_LDA(dst, b, h) do { _Pragma("unroll") for (int m = 0; m < 4; ++m) _Pragma("unroll") for (int k = 0; k < 2; ++k) dst[m][k] = *(const PG8_LAS bf16x8*)(lds + PG8_SA(b, h) + aoff + m * 2048 + k * 1024); } while (0)
; #define PG8_LDB(dst, b, h) do { _Pragma("unroll") for (int n = 0; n < 2; ++n) _Pragma("unroll") for (int k = 0; k < 2; ++k) dst[n][k] = *(const PG8_LAS bf16x8*)(lds + PG8_SB(b, h) + boff + n * 2048 + k * 1024); } while (0)
; #define PG8_MMA(ai, bj, At, Bt) do { __builtin_amdgcn_s_setprio(1); _Pragma("unroll") for (int m = 0; m < 4; ++m) _Pragma("unroll") for (int n = 0; n < 2; ++n) _Pragma("unroll") for (int k = 0; k < 2; ++k) \
;         acc[ai][bj][m][n] = __builtin_amdgcn_mfma_f32_16x16x32_bf16(Bt[n][k], At[m][k], acc[ai][bj][m][n], 0, 0, 0); __builtin_amdgcn_s_setprio(0); } while (0)
; #define PG8_WAIT_V(n) asm volatile("s_waitcnt vmcnt(" #n ")" ::: "memory")
; #define PG8_WAIT_L(n) asm volatile("s_waitcnt lgkmcnt(" #n ")" ::: "memory")
; #define PG8_BAR __builtin_amdgcn_s_barrier()
; #define PG8_SCHED __builtin_amdgcn_sched_barrier(0)
; template <class Epi, class Sched, bool ALIGN_EPI = false, bool SP2 = false>
; __device__ __forceinline__ void gemm_phase(PG8_LAS unsigned char* lds, const Gemm g, const Sched& S, const Epi& E) {
;     ...
;             PG8_WAIT_V(8); PG8_WAIT_L(0); PG8_BAR; PG8_MMA(1, 0, At, B0); PG8_MMA(1, 1, At, B1); PG8_BAR; PG8_SCHED;
;             PG8_LDB(B0, 1, 0); PG8_LDB(B1, 1, 1); PG8_SCHED; PG8_LDA(At, 1, 0); PG8_STAGE(PG8_SA(0, 1), a2 + hstep, voffA);
;             PG8_WAIT_V(8); PG8_WAIT_L(0); PG8_BAR; PG8_MMA(0, 0, At, B0); PG8_MMA(0, 1, At, B1); PG8_BAR; PG8_SCHED;
	s_setprio 1
	s_waitcnt lgkmcnt(0)
	v_mfma_f32_16x16x32_bf16 v[62:65], v[114:117], v[172:175], 0
	v_mfma_f32_16x16x32_bf16 v[58:61], v[126:129], v[172:175], 0
	v_mfma_f32_16x16x32_bf16 v[46:49], v[114:117], v[180:183], 0
	v_mfma_f32_16x16x32_bf16 v[42:45], v[126:129], v[180:183], 0
	v_mfma_f32_16x16x32_bf16 v[30:33], v[114:117], v[198:201], 0
	v_mfma_f32_16x16x32_bf16 v[26:29], v[126:129], v[198:201], 0
	v_mfma_f32_16x16x32_bf16 v[14:17], v[114:117], v[206:209], 0
	v_mfma_f32_16x16x32_bf16 v[10:13], v[126:129], v[206:209], 0
	v_mfma_f32_16x16x32_bf16 v[62:65], v[118:121], v[176:179], v[62:65]
	v_mfma_f32_16x16x32_bf16 v[58:61], v[134:137], v[176:179], v[58:61]
	v_mfma_f32_16x16x32_bf16 v[46:49], v[118:121], v[188:191], v[46:49]
	v_mfma_f32_16x16x32_bf16 v[42:45], v[134:137], v[188:191], v[42:45]
	v_mfma_f32_16x16x32_bf16 v[30:33], v[118:121], v[202:205], v[30:33]
	v_mfma_f32_16x16x32_bf16 v[26:29], v[134:137], v[202:205], v[26:29]
	v_mfma_f32_16x16x32_bf16 v[14:17], v[118:121], v[222:225], v[14:17]
	v_mfma_f32_16x16x32_bf16 v[10:13], v[134:137], v[222:225], v[10:13]
	s_setprio 0
	s_setprio 1
	v_mfma_f32_16x16x32_bf16 v[54:57], v[146:149], v[172:175], 0
	v_mfma_f32_16x16x32_bf16 v[50:53], v[164:167], v[172:175], 0
	v_mfma_f32_16x16x32_bf16 v[38:41], v[146:149], v[180:183], 0
	v_mfma_f32_16x16x32_bf16 v[34:37], v[164:167], v[180:183], 0
	v_mfma_f32_16x16x32_bf16 v[22:25], v[146:149], v[198:201], 0
	v_mfma_f32_16x16x32_bf16 v[18:21], v[164:167], v[198:201], 0
	v_mfma_f32_16x16x32_bf16 v[6:9], v[146:149], v[206:209], 0
	v_mfma_f32_16x16x32_bf16 v[2:5], v[164:167], v[206:209], 0
	v_mfma_f32_16x16x32_bf16 v[54:57], v[150:153], v[176:179], v[54:57]
	v_mfma_f32_16x16x32_bf16 v[50:53], v[168:171], v[176:179], v[50:53]
	v_mfma_f32_16x16x32_bf16 v[38:41], v[150:153], v[188:191], v[38:41]
	v_mfma_f32_16x16x32_bf16 v[34:37], v[168:171], v[188:191], v[34:37]
	v_mfma_f32_16x16x32_bf16 v[22:25], v[150:153], v[202:205], v[22:25]
	v_mfma_f32_16x16x32_bf16 v[18:21], v[168:171], v[202:205], v[18:21]
	v_mfma_f32_16x16x32_bf16 v[6:9], v[150:153], v[222:225], v[6:9]
	v_mfma_f32_16x16x32_bf16 v[2:5], v[168:171], v[222:225], v[2:5]
	s_setprio 0
	s_barrier
	s_add_i32 s62, 0, 0x18000
	s_add_i32 s63, 0, 0x1c000
	v_add_u32_e32 v134, s62, v185
	v_add_u32_e32 v168, s63, v185
	ds_read_b128 v[114:117], v134
	ds_read_b128 v[118:121], v134 offset:1024
	ds_read_b128 v[126:129], v134 offset:2048
	ds_read_b128 v[134:137], v134 offset:3072
	ds_read_b128 v[146:149], v168
	ds_read_b128 v[150:153], v168 offset:1024
	ds_read_b128 v[164:167], v168 offset:2048
	ds_read_b128 v[168:171], v168 offset:3072
	s_add_u32 s30, s48, 0x40000
	s_addc_u32 s31, s49, 0
	s_mov_b32 m0, s52
	v_lshl_add_u64 v[232:233], s[30:31], 0, v[158:159]
	ds_read_b128 v[172:175], v187 offset:32768
	ds_read_b128 v[176:179], v187 offset:33792
	ds_read_b128 v[180:183], v187 offset:34816
	ds_read_b128 v[188:191], v187 offset:35840
	ds_read_b128 v[198:201], v187 offset:36864
	ds_read_b128 v[202:205], v187 offset:37888
	ds_read_b128 v[206:209], v187 offset:38912
	ds_read_b128 v[222:225], v187 offset:39936
	global_load_lds_dwordx4 v[232:233], off
	v_lshl_add_u64 v[232:233], s[30:31], 0, v[156:157]
	s_mov_b32 m0, s53
	s_nop 0
	global_load_lds_dwordx4 v[232:233], off
	s_waitcnt vmcnt(8)
	s_waitcnt lgkmcnt(0)
	s_barrier
	s_setprio 1
	s_waitcnt lgkmcnt(0)
	v_mfma_f32_16x16x32_bf16 v[142:145], v[114:117], v[172:175], v[142:145]
	v_mfma_f32_16x16x32_bf16 v[138:141], v[126:129], v[172:175], v[138:141]
	v_mfma_f32_16x16x32_bf16 v[110:113], v[114:117], v[180:183], v[110:113]
	v_mfma_f32_16x16x32_bf16 v[106:109], v[126:129], v[180:183], v[106:109]
	v_mfma_f32_16x16x32_bf16 v[94:97], v[114:117], v[198:201], v[94:97]
	v_mfma_f32_16x16x32_bf16 v[90:93], v[126:129], v[198:201], v[90:93]
	v_mfma_f32_16x16x32_bf16 v[78:81], v[114:117], v[206:209], v[78:81]
	v_mfma_f32_16x16x32_bf16 v[74:77], v[126:129], v[206:209], v[74:77]
	v_mfma_f32_16x16x32_bf16 v[142:145], v[118:121], v[176:179], v[142:145]
	v_mfma_f32_16x16x32_bf16 v[138:141], v[134:137], v[176:179], v[138:141]
	v_mfma_f32_16x16x32_bf16 v[110:113], v[118:121], v[188:191], v[110:113]
	v_mfma_f32_16x16x32_bf16 v[106:109], v[134:137], v[188:191], v[106:109]
	v_mfma_f32_16x16x32_bf16 v[94:97], v[118:121], v[202:205], v[94:97]
	v_mfma_f32_16x16x32_bf16 v[90:93], v[134:137], v[202:205], v[90:93]
	v_mfma_f32_16x16x32_bf16 v[78:81], v[118:121], v[222:225], v[78:81]
	v_mfma_f32_16x16x32_bf16 v[74:77], v[134:137], v[222:225], v[74:77]
	s_setprio 0
	s_setprio 1
	v_mfma_f32_16x16x32_bf16 v[130:133], v[146:149], v[172:175], v[130:133]
	v_mfma_f32_16x16x32_bf16 v[122:125], v[164:167], v[172:175], v[122:125]
	v_mfma_f32_16x16x32_bf16 v[102:105], v[146:149], v[180:183], v[102:105]
	v_mfma_f32_16x16x32_bf16 v[98:101], v[164:167], v[180:183], v[98:101]
	v_mfma_f32_16x16x32_bf16 v[86:89], v[146:149], v[198:201], v[86:89]
	v_mfma_f32_16x16x32_bf16 v[82:85], v[164:167], v[198:201], v[82:85]
	v_mfma_f32_16x16x32_bf16 v[70:73], v[146:149], v[206:209], v[70:73]
	v_mfma_f32_16x16x32_bf16 v[66:69], v[164:167], v[206:209], v[66:69]
	v_mfma_f32_16x16x32_bf16 v[130:133], v[150:153], v[176:179], v[130:133]
	v_mfma_f32_16x16x32_bf16 v[122:125], v[168:171], v[176:179], v[122:125]
	v_mfma_f32_16x16x32_bf16 v[102:105], v[150:153], v[188:191], v[102:105]
	v_mfma_f32_16x16x32_bf16 v[98:101], v[168:171], v[188:191], v[98:101]
	v_mfma_f32_16x16x32_bf16 v[86:89], v[150:153], v[202:205], v[86:89]
	v_mfma_f32_16x16x32_bf16 v[82:85], v[168:171], v[202:205], v[82:85]
	v_mfma_f32_16x16x32_bf16 v[70:73], v[150:153], v[222:225], v[70:73]
	v_mfma_f32_16x16x32_bf16 v[66:69], v[168:171], v[222:225], v[66:69]
	s_setprio 0
	s_barrier
; #define PG8_STAGE(bufoff, gbase, voff) do { _Pragma("unroll") for (int _i = 0; _i < 2; ++_i) \
;         __builtin_amdgcn_global_load_lds((const unsigned*)((const char*)(gbase) + (voff)[_i]), (PG8_LAS unsigned*)(lds + (bufoff) + ldsw + _i * 8192), 16, 0, 0); } while (0)
; #define PG8_LDA(dst, b, h) do { _Pragma("unroll") for (int m = 0; m < 4; ++m) _Pragma("unroll") for (int k = 0; k < 2; ++k) dst[m][k] = *(const PG8_LAS bf16x8*)(lds + PG8_SA(b, h) + aoff + m * 2048 + k * 1024); } while (0)
; #define PG8_MMA(ai, bj, At, Bt) do { __builtin_amdgcn_s_setprio(1); _Pragma("unroll") for (int m = 0; m < 4; ++m) _Pragma("unroll") for (int n = 0; n < 2; ++n) _Pragma("unroll") for (int k = 0; k < 2; ++k) \
;         acc[ai][bj][m][n] = __builtin_amdgcn_mfma_f32_16x16x32_bf16(Bt[n][k], At[m][k], acc[ai][bj][m][n], 0, 0, 0); __builtin_amdgcn_s_setprio(0); } while (0)
; #define PG8_WAIT_V(n) asm volatile("s_waitcnt vmcnt(" #n ")" ::: "memory")
; #define PG8_WAIT_L(n) asm volatile("s_waitcnt lgkmcnt(" #n ")" ::: "memory")
; #define PG8_BAR __builtin_amdgcn_s_barrier()
; #define PG8_SCHED __builtin_amdgcn_sched_barrier(0)
; template <class Epi, class Sched, bool ALIGN_EPI = false, bool SP2 = false>
; __device__ __forceinline__ void gemm_phase(PG8_LAS unsigned char* lds, const Gemm g, const Sched& S, const Epi& E) {
;     ...
;         for (int t = 0; t < nt; t += 2) {
;             const bool last = (t == nt - 2);
;             const char* a1 = cA + (size_t)(t + 1) * kstep;
;             const char* a2 = last ? nA : cA + (size_t)(t + 2) * kstep; const char* b2 = last ? nB : cB + (size_t)(t + 2) * kstep;
;             const char* a3 = a2 + kstep; const char* b3 = b2 + kstep;
;             if (last && has_next) S.a_ready(nxt);
;     ...
;             PG8_LDA(At, 1, 1); PG8_STAGE(PG8_SB(1, 0), b3, voffB); PG8_STAGE(PG8_SB(1, 1), b3 + hstep, voffB); PG8_STAGE(PG8_SA(1, 0), a3, voffA);
;             PG8_WAIT_V(8); PG8_WAIT_L(0); PG8_BAR; PG8_MMA(1, 0, At, B0); PG8_MMA(1, 1, At, B1); PG8_BAR; PG8_SCHED;
	s_add_i32 s30, s62, s33
	v_lshl_add_u64 v[210:211], v[210:211], 0, s[0:1]
	s_mov_b32 m0, s30
	ds_read_b128 v[172:175], v187 offset:49152
	ds_read_b128 v[176:179], v187 offset:50176
	ds_read_b128 v[180:183], v187 offset:51200
	ds_read_b128 v[188:191], v187 offset:52224
	ds_read_b128 v[198:201], v187 offset:53248
	ds_read_b128 v[202:205], v187 offset:54272
	ds_read_b128 v[206:209], v187 offset:55296
	ds_read_b128 v[222:225], v187 offset:56320
	global_load_lds_dwordx4 v[210:211], off
	s_add_i32 m0, s30, 0x2000
	s_add_u32 s30, s46, 0x40080
	v_lshl_add_u64 v[210:211], v[226:227], 0, s[0:1]
	s_addc_u32 s31, s47, 0
	s_add_i32 s46, s63, s33
	global_load_lds_dwordx4 v[210:211], off
	v_lshl_add_u64 v[210:211], s[30:31], 0, v[0:1]
	s_mov_b32 m0, s46
	s_nop 0
	global_load_lds_dwordx4 v[210:211], off
	v_lshl_add_u64 v[210:211], s[30:31], 0, v[154:155]
	s_add_i32 m0, s46, 0x2000
	s_nop 0
	global_load_lds_dwordx4 v[210:211], off
	v_lshl_add_u64 v[210:211], v[228:229], 0, s[0:1]
	s_mov_b32 m0, s56
	s_nop 0
	global_load_lds_dwordx4 v[210:211], off
	v_lshl_add_u64 v[210:211], v[230:231], 0, s[0:1]
	s_mov_b32 m0, s57
	s_nop 0
	global_load_lds_dwordx4 v[210:211], off
	s_waitcnt vmcnt(8)
	s_waitcnt lgkmcnt(0)
	s_barrier
	s_setprio 1
	s_waitcnt lgkmcnt(0)
	v_mfma_f32_16x16x32_bf16 v[62:65], v[114:117], v[172:175], v[62:65]
	v_mfma_f32_16x16x32_bf16 v[58:61], v[126:129], v[172:175], v[58:61]
	v_mfma_f32_16x16x32_bf16 v[46:49], v[114:117], v[180:183], v[46:49]
	v_mfma_f32_16x16x32_bf16 v[42:45], v[126:129], v[180:183], v[42:45]
	v_mfma_f32_16x16x32_bf16 v[30:33], v[114:117], v[198:201], v[30:33]
	v_mfma_f32_16x16x32_bf16 v[26:29], v[126:129], v[198:201], v[26:29]
	v_mfma_f32_16x16x32_bf16 v[14:17], v[114:117], v[206:209], v[14:17]
	v_mfma_f32_16x16x32_bf16 v[10:13], v[126:129], v[206:209], v[10:13]
	v_mfma_f32_16x16x32_bf16 v[62:65], v[118:121], v[176:179], v[62:65]
	v_mfma_f32_16x16x32_bf16 v[58:61], v[134:137], v[176:179], v[58:61]
	v_mfma_f32_16x16x32_bf16 v[46:49], v[118:121], v[188:191], v[46:49]
	v_mfma_f32_16x16x32_bf16 v[42:45], v[134:137], v[188:191], v[42:45]
	v_mfma_f32_16x16x32_bf16 v[30:33], v[118:121], v[202:205], v[30:33]
	v_mfma_f32_16x16x32_bf16 v[26:29], v[134:137], v[202:205], v[26:29]
	v_mfma_f32_16x16x32_bf16 v[14:17], v[118:121], v[222:225], v[14:17]
	v_mfma_f32_16x16x32_bf16 v[10:13], v[134:137], v[222:225], v[10:13]
	s_setprio 0
	s_setprio 1
	v_mfma_f32_16x16x32_bf16 v[54:57], v[146:149], v[172:175], v[54:57]
	v_mfma_f32_16x16x32_bf16 v[50:53], v[164:167], v[172:175], v[50:53]
	v_mfma_f32_16x16x32_bf16 v[38:41], v[146:149], v[180:183], v[38:41]
	v_mfma_f32_16x16x32_bf16 v[34:37], v[164:167], v[180:183], v[34:37]
	v_mfma_f32_16x16x32_bf16 v[22:25], v[146:149], v[198:201], v[22:25]
	v_mfma_f32_16x16x32_bf16 v[18:21], v[164:167], v[198:201], v[18:21]
	v_mfma_f32_16x16x32_bf16 v[6:9], v[146:149], v[206:209], v[6:9]
	v_mfma_f32_16x16x32_bf16 v[2:5], v[164:167], v[206:209], v[2:5]
	v_mfma_f32_16x16x32_bf16 v[54:57], v[150:153], v[176:179], v[54:57]
	v_mfma_f32_16x16x32_bf16 v[50:53], v[168:171], v[176:179], v[50:53]
	v_mfma_f32_16x16x32_bf16 v[38:41], v[150:153], v[188:191], v[38:41]
	v_mfma_f32_16x16x32_bf16 v[34:37], v[168:171], v[188:191], v[34:37]
	v_mfma_f32_16x16x32_bf16 v[22:25], v[150:153], v[202:205], v[22:25]
	v_mfma_f32_16x16x32_bf16 v[18:21], v[168:171], v[202:205], v[18:21]
	v_mfma_f32_16x16x32_bf16 v[6:9], v[150:153], v[222:225], v[6:9]
	v_mfma_f32_16x16x32_bf16 v[2:5], v[168:171], v[222:225], v[2:5]
	s_setprio 0
	s_add_i32 s61, s61, 2
	s_add_u32 s44, s44, 0x100
	s_addc_u32 s45, s45, 0
	s_add_u32 s59, s59, 0x100
	s_addc_u32 s60, s60, 0
	s_cmp_gt_u32 s61, 13
	s_cbranch_scc1 .Lrot_exit_peel_p3
	s_add_u32 s30, s44, 0xfffc0080
	s_addc_u32 s31, s45, -1
	s_add_i32 s62, 0, 0x10000
	s_cmp_eq_u32 s61, 12
	s_cselect_b32 s49, s15, s31
	s_cselect_b32 s48, s34, s30
	s_cselect_b32 s47, s11, s60
	s_cselect_b32 s46, s35, s59
	s_add_i32 s63, 0, 0x14000
	v_add_u32_e32 v134, s62, v185
	v_add_u32_e32 v168, s63, v185
	s_barrier
	s_branch .LBB0_676

; #define PG8_STAGE(bufoff, gbase, voff) do { _Pragma("unroll") for (int _i = 0; _i < 2; ++_i) \
;         __builtin_amdgcn_global_load_lds((const unsigned*)((const char*)(gbase) + (voff)[_i]), (PG8_LAS unsigned*)(lds + (bufoff) + ldsw + _i * 8192), 16, 0, 0); } while (0)
; #define PG8_LDA(dst, b, h) do { _Pragma("unroll") for (int m = 0; m < 4; ++m) _Pragma("unroll") for (int k = 0; k < 2; ++k) dst[m][k] = *(const PG8_LAS bf16x8*)(lds + PG8_SA(b, h) + aoff + m * 2048 + k * 1024); } while (0)
; #define PG8_LDB(dst, b, h) do { _Pragma("unroll") for (int n = 0; n < 2; ++n) _Pragma("unroll") for (int k = 0; k < 2; ++k) dst[n][k] = *(const PG8_LAS bf16x8*)(lds + PG8_SB(b, h) + boff + n * 2048 + k * 1024); } while (0)
; #define PG8_MMA(ai, bj, At, Bt) do { __builtin_amdgcn_s_setprio(1); _Pragma("unroll") for (int m = 0; m < 4; ++m) _Pragma("unroll") for (int n = 0; n < 2; ++n) _Pragma("unroll") for (int k = 0; k < 2; ++k) \
;         acc[ai][bj][m][n] = __builtin_amdgcn_mfma_f32_16x16x32_bf16(Bt[n][k], At[m][k], acc[ai][bj][m][n], 0, 0, 0); __builtin_amdgcn_s_setprio(0); } while (0)
; #define PG8_WAIT_V(n) asm volatile("s_waitcnt vmcnt(" #n ")" ::: "memory")
; #define PG8_WAIT_L(n) asm volatile("s_waitcnt lgkmcnt(" #n ")" ::: "memory")
; #define PG8_BAR __builtin_amdgcn_s_barrier()
; #define PG8_SCHED __builtin_amdgcn_sched_barrier(0)
; template <class Epi, class Sched, bool ALIGN_EPI = false, bool SP2 = false>
; __device__ __forceinline__ void gemm_phase(PG8_LAS unsigned char* lds, const Gemm g, const Sched& S, const Epi& E) {
;     ...
;             PG8_LDB(B0, 0, 0); PG8_LDB(B1, 0, 1); PG8_SCHED; PG8_LDA(At, 0, 0); PG8_STAGE(PG8_SA(1, 1), a1 + hstep, voffA);
;             PG8_WAIT_V(8); PG8_WAIT_L(0); PG8_BAR; PG8_MMA(0, 0, At, B0); PG8_MMA(0, 1, At, B1); PG8_BAR; PG8_SCHED;
;             PG8_LDA(At, 0, 1); PG8_STAGE(PG8_SB(0, 0), b2, voffB); PG8_STAGE(PG8_SB(0, 1), b2 + hstep, voffB); PG8_STAGE(PG8_SA(0, 0), a2, voffA);
.LBB0_676:
	ds_read_b128 v[114:117], v134
	ds_read_b128 v[118:121], v134 offset:1024
	ds_read_b128 v[126:129], v134 offset:2048
	ds_read_b128 v[134:137], v134 offset:3072
	ds_read_b128 v[146:149], v168
	ds_read_b128 v[150:153], v168 offset:1024
	ds_read_b128 v[164:167], v168 offset:2048
	ds_read_b128 v[168:171], v168 offset:3072
	v_lshl_add_u64 v[210:211], s[44:45], 0, v[160:161]
	s_add_i32 m0, s50, 0xc000
	ds_read_b128 v[172:175], v187
	ds_read_b128 v[176:179], v187 offset:1024
	ds_read_b128 v[180:183], v187 offset:2048
	ds_read_b128 v[188:191], v187 offset:3072
	ds_read_b128 v[198:201], v187 offset:4096
	ds_read_b128 v[202:205], v187 offset:5120
	ds_read_b128 v[206:209], v187 offset:6144
	ds_read_b128 v[222:225], v187 offset:7168
	global_load_lds_dwordx4 v[210:211], off
	v_lshl_add_u64 v[210:211], s[44:45], 0, v[162:163]
	s_add_i32 m0, s50, 0xe000
	s_nop 0
	global_load_lds_dwordx4 v[210:211], off
	s_waitcnt vmcnt(8)
	s_waitcnt lgkmcnt(0)
	s_barrier
	s_setprio 1
	s_waitcnt lgkmcnt(0)
	v_mfma_f32_16x16x32_bf16 v[142:145], v[114:117], v[172:175], v[142:145]
	v_mfma_f32_16x16x32_bf16 v[138:141], v[126:129], v[172:175], v[138:141]
	v_mfma_f32_16x16x32_bf16 v[110:113], v[114:117], v[180:183], v[110:113]
	v_mfma_f32_16x16x32_bf16 v[106:109], v[126:129], v[180:183], v[106:109]
	v_mfma_f32_16x16x32_bf16 v[94:97], v[114:117], v[198:201], v[94:97]
	v_mfma_f32_16x16x32_bf16 v[90:93], v[126:129], v[198:201], v[90:93]
	v_mfma_f32_16x16x32_bf16 v[78:81], v[114:117], v[206:209], v[78:81]
	v_mfma_f32_16x16x32_bf16 v[74:77], v[126:129], v[206:209], v[74:77]
	v_mfma_f32_16x16x32_bf16 v[142:145], v[118:121], v[176:179], v[142:145]
	v_mfma_f32_16x16x32_bf16 v[138:141], v[134:137], v[176:179], v[138:141]
	v_mfma_f32_16x16x32_bf16 v[110:113], v[118:121], v[188:191], v[110:113]
	v_mfma_f32_16x16x32_bf16 v[106:109], v[134:137], v[188:191], v[106:109]
	v_mfma_f32_16x16x32_bf16 v[94:97], v[118:121], v[202:205], v[94:97]
	v_mfma_f32_16x16x32_bf16 v[90:93], v[134:137], v[202:205], v[90:93]
	v_mfma_f32_16x16x32_bf16 v[78:81], v[118:121], v[222:225], v[78:81]
	v_mfma_f32_16x16x32_bf16 v[74:77], v[134:137], v[222:225], v[74:77]
	s_setprio 0
	s_setprio 1
	v_mfma_f32_16x16x32_bf16 v[130:133], v[146:149], v[172:175], v[130:133]
	v_mfma_f32_16x16x32_bf16 v[122:125], v[164:167], v[172:175], v[122:125]
	v_mfma_f32_16x16x32_bf16 v[102:105], v[146:149], v[180:183], v[102:105]
	v_mfma_f32_16x16x32_bf16 v[98:101], v[164:167], v[180:183], v[98:101]
	v_mfma_f32_16x16x32_bf16 v[86:89], v[146:149], v[198:201], v[86:89]
	v_mfma_f32_16x16x32_bf16 v[82:85], v[164:167], v[198:201], v[82:85]
	v_mfma_f32_16x16x32_bf16 v[70:73], v[146:149], v[206:209], v[70:73]
	v_mfma_f32_16x16x32_bf16 v[66:69], v[164:167], v[206:209], v[66:69]
	v_mfma_f32_16x16x32_bf16 v[130:133], v[150:153], v[176:179], v[130:133]
	v_mfma_f32_16x16x32_bf16 v[122:125], v[168:171], v[176:179], v[122:125]
	v_mfma_f32_16x16x32_bf16 v[102:105], v[150:153], v[188:191], v[102:105]
	v_mfma_f32_16x16x32_bf16 v[98:101], v[168:171], v[188:191], v[98:101]
	v_mfma_f32_16x16x32_bf16 v[86:89], v[150:153], v[202:205], v[86:89]
	v_mfma_f32_16x16x32_bf16 v[82:85], v[168:171], v[202:205], v[82:85]
	v_mfma_f32_16x16x32_bf16 v[70:73], v[150:153], v[222:225], v[70:73]
	v_mfma_f32_16x16x32_bf16 v[66:69], v[168:171], v[222:225], v[66:69]
	s_setprio 0
	s_barrier
	s_add_i32 s30, s62, s33
	v_lshl_add_u64 v[210:211], s[46:47], 0, v[0:1]
	s_mov_b32 m0, s30
	ds_read_b128 v[172:175], v187 offset:16384
	ds_read_b128 v[176:179], v187 offset:17408
	ds_read_b128 v[180:183], v187 offset:18432
	ds_read_b128 v[188:191], v187 offset:19456
	ds_read_b128 v[198:201], v187 offset:20480
	ds_read_b128 v[202:205], v187 offset:21504
	ds_read_b128 v[206:209], v187 offset:22528
	ds_read_b128 v[222:225], v187 offset:23552
	global_load_lds_dwordx4 v[210:211], off
	s_add_i32 m0, s30, 0x2000
	s_add_u32 s30, s46, 0x40000
	v_lshl_add_u64 v[226:227], s[46:47], 0, v[154:155]
	s_addc_u32 s31, s47, 0
	s_add_i32 s62, s63, s33
	global_load_lds_dwordx4 v[226:227], off
	v_lshl_add_u64 v[228:229], s[30:31], 0, v[0:1]
	s_mov_b32 m0, s62
	v_lshl_add_u64 v[230:231], s[48:49], 0, v[156:157]
	global_load_lds_dwordx4 v[228:229], off
	v_lshl_add_u64 v[228:229], s[30:31], 0, v[154:155]
	s_add_i32 m0, s62, 0x2000
	s_nop 0
	global_load_lds_dwordx4 v[228:229], off
	v_lshl_add_u64 v[228:229], s[48:49], 0, v[158:159]
	s_mov_b32 m0, s50
	s_nop 0
	global_load_lds_dwordx4 v[228:229], off
	s_mov_b32 m0, s51
	s_nop 0
	global_load_lds_dwordx4 v[230:231], off
	s_waitcnt vmcnt(8)
	s_waitcnt lgkmcnt(0)
	s_barrier
; #define PG8_STAGE(bufoff, gbase, voff) do { _Pragma("unroll") for (int _i = 0; _i < 2; ++_i) \
;         __builtin_amdgcn_global_load_lds((const unsigned*)((const char*)(gbase) + (voff)[_i]), (PG8_LAS unsigned*)(lds + (bufoff) + ldsw + _i * 8192), 16, 0, 0); } while (0)
; #define PG8_LDA(dst, b, h) do { _Pragma("unroll") for (int m = 0; m < 4; ++m) _Pragma("unroll") for (int k = 0; k < 2; ++k) dst[m][k] = *(const PG8_LAS bf16x8*)(lds + PG8_SA(b, h) + aoff + m * 2048 + k * 1024); } while (0)
; #define PG8_LDB(dst, b, h) do { _Pragma("unroll") for (int n = 0; n < 2; ++n) _Pragma("unroll") for (int k = 0; k < 2; ++k) dst[n][k] = *(const PG8_LAS bf16x8*)(lds + PG8_SB(b, h) + boff + n * 2048 + k * 1024); } while (0)
; #define PG8_MMA(ai, bj, At, Bt) do { __builtin_amdgcn_s_setprio(1); _Pragma("unroll") for (int m = 0; m < 4; ++m) _Pragma("unroll") for (int n = 0; n < 2; ++n) _Pragma("unroll") for (int k = 0; k < 2; ++k) \
;         acc[ai][bj][m][n] = __builtin_amdgcn_mfma_f32_16x16x32_bf16(Bt[n][k], At[m][k], acc[ai][bj][m][n], 0, 0, 0); __builtin_amdgcn_s_setprio(0); } while (0)
; #define PG8_WAIT_V(n) asm volatile("s_waitcnt vmcnt(" #n ")" ::: "memory")
; #define PG8_WAIT_L(n) asm volatile("s_waitcnt lgkmcnt(" #n ")" ::: "memory")
; #define PG8_BAR __builtin_amdgcn_s_barrier()
; #define PG8_SCHED __builtin_amdgcn_sched_barrier(0)
; template <class Epi, class Sched, bool ALIGN_EPI = false, bool SP2 = false>
; __device__ __forceinline__ void gemm_phase(PG8_LAS unsigned char* lds, const Gemm g, const Sched& S, const Epi& E) {
;     ...
;             PG8_WAIT_V(8); PG8_WAIT_L(0); PG8_BAR; PG8_MMA(1, 0, At, B0); PG8_MMA(1, 1, At, B1); PG8_BAR; PG8_SCHED;
;             PG8_LDB(B0, 1, 0); PG8_LDB(B1, 1, 1); PG8_SCHED; PG8_LDA(At, 1, 0); PG8_STAGE(PG8_SA(0, 1), a2 + hstep, voffA);
;             PG8_WAIT_V(8); PG8_WAIT_L(0); PG8_BAR; PG8_MMA(0, 0, At, B0); PG8_MMA(0, 1, At, B1); PG8_BAR; PG8_SCHED;
	s_setprio 1
	s_waitcnt lgkmcnt(0)
	v_mfma_f32_16x16x32_bf16 v[62:65], v[114:117], v[172:175], v[62:65]
	v_mfma_f32_16x16x32_bf16 v[58:61], v[126:129], v[172:175], v[58:61]
	v_mfma_f32_16x16x32_bf16 v[46:49], v[114:117], v[180:183], v[46:49]
	v_mfma_f32_16x16x32_bf16 v[42:45], v[126:129], v[180:183], v[42:45]
	v_mfma_f32_16x16x32_bf16 v[30:33], v[114:117], v[198:201], v[30:33]
	v_mfma_f32_16x16x32_bf16 v[26:29], v[126:129], v[198:201], v[26:29]
	v_mfma_f32_16x16x32_bf16 v[14:17], v[114:117], v[206:209], v[14:17]
	v_mfma_f32_16x16x32_bf16 v[10:13], v[126:129], v[206:209], v[10:13]
	v_mfma_f32_16x16x32_bf16 v[62:65], v[118:121], v[176:179], v[62:65]
	v_mfma_f32_16x16x32_bf16 v[58:61], v[134:137], v[176:179], v[58:61]
	v_mfma_f32_16x16x32_bf16 v[46:49], v[118:121], v[188:191], v[46:49]
	v_mfma_f32_16x16x32_bf16 v[42:45], v[134:137], v[188:191], v[42:45]
	v_mfma_f32_16x16x32_bf16 v[30:33], v[118:121], v[202:205], v[30:33]
	v_mfma_f32_16x16x32_bf16 v[26:29], v[134:137], v[202:205], v[26:29]
	v_mfma_f32_16x16x32_bf16 v[14:17], v[118:121], v[222:225], v[14:17]
	v_mfma_f32_16x16x32_bf16 v[10:13], v[134:137], v[222:225], v[10:13]
	s_setprio 0
	s_setprio 1
	v_mfma_f32_16x16x32_bf16 v[54:57], v[146:149], v[172:175], v[54:57]
	v_mfma_f32_16x16x32_bf16 v[50:53], v[164:167], v[172:175], v[50:53]
	v_mfma_f32_16x16x32_bf16 v[38:41], v[146:149], v[180:183], v[38:41]
	v_mfma_f32_16x16x32_bf16 v[34:37], v[164:167], v[180:183], v[34:37]
	v_mfma_f32_16x16x32_bf16 v[22:25], v[146:149], v[198:201], v[22:25]
	v_mfma_f32_16x16x32_bf16 v[18:21], v[164:167], v[198:201], v[18:21]
	v_mfma_f32_16x16x32_bf16 v[6:9], v[146:149], v[206:209], v[6:9]
	v_mfma_f32_16x16x32_bf16 v[2:5], v[164:167], v[206:209], v[2:5]
	v_mfma_f32_16x16x32_bf16 v[54:57], v[150:153], v[176:179], v[54:57]
	v_mfma_f32_16x16x32_bf16 v[50:53], v[168:171], v[176:179], v[50:53]
	v_mfma_f32_16x16x32_bf16 v[38:41], v[150:153], v[188:191], v[38:41]
	v_mfma_f32_16x16x32_bf16 v[34:37], v[168:171], v[188:191], v[34:37]
	v_mfma_f32_16x16x32_bf16 v[22:25], v[150:153], v[202:205], v[22:25]
	v_mfma_f32_16x16x32_bf16 v[18:21], v[168:171], v[202:205], v[18:21]
	v_mfma_f32_16x16x32_bf16 v[6:9], v[150:153], v[222:225], v[6:9]
	v_mfma_f32_16x16x32_bf16 v[2:5], v[168:171], v[222:225], v[2:5]
	s_setprio 0
	s_barrier
	s_add_i32 s62, 0, 0x18000
	s_add_i32 s63, 0, 0x1c000
	v_add_u32_e32 v134, s62, v185
	v_add_u32_e32 v168, s63, v185
	ds_read_b128 v[114:117], v134
	ds_read_b128 v[118:121], v134 offset:1024
	ds_read_b128 v[126:129], v134 offset:2048
	ds_read_b128 v[134:137], v134 offset:3072
	ds_read_b128 v[146:149], v168
	ds_read_b128 v[150:153], v168 offset:1024
	ds_read_b128 v[164:167], v168 offset:2048
	ds_read_b128 v[168:171], v168 offset:3072
	s_add_u32 s30, s48, 0x40000
	s_addc_u32 s31, s49, 0
	s_mov_b32 m0, s52
	v_lshl_add_u64 v[232:233], s[30:31], 0, v[158:159]
	ds_read_b128 v[172:175], v187 offset:32768
	ds_read_b128 v[176:179], v187 offset:33792
	ds_read_b128 v[180:183], v187 offset:34816
	ds_read_b128 v[188:191], v187 offset:35840
	ds_read_b128 v[198:201], v187 offset:36864
	ds_read_b128 v[202:205], v187 offset:37888
	ds_read_b128 v[206:209], v187 offset:38912
	ds_read_b128 v[222:225], v187 offset:39936
	global_load_lds_dwordx4 v[232:233], off
	v_lshl_add_u64 v[232:233], s[30:31], 0, v[156:157]
	s_mov_b32 m0, s53
	s_nop 0
	global_load_lds_dwordx4 v[232:233], off
	s_waitcnt vmcnt(8)
	s_waitcnt lgkmcnt(0)
	s_barrier
	s_setprio 1
	s_waitcnt lgkmcnt(0)
	v_mfma_f32_16x16x32_bf16 v[142:145], v[114:117], v[172:175], v[142:145]
	v_mfma_f32_16x16x32_bf16 v[138:141], v[126:129], v[172:175], v[138:141]
	v_mfma_f32_16x16x32_bf16 v[110:113], v[114:117], v[180:183], v[110:113]
	v_mfma_f32_16x16x32_bf16 v[106:109], v[126:129], v[180:183], v[106:109]
	v_mfma_f32_16x16x32_bf16 v[94:97], v[114:117], v[198:201], v[94:97]
	v_mfma_f32_16x16x32_bf16 v[90:93], v[126:129], v[198:201], v[90:93]
	v_mfma_f32_16x16x32_bf16 v[78:81], v[114:117], v[206:209], v[78:81]
	v_mfma_f32_16x16x32_bf16 v[74:77], v[126:129], v[206:209], v[74:77]
	v_mfma_f32_16x16x32_bf16 v[142:145], v[118:121], v[176:179], v[142:145]
	v_mfma_f32_16x16x32_bf16 v[138:141], v[134:137], v[176:179], v[138:141]
	v_mfma_f32_16x16x32_bf16 v[110:113], v[118:121], v[188:191], v[110:113]
	v_mfma_f32_16x16x32_bf16 v[106:109], v[134:137], v[188:191], v[106:109]
	v_mfma_f32_16x16x32_bf16 v[94:97], v[118:121], v[202:205], v[94:97]
	v_mfma_f32_16x16x32_bf16 v[90:93], v[134:137], v[202:205], v[90:93]
	v_mfma_f32_16x16x32_bf16 v[78:81], v[118:121], v[222:225], v[78:81]
	v_mfma_f32_16x16x32_bf16 v[74:77], v[134:137], v[222:225], v[74:77]
	s_setprio 0
	s_setprio 1
	v_mfma_f32_16x16x32_bf16 v[130:133], v[146:149], v[172:175], v[130:133]
	v_mfma_f32_16x16x32_bf16 v[122:125], v[164:167], v[172:175], v[122:125]
	v_mfma_f32_16x16x32_bf16 v[102:105], v[146:149], v[180:183], v[102:105]
	v_mfma_f32_16x16x32_bf16 v[98:101], v[164:167], v[180:183], v[98:101]
	v_mfma_f32_16x16x32_bf16 v[86:89], v[146:149], v[198:201], v[86:89]
	v_mfma_f32_16x16x32_bf16 v[82:85], v[164:167], v[198:201], v[82:85]
	v_mfma_f32_16x16x32_bf16 v[70:73], v[146:149], v[206:209], v[70:73]
	v_mfma_f32_16x16x32_bf16 v[66:69], v[164:167], v[206:209], v[66:69]
	v_mfma_f32_16x16x32_bf16 v[130:133], v[150:153], v[176:179], v[130:133]
	v_mfma_f32_16x16x32_bf16 v[122:125], v[168:171], v[176:179], v[122:125]
	v_mfma_f32_16x16x32_bf16 v[102:105], v[150:153], v[188:191], v[102:105]
	v_mfma_f32_16x16x32_bf16 v[98:101], v[168:171], v[188:191], v[98:101]
	v_mfma_f32_16x16x32_bf16 v[86:89], v[150:153], v[202:205], v[86:89]
	v_mfma_f32_16x16x32_bf16 v[82:85], v[168:171], v[202:205], v[82:85]
	v_mfma_f32_16x16x32_bf16 v[70:73], v[150:153], v[222:225], v[70:73]
	v_mfma_f32_16x16x32_bf16 v[66:69], v[168:171], v[222:225], v[66:69]
	s_setprio 0
	s_barrier
; #define PG8_STAGE(bufoff, gbase, voff) do { _Pragma("unroll") for (int _i = 0; _i < 2; ++_i) \
;         __builtin_amdgcn_global_load_lds((const unsigned*)((const char*)(gbase) + (voff)[_i]), (PG8_LAS unsigned*)(lds + (bufoff) + ldsw + _i * 8192), 16, 0, 0); } while (0)
; #define PG8_LDA(dst, b, h) do { _Pragma("unroll") for (int m = 0; m < 4; ++m) _Pragma("unroll") for (int k = 0; k < 2; ++k) dst[m][k] = *(const PG8_LAS bf16x8*)(lds + PG8_SA(b, h) + aoff + m * 2048 + k * 1024); } while (0)
; #define PG8_MMA(ai, bj, At, Bt) do { __builtin_amdgcn_s_setprio(1); _Pragma("unroll") for (int m = 0; m < 4; ++m) _Pragma("unroll") for (int n = 0; n < 2; ++n) _Pragma("unroll") for (int k = 0; k < 2; ++k) \
;         acc[ai][bj][m][n] = __builtin_amdgcn_mfma_f32_16x16x32_bf16(Bt[n][k], At[m][k], acc[ai][bj][m][n], 0, 0, 0); __builtin_amdgcn_s_setprio(0); } while (0)
; #define PG8_WAIT_V(n) asm volatile("s_waitcnt vmcnt(" #n ")" ::: "memory")
; #define PG8_WAIT_L(n) asm volatile("s_waitcnt lgkmcnt(" #n ")" ::: "memory")
; #define PG8_BAR __builtin_amdgcn_s_barrier()
; #define PG8_SCHED __builtin_amdgcn_sched_barrier(0)
; template <class Epi, class Sched, bool ALIGN_EPI = false, bool SP2 = false>
; __device__ __forceinline__ void gemm_phase(PG8_LAS unsigned char* lds, const Gemm g, const Sched& S, const Epi& E) {
;     ...
;         for (int t = 0; t < nt; t += 2) {
;             const bool last = (t == nt - 2);
;             const char* a1 = cA + (size_t)(t + 1) * kstep;
;             const char* a2 = last ? nA : cA + (size_t)(t + 2) * kstep; const char* b2 = last ? nB : cB + (size_t)(t + 2) * kstep;
;             const char* a3 = a2 + kstep; const char* b3 = b2 + kstep;
;     ...
;             PG8_LDA(At, 1, 1); PG8_STAGE(PG8_SB(1, 0), b3, voffB); PG8_STAGE(PG8_SB(1, 1), b3 + hstep, voffB); PG8_STAGE(PG8_SA(1, 0), a3, voffA);
;             PG8_WAIT_V(8); PG8_WAIT_L(0); PG8_BAR; PG8_MMA(1, 0, At, B0); PG8_MMA(1, 1, At, B1); PG8_BAR; PG8_SCHED;
	s_add_i32 s30, s62, s33
	v_lshl_add_u64 v[210:211], v[210:211], 0, s[0:1]
	s_mov_b32 m0, s30
	ds_read_b128 v[172:175], v187 offset:49152
	ds_read_b128 v[176:179], v187 offset:50176
	ds_read_b128 v[180:183], v187 offset:51200
	ds_read_b128 v[188:191], v187 offset:52224
	ds_read_b128 v[198:201], v187 offset:53248
	ds_read_b128 v[202:205], v187 offset:54272
	ds_read_b128 v[206:209], v187 offset:55296
	ds_read_b128 v[222:225], v187 offset:56320
	global_load_lds_dwordx4 v[210:211], off
	s_add_i32 m0, s30, 0x2000
	s_add_u32 s30, s46, 0x40080
	v_lshl_add_u64 v[210:211], v[226:227], 0, s[0:1]
	s_addc_u32 s31, s47, 0
	s_add_i32 s46, s63, s33
	global_load_lds_dwordx4 v[210:211], off
	v_lshl_add_u64 v[210:211], s[30:31], 0, v[0:1]
	s_mov_b32 m0, s46
	s_nop 0
	global_load_lds_dwordx4 v[210:211], off
	v_lshl_add_u64 v[210:211], s[30:31], 0, v[154:155]
	s_add_i32 m0, s46, 0x2000
	s_nop 0
	global_load_lds_dwordx4 v[210:211], off
	v_lshl_add_u64 v[210:211], v[228:229], 0, s[0:1]
	s_mov_b32 m0, s56
	s_nop 0
	global_load_lds_dwordx4 v[210:211], off
	v_lshl_add_u64 v[210:211], v[230:231], 0, s[0:1]
	s_mov_b32 m0, s57
	s_nop 0
	global_load_lds_dwordx4 v[210:211], off
	s_waitcnt vmcnt(8)
	s_waitcnt lgkmcnt(0)
	s_barrier
	s_setprio 1
	s_waitcnt lgkmcnt(0)
	v_mfma_f32_16x16x32_bf16 v[62:65], v[114:117], v[172:175], v[62:65]
	v_mfma_f32_16x16x32_bf16 v[58:61], v[126:129], v[172:175], v[58:61]
	v_mfma_f32_16x16x32_bf16 v[46:49], v[114:117], v[180:183], v[46:49]
	v_mfma_f32_16x16x32_bf16 v[42:45], v[126:129], v[180:183], v[42:45]
	v_mfma_f32_16x16x32_bf16 v[30:33], v[114:117], v[198:201], v[30:33]
	v_mfma_f32_16x16x32_bf16 v[26:29], v[126:129], v[198:201], v[26:29]
	v_mfma_f32_16x16x32_bf16 v[14:17], v[114:117], v[206:209], v[14:17]
	v_mfma_f32_16x16x32_bf16 v[10:13], v[126:129], v[206:209], v[10:13]
	v_mfma_f32_16x16x32_bf16 v[62:65], v[118:121], v[176:179], v[62:65]
	v_mfma_f32_16x16x32_bf16 v[58:61], v[134:137], v[176:179], v[58:61]
	v_mfma_f32_16x16x32_bf16 v[46:49], v[118:121], v[188:191], v[46:49]
	v_mfma_f32_16x16x32_bf16 v[42:45], v[134:137], v[188:191], v[42:45]
	v_mfma_f32_16x16x32_bf16 v[30:33], v[118:121], v[202:205], v[30:33]
	v_mfma_f32_16x16x32_bf16 v[26:29], v[134:137], v[202:205], v[26:29]
	v_mfma_f32_16x16x32_bf16 v[14:17], v[118:121], v[222:225], v[14:17]
	v_mfma_f32_16x16x32_bf16 v[10:13], v[134:137], v[222:225], v[10:13]
	s_setprio 0
	s_setprio 1
	v_mfma_f32_16x16x32_bf16 v[54:57], v[146:149], v[172:175], v[54:57]
	v_mfma_f32_16x16x32_bf16 v[50:53], v[164:167], v[172:175], v[50:53]
	v_mfma_f32_16x16x32_bf16 v[38:41], v[146:149], v[180:183], v[38:41]
	v_mfma_f32_16x16x32_bf16 v[34:37], v[164:167], v[180:183], v[34:37]
	v_mfma_f32_16x16x32_bf16 v[22:25], v[146:149], v[198:201], v[22:25]
	v_mfma_f32_16x16x32_bf16 v[18:21], v[164:167], v[198:201], v[18:21]
	v_mfma_f32_16x16x32_bf16 v[6:9], v[146:149], v[206:209], v[6:9]
	v_mfma_f32_16x16x32_bf16 v[2:5], v[164:167], v[206:209], v[2:5]
	v_mfma_f32_16x16x32_bf16 v[54:57], v[150:153], v[176:179], v[54:57]
	v_mfma_f32_16x16x32_bf16 v[50:53], v[168:171], v[176:179], v[50:53]
	v_mfma_f32_16x16x32_bf16 v[38:41], v[150:153], v[188:191], v[38:41]
	v_mfma_f32_16x16x32_bf16 v[34:37], v[168:171], v[188:191], v[34:37]
	v_mfma_f32_16x16x32_bf16 v[22:25], v[150:153], v[202:205], v[22:25]
	v_mfma_f32_16x16x32_bf16 v[18:21], v[168:171], v[202:205], v[18:21]
	v_mfma_f32_16x16x32_bf16 v[6:9], v[150:153], v[222:225], v[6:9]
	v_mfma_f32_16x16x32_bf16 v[2:5], v[168:171], v[222:225], v[2:5]
	s_setprio 0
	s_add_i32 s61, s61, 2
	s_add_u32 s44, s44, 0x100
	s_addc_u32 s45, s45, 0
	s_add_u32 s59, s59, 0x100
	s_addc_u32 s60, s60, 0
	s_cmp_gt_u32 s61, 13
	s_cbranch_scc1 .Lrot_exit_p3
	s_add_u32 s30, s44, 0xfffc0080
	s_addc_u32 s31, s45, -1
	s_add_i32 s62, 0, 0x10000
	s_cmp_eq_u32 s61, 12
	s_cselect_b32 s49, s15, s31
	s_cselect_b32 s48, s34, s30
	s_cselect_b32 s47, s11, s60
	s_cselect_b32 s46, s35, s59
	s_add_i32 s63, 0, 0x14000
	v_add_u32_e32 v134, s62, v185
	v_add_u32_e32 v168, s63, v185
	s_barrier
	s_branch .LBB0_676

; #define PG8_STAGE(bufoff, gbase, voff) do { _Pragma("unroll") for (int _i = 0; _i < 2; ++_i) \
;         __builtin_amdgcn_global_load_lds((const unsigned*)((const char*)(gbase) + (voff)[_i]), (PG8_LAS unsigned*)(lds + (bufoff) + ldsw + _i * 8192), 16, 0, 0); } while (0)
; #define PG8_LDA(dst, b, h) do { _Pragma("unroll") for (int m = 0; m < 4; ++m) _Pragma("unroll") for (int k = 0; k < 2; ++k) dst[m][k] = *(const PG8_LAS bf16x8*)(lds + PG8_SA(b, h) + aoff + m * 2048 + k * 1024); } while (0)
; #define PG8_LDB(dst, b, h) do { _Pragma("unroll") for (int n = 0; n < 2; ++n) _Pragma("unroll") for (int k = 0; k < 2; ++k) dst[n][k] = *(const PG8_LAS bf16x8*)(lds + PG8_SB(b, h) + boff + n * 2048 + k * 1024); } while (0)
; #define PG8_MMA(ai, bj, At, Bt) do { __builtin_amdgcn_s_setprio(1); _Pragma("unroll") for (int m = 0; m < 4; ++m) _Pragma("unroll") for (int n = 0; n < 2; ++n) _Pragma("unroll") for (int k = 0; k < 2; ++k) \
;         acc[ai][bj][m][n] = __builtin_amdgcn_mfma_f32_16x16x32_bf16(Bt[n][k], At[m][k], acc[ai][bj][m][n], 0, 0, 0); __builtin_amdgcn_s_setprio(0); } while (0)
; #define PG8_WAIT_V(n) asm volatile("s_waitcnt vmcnt(" #n ")" ::: "memory")
; #define PG8_WAIT_L(n) asm volatile("s_waitcnt lgkmcnt(" #n ")" ::: "memory")
; #define PG8_BAR __builtin_amdgcn_s_barrier()
; #define PG8_SCHED __builtin_amdgcn_sched_barrier(0)
; template <class Epi, class Sched, bool ALIGN_EPI = false, bool SP2 = false>
; __device__ __forceinline__ void gemm_phase(PG8_LAS unsigned char* lds, const Gemm g, const Sched& S, const Epi& E) {
;     ...
;         for (int t = 0; t < nt; t += 2) {
;             const bool last = (t == nt - 2);
;             const char* a1 = cA + (size_t)(t + 1) * kstep;
;             const char* a2 = last ? nA : cA + (size_t)(t + 2) * kstep; const char* b2 = last ? nB : cB + (size_t)(t + 2) * kstep;
;             const char* a3 = a2 + kstep; const char* b3 = b2 + kstep;
;             if (last && has_next) S.a_ready(nxt);
;             if constexpr (SP2) {
;             PG8_LDB(B0, 0, 0); PG8_LDB(B1, 0, 1); PG8_SCHED; PG8_LDA(At, 0, 0); PG8_STAGE(PG8_SA(1, 1), a1 + hstep, voffA);
;             PG8_WAIT_V(8); PG8_WAIT_L(0); PG8_BAR; PG8_MMA(0, 0, At, B0); PG8_MMA(0, 1, At, B1); PG8_BAR; PG8_SCHED;
;             PG8_LDA(At, 0, 1); PG8_STAGE(PG8_SB(0, 0), b2, voffB); PG8_STAGE(PG8_SB(0, 1), b2 + hstep, voffB); PG8_STAGE(PG8_SA(0, 0), a2, voffA);
.Lpeel_p4:
	s_add_u32 s30, s46, 0xfffc0080
	s_addc_u32 s31, s47, -1
	s_add_i32 s65, 0, 0x10000
	s_cmp_eq_u32 s64, 12
	s_cselect_b32 s51, s15, s31
	s_cselect_b32 s50, s60, s30
	v_add_u32_e32 v152, s65, v157
	s_cselect_b32 s49, s11, s63
	s_cselect_b32 s48, s61, s62
	s_add_i32 s66, 0, 0x14000
	ds_read_b128 v[50:53], v152
	ds_read_b128 v[54:57], v152 offset:1024
	ds_read_b128 v[162:165], v152 offset:2048
	ds_read_b128 v[166:169], v152 offset:3072
	v_add_u32_e32 v152, s66, v157
	ds_read_b128 v[170:173], v152
	ds_read_b128 v[174:177], v152 offset:1024
	ds_read_b128 v[178:181], v152 offset:2048
	ds_read_b128 v[182:185], v152 offset:3072
	v_lshl_add_u64 v[152:153], s[46:47], 0, v[148:149]
	s_add_i32 m0, s52, 0xc000
	ds_read_b128 v[186:189], v160
	ds_read_b128 v[198:201], v160 offset:1024
	ds_read_b128 v[202:205], v160 offset:2048
	ds_read_b128 v[206:209], v160 offset:3072
	ds_read_b128 v[222:225], v160 offset:4096
	ds_read_b128 v[226:229], v160 offset:5120
	ds_read_b128 v[230:233], v160 offset:6144
	ds_read_b128 v[234:237], v160 offset:7168
	global_load_lds_dwordx4 v[152:153], off
	v_lshl_add_u64 v[152:153], s[46:47], 0, v[150:151]
	s_add_i32 m0, s52, 0xe000
	s_nop 0
	global_load_lds_dwordx4 v[152:153], off
	s_waitcnt vmcnt(8)
	s_waitcnt lgkmcnt(0)
	s_barrier
	s_setprio 1
	s_waitcnt lgkmcnt(0)
	v_mfma_f32_16x16x32_bf16 v[134:137], v[50:53], v[186:189], 0
	v_mfma_f32_16x16x32_bf16 v[126:129], v[162:165], v[186:189], 0
	v_mfma_f32_16x16x32_bf16 v[118:121], v[50:53], v[202:205], 0
	v_mfma_f32_16x16x32_bf16 v[110:113], v[162:165], v[202:205], 0
	v_mfma_f32_16x16x32_bf16 v[102:105], v[50:53], v[222:225], 0
	v_mfma_f32_16x16x32_bf16 v[94:97], v[162:165], v[222:225], 0
	v_mfma_f32_16x16x32_bf16 v[86:89], v[50:53], v[230:233], 0
	v_mfma_f32_16x16x32_bf16 v[78:81], v[162:165], v[230:233], 0
	v_mfma_f32_16x16x32_bf16 v[134:137], v[54:57], v[198:201], v[134:137]
	v_mfma_f32_16x16x32_bf16 v[126:129], v[166:169], v[198:201], v[126:129]
	v_mfma_f32_16x16x32_bf16 v[118:121], v[54:57], v[206:209], v[118:121]
	v_mfma_f32_16x16x32_bf16 v[110:113], v[166:169], v[206:209], v[110:113]
	v_mfma_f32_16x16x32_bf16 v[102:105], v[54:57], v[226:229], v[102:105]
	v_mfma_f32_16x16x32_bf16 v[94:97], v[166:169], v[226:229], v[94:97]
	v_mfma_f32_16x16x32_bf16 v[86:89], v[54:57], v[234:237], v[86:89]
	v_mfma_f32_16x16x32_bf16 v[78:81], v[166:169], v[234:237], v[78:81]
	s_setprio 0
	s_setprio 1
	v_mfma_f32_16x16x32_bf16 v[130:133], v[170:173], v[186:189], 0
	v_mfma_f32_16x16x32_bf16 v[122:125], v[178:181], v[186:189], 0
	v_mfma_f32_16x16x32_bf16 v[114:117], v[170:173], v[202:205], 0
	v_mfma_f32_16x16x32_bf16 v[106:109], v[178:181], v[202:205], 0
	v_mfma_f32_16x16x32_bf16 v[98:101], v[170:173], v[222:225], 0
	v_mfma_f32_16x16x32_bf16 v[90:93], v[178:181], v[222:225], 0
	v_mfma_f32_16x16x32_bf16 v[82:85], v[170:173], v[230:233], 0
	v_mfma_f32_16x16x32_bf16 v[74:77], v[178:181], v[230:233], 0
	v_mfma_f32_16x16x32_bf16 v[130:133], v[174:177], v[198:201], v[130:133]
	v_mfma_f32_16x16x32_bf16 v[122:125], v[182:185], v[198:201], v[122:125]
	v_mfma_f32_16x16x32_bf16 v[114:117], v[174:177], v[206:209], v[114:117]
	v_mfma_f32_16x16x32_bf16 v[106:109], v[182:185], v[206:209], v[106:109]
	v_mfma_f32_16x16x32_bf16 v[98:101], v[174:177], v[226:229], v[98:101]
	v_mfma_f32_16x16x32_bf16 v[90:93], v[182:185], v[226:229], v[90:93]
	v_mfma_f32_16x16x32_bf16 v[82:85], v[174:177], v[234:237], v[82:85]
	v_mfma_f32_16x16x32_bf16 v[74:77], v[182:185], v[234:237], v[74:77]
	s_setprio 0
	s_barrier
	s_add_i32 s30, s65, s33
	v_lshl_add_u64 v[152:153], s[48:49], 0, v[140:141]
	s_mov_b32 m0, s30
	ds_read_b128 v[186:189], v160 offset:16384
	ds_read_b128 v[198:201], v160 offset:17408
	ds_read_b128 v[202:205], v160 offset:18432
	ds_read_b128 v[206:209], v160 offset:19456
	ds_read_b128 v[222:225], v160 offset:20480
	ds_read_b128 v[226:229], v160 offset:21504
	ds_read_b128 v[230:233], v160 offset:22528
	ds_read_b128 v[234:237], v160 offset:23552
	global_load_lds_dwordx4 v[152:153], off
	s_add_i32 m0, s30, 0x2000
	s_add_u32 s30, s48, 0x40000
	v_lshl_add_u64 v[190:191], s[48:49], 0, v[144:145]
	s_addc_u32 s31, s49, 0
	s_add_i32 s65, s66, s33
	global_load_lds_dwordx4 v[190:191], off
	v_lshl_add_u64 v[210:211], s[30:31], 0, v[140:141]
	s_mov_b32 m0, s65
	v_lshl_add_u64 v[238:239], s[50:51], 0, v[142:143]
	global_load_lds_dwordx4 v[210:211], off
	v_lshl_add_u64 v[210:211], s[30:31], 0, v[144:145]
	s_add_i32 m0, s65, 0x2000
	s_nop 0
	global_load_lds_dwordx4 v[210:211], off
	v_lshl_add_u64 v[210:211], s[50:51], 0, v[138:139]
	s_mov_b32 m0, s52
	s_nop 0
	global_load_lds_dwordx4 v[210:211], off
	s_mov_b32 m0, s53
	s_nop 0
	global_load_lds_dwordx4 v[238:239], off
	s_waitcnt vmcnt(8)
	s_waitcnt lgkmcnt(0)
	s_barrier
; #define PG8_STAGE(bufoff, gbase, voff) do { _Pragma("unroll") for (int _i = 0; _i < 2; ++_i) \
;         __builtin_amdgcn_global_load_lds((const unsigned*)((const char*)(gbase) + (voff)[_i]), (PG8_LAS unsigned*)(lds + (bufoff) + ldsw + _i * 8192), 16, 0, 0); } while (0)
; #define PG8_LDA(dst, b, h) do { _Pragma("unroll") for (int m = 0; m < 4; ++m) _Pragma("unroll") for (int k = 0; k < 2; ++k) dst[m][k] = *(const PG8_LAS bf16x8*)(lds + PG8_SA(b, h) + aoff + m * 2048 + k * 1024); } while (0)
; #define PG8_LDB(dst, b, h) do { _Pragma("unroll") for (int n = 0; n < 2; ++n) _Pragma("unroll") for (int k = 0; k < 2; ++k) dst[n][k] = *(const PG8_LAS bf16x8*)(lds + PG8_SB(b, h) + boff + n * 2048 + k * 1024); } while (0)
; #define PG8_MMA(ai, bj, At, Bt) do { __builtin_amdgcn_s_setprio(1); _Pragma("unroll") for (int m = 0; m < 4; ++m) _Pragma("unroll") for (int n = 0; n < 2; ++n) _Pragma("unroll") for (int k = 0; k < 2; ++k) \
;         acc[ai][bj][m][n] = __builtin_amdgcn_mfma_f32_16x16x32_bf16(Bt[n][k], At[m][k], acc[ai][bj][m][n], 0, 0, 0); __builtin_amdgcn_s_setprio(0); } while (0)
; #define PG8_WAIT_V(n) asm volatile("s_waitcnt vmcnt(" #n ")" ::: "memory")
; #define PG8_WAIT_L(n) asm volatile("s_waitcnt lgkmcnt(" #n ")" ::: "memory")
; #define PG8_BAR __builtin_amdgcn_s_barrier()
; #define PG8_SCHED __builtin_amdgcn_sched_barrier(0)
; template <class Epi, class Sched, bool ALIGN_EPI = false, bool SP2 = false>
; __device__ __forceinline__ void gemm_phase(PG8_LAS unsigned char* lds, const Gemm g, const Sched& S, const Epi& E) {
;     ...
;             PG8_WAIT_V(8); PG8_WAIT_L(0); PG8_BAR; PG8_MMA(1, 0, At, B0); PG8_MMA(1, 1, At, B1); PG8_BAR; PG8_SCHED;
;             PG8_LDB(B0, 1, 0); PG8_LDB(B1, 1, 1); PG8_SCHED; PG8_LDA(At, 1, 0); PG8_STAGE(PG8_SA(0, 1), a2 + hstep, voffA);
;             PG8_WAIT_V(8); PG8_WAIT_L(0); PG8_BAR; PG8_MMA(0, 0, At, B0); PG8_MMA(0, 1, At, B1); PG8_BAR; PG8_SCHED;
	s_setprio 1
	s_waitcnt lgkmcnt(0)
	v_mfma_f32_16x16x32_bf16 v[70:73], v[50:53], v[186:189], 0
	v_mfma_f32_16x16x32_bf16 v[62:65], v[162:165], v[186:189], 0
	v_mfma_f32_16x16x32_bf16 v[46:49], v[50:53], v[202:205], 0
	v_mfma_f32_16x16x32_bf16 v[38:41], v[162:165], v[202:205], 0
	v_mfma_f32_16x16x32_bf16 v[30:33], v[50:53], v[222:225], 0
	v_mfma_f32_16x16x32_bf16 v[22:25], v[162:165], v[222:225], 0
	v_mfma_f32_16x16x32_bf16 v[14:17], v[50:53], v[230:233], 0
	v_mfma_f32_16x16x32_bf16 v[6:9], v[162:165], v[230:233], 0
	v_mfma_f32_16x16x32_bf16 v[70:73], v[54:57], v[198:201], v[70:73]
	v_mfma_f32_16x16x32_bf16 v[62:65], v[166:169], v[198:201], v[62:65]
	v_mfma_f32_16x16x32_bf16 v[46:49], v[54:57], v[206:209], v[46:49]
	v_mfma_f32_16x16x32_bf16 v[38:41], v[166:169], v[206:209], v[38:41]
	v_mfma_f32_16x16x32_bf16 v[30:33], v[54:57], v[226:229], v[30:33]
	v_mfma_f32_16x16x32_bf16 v[22:25], v[166:169], v[226:229], v[22:25]
	v_mfma_f32_16x16x32_bf16 v[14:17], v[54:57], v[234:237], v[14:17]
	v_mfma_f32_16x16x32_bf16 v[6:9], v[166:169], v[234:237], v[6:9]
	s_setprio 0
	s_setprio 1
	v_mfma_f32_16x16x32_bf16 v[42:45], v[170:173], v[202:205], 0
	v_mfma_f32_16x16x32_bf16 v[34:37], v[178:181], v[202:205], 0
	v_mfma_f32_16x16x32_bf16 v[26:29], v[170:173], v[222:225], 0
	v_mfma_f32_16x16x32_bf16 v[18:21], v[178:181], v[222:225], 0
	v_mfma_f32_16x16x32_bf16 v[10:13], v[170:173], v[230:233], 0
	v_mfma_f32_16x16x32_bf16 v[2:5], v[178:181], v[230:233], 0
	v_mfma_f32_16x16x32_bf16 v[50:53], v[170:173], v[186:189], 0
	v_mfma_f32_16x16x32_bf16 v[54:57], v[178:181], v[186:189], 0
	v_mfma_f32_16x16x32_bf16 v[42:45], v[174:177], v[206:209], v[42:45]
	v_mfma_f32_16x16x32_bf16 v[34:37], v[182:185], v[206:209], v[34:37]
	v_mfma_f32_16x16x32_bf16 v[26:29], v[174:177], v[226:229], v[26:29]
	v_mfma_f32_16x16x32_bf16 v[18:21], v[182:185], v[226:229], v[18:21]
	v_mfma_f32_16x16x32_bf16 v[10:13], v[174:177], v[234:237], v[10:13]
	v_mfma_f32_16x16x32_bf16 v[2:5], v[182:185], v[234:237], v[2:5]
	v_mfma_f32_16x16x32_bf16 v[50:53], v[174:177], v[198:201], v[50:53]
	v_mfma_f32_16x16x32_bf16 v[54:57], v[182:185], v[198:201], v[54:57]
	s_setprio 0
	s_barrier
	s_add_i32 s65, 0, 0x18000
	v_add_u32_e32 v161, s65, v157
	s_add_i32 s66, 0, 0x1c000
	ds_read_b128 v[58:61], v161
	ds_read_b128 v[66:69], v161 offset:1024
	ds_read_b128 v[162:165], v161 offset:2048
	ds_read_b128 v[166:169], v161 offset:3072
	v_add_u32_e32 v161, s66, v157
	ds_read_b128 v[170:173], v161
	ds_read_b128 v[174:177], v161 offset:1024
	ds_read_b128 v[178:181], v161 offset:2048
	ds_read_b128 v[182:185], v161 offset:3072
	s_add_u32 s30, s50, 0x40000
	s_addc_u32 s31, s51, 0
	s_mov_b32 m0, s54
	v_lshl_add_u64 v[240:241], s[30:31], 0, v[138:139]
	ds_read_b128 v[186:189], v160 offset:32768
	ds_read_b128 v[198:201], v160 offset:33792
	ds_read_b128 v[202:205], v160 offset:34816
	ds_read_b128 v[206:209], v160 offset:35840
	ds_read_b128 v[222:225], v160 offset:36864
	ds_read_b128 v[226:229], v160 offset:37888
	ds_read_b128 v[230:233], v160 offset:38912
	ds_read_b128 v[234:237], v160 offset:39936
	global_load_lds_dwordx4 v[240:241], off
	v_lshl_add_u64 v[240:241], s[30:31], 0, v[142:143]
	s_mov_b32 m0, s55
	s_nop 0
	global_load_lds_dwordx4 v[240:241], off
	s_waitcnt vmcnt(8)
	s_waitcnt lgkmcnt(0)
	s_barrier
	s_setprio 1
	s_waitcnt lgkmcnt(0)
	v_mfma_f32_16x16x32_bf16 v[134:137], v[58:61], v[186:189], v[134:137]
	v_mfma_f32_16x16x32_bf16 v[126:129], v[162:165], v[186:189], v[126:129]
	v_mfma_f32_16x16x32_bf16 v[118:121], v[58:61], v[202:205], v[118:121]
	v_mfma_f32_16x16x32_bf16 v[110:113], v[162:165], v[202:205], v[110:113]
	v_mfma_f32_16x16x32_bf16 v[102:105], v[58:61], v[222:225], v[102:105]
	v_mfma_f32_16x16x32_bf16 v[94:97], v[162:165], v[222:225], v[94:97]
	v_mfma_f32_16x16x32_bf16 v[86:89], v[58:61], v[230:233], v[86:89]
	v_mfma_f32_16x16x32_bf16 v[78:81], v[162:165], v[230:233], v[78:81]
	v_mfma_f32_16x16x32_bf16 v[134:137], v[66:69], v[198:201], v[134:137]
	v_mfma_f32_16x16x32_bf16 v[126:129], v[166:169], v[198:201], v[126:129]
	v_mfma_f32_16x16x32_bf16 v[118:121], v[66:69], v[206:209], v[118:121]
	v_mfma_f32_16x16x32_bf16 v[110:113], v[166:169], v[206:209], v[110:113]
	v_mfma_f32_16x16x32_bf16 v[102:105], v[66:69], v[226:229], v[102:105]
	v_mfma_f32_16x16x32_bf16 v[94:97], v[166:169], v[226:229], v[94:97]
	v_mfma_f32_16x16x32_bf16 v[86:89], v[66:69], v[234:237], v[86:89]
	v_mfma_f32_16x16x32_bf16 v[78:81], v[166:169], v[234:237], v[78:81]
	s_setprio 0
	s_setprio 1
	v_mfma_f32_16x16x32_bf16 v[130:133], v[170:173], v[186:189], v[130:133]
	v_mfma_f32_16x16x32_bf16 v[122:125], v[178:181], v[186:189], v[122:125]
	v_mfma_f32_16x16x32_bf16 v[114:117], v[170:173], v[202:205], v[114:117]
	v_mfma_f32_16x16x32_bf16 v[106:109], v[178:181], v[202:205], v[106:109]
	v_mfma_f32_16x16x32_bf16 v[98:101], v[170:173], v[222:225], v[98:101]
	v_mfma_f32_16x16x32_bf16 v[90:93], v[178:181], v[222:225], v[90:93]
	v_mfma_f32_16x16x32_bf16 v[82:85], v[170:173], v[230:233], v[82:85]
	v_mfma_f32_16x16x32_bf16 v[74:77], v[178:181], v[230:233], v[74:77]
	v_mfma_f32_16x16x32_bf16 v[130:133], v[174:177], v[198:201], v[130:133]
	v_mfma_f32_16x16x32_bf16 v[122:125], v[182:185], v[198:201], v[122:125]
	v_mfma_f32_16x16x32_bf16 v[114:117], v[174:177], v[206:209], v[114:117]
	v_mfma_f32_16x16x32_bf16 v[106:109], v[182:185], v[206:209], v[106:109]
	v_mfma_f32_16x16x32_bf16 v[98:101], v[174:177], v[226:229], v[98:101]
	v_mfma_f32_16x16x32_bf16 v[90:93], v[182:185], v[226:229], v[90:93]
	v_mfma_f32_16x16x32_bf16 v[82:85], v[174:177], v[234:237], v[82:85]
	v_mfma_f32_16x16x32_bf16 v[74:77], v[182:185], v[234:237], v[74:77]
	s_setprio 0
	s_barrier
; #define PG8_STAGE(bufoff, gbase, voff) do { _Pragma("unroll") for (int _i = 0; _i < 2; ++_i) \
;         __builtin_amdgcn_global_load_lds((const unsigned*)((const char*)(gbase) + (voff)[_i]), (PG8_LAS unsigned*)(lds + (bufoff) + ldsw + _i * 8192), 16, 0, 0); } while (0)
; #define PG8_LDA(dst, b, h) do { _Pragma("unroll") for (int m = 0; m < 4; ++m) _Pragma("unroll") for (int k = 0; k < 2; ++k) dst[m][k] = *(const PG8_LAS bf16x8*)(lds + PG8_SA(b, h) + aoff + m * 2048 + k * 1024); } while (0)
; #define PG8_MMA(ai, bj, At, Bt) do { __builtin_amdgcn_s_setprio(1); _Pragma("unroll") for (int m = 0; m < 4; ++m) _Pragma("unroll") for (int n = 0; n < 2; ++n) _Pragma("unroll") for (int k = 0; k < 2; ++k) \
;         acc[ai][bj][m][n] = __builtin_amdgcn_mfma_f32_16x16x32_bf16(Bt[n][k], At[m][k], acc[ai][bj][m][n], 0, 0, 0); __builtin_amdgcn_s_setprio(0); } while (0)
; #define PG8_WAIT_V(n) asm volatile("s_waitcnt vmcnt(" #n ")" ::: "memory")
; #define PG8_WAIT_L(n) asm volatile("s_waitcnt lgkmcnt(" #n ")" ::: "memory")
; #define PG8_BAR __builtin_amdgcn_s_barrier()
; #define PG8_SCHED __builtin_amdgcn_sched_barrier(0)
; template <class Epi, class Sched, bool ALIGN_EPI = false, bool SP2 = false>
; __device__ __forceinline__ void gemm_phase(PG8_LAS unsigned char* lds, const Gemm g, const Sched& S, const Epi& E) {
;     ...
;         for (int t = 0; t < nt; t += 2) {
;             const bool last = (t == nt - 2);
;             const char* a1 = cA + (size_t)(t + 1) * kstep;
;             const char* a2 = last ? nA : cA + (size_t)(t + 2) * kstep; const char* b2 = last ? nB : cB + (size_t)(t + 2) * kstep;
;             const char* a3 = a2 + kstep; const char* b3 = b2 + kstep;
;     ...
;             PG8_LDA(At, 1, 1); PG8_STAGE(PG8_SB(1, 0), b3, voffB); PG8_STAGE(PG8_SB(1, 1), b3 + hstep, voffB); PG8_STAGE(PG8_SA(1, 0), a3, voffA);
;             PG8_WAIT_V(8); PG8_WAIT_L(0); PG8_BAR; PG8_MMA(1, 0, At, B0); PG8_MMA(1, 1, At, B1); PG8_BAR; PG8_SCHED;
	s_add_i32 s30, s65, s33
	v_lshl_add_u64 v[152:153], v[152:153], 0, s[0:1]
	s_mov_b32 m0, s30
	ds_read_b128 v[186:189], v160 offset:49152
	ds_read_b128 v[198:201], v160 offset:50176
	ds_read_b128 v[202:205], v160 offset:51200
	ds_read_b128 v[206:209], v160 offset:52224
	ds_read_b128 v[222:225], v160 offset:53248
	ds_read_b128 v[226:229], v160 offset:54272
	ds_read_b128 v[230:233], v160 offset:55296
	ds_read_b128 v[234:237], v160 offset:56320
	global_load_lds_dwordx4 v[152:153], off
	s_add_i32 m0, s30, 0x2000
	s_add_u32 s30, s48, 0x40080
	v_lshl_add_u64 v[152:153], v[190:191], 0, s[0:1]
	s_addc_u32 s31, s49, 0
	s_add_i32 s48, s66, s33
	global_load_lds_dwordx4 v[152:153], off
	v_lshl_add_u64 v[152:153], s[30:31], 0, v[140:141]
	s_mov_b32 m0, s48
	s_nop 0
	global_load_lds_dwordx4 v[152:153], off
	v_lshl_add_u64 v[152:153], s[30:31], 0, v[144:145]
	s_add_i32 m0, s48, 0x2000
	s_nop 0
	global_load_lds_dwordx4 v[152:153], off
	v_lshl_add_u64 v[152:153], v[210:211], 0, s[0:1]
	s_mov_b32 m0, s56
	s_nop 0
	global_load_lds_dwordx4 v[152:153], off
	v_lshl_add_u64 v[152:153], v[238:239], 0, s[0:1]
	s_mov_b32 m0, s57
	s_nop 0
	global_load_lds_dwordx4 v[152:153], off
	s_waitcnt vmcnt(8)
	s_waitcnt lgkmcnt(0)
	s_barrier
	s_setprio 1
	s_waitcnt lgkmcnt(0)
	v_mfma_f32_16x16x32_bf16 v[70:73], v[58:61], v[186:189], v[70:73]
	v_mfma_f32_16x16x32_bf16 v[62:65], v[162:165], v[186:189], v[62:65]
	v_mfma_f32_16x16x32_bf16 v[46:49], v[58:61], v[202:205], v[46:49]
	v_mfma_f32_16x16x32_bf16 v[38:41], v[162:165], v[202:205], v[38:41]
	v_mfma_f32_16x16x32_bf16 v[30:33], v[58:61], v[222:225], v[30:33]
	v_mfma_f32_16x16x32_bf16 v[22:25], v[162:165], v[222:225], v[22:25]
	v_mfma_f32_16x16x32_bf16 v[14:17], v[58:61], v[230:233], v[14:17]
	v_mfma_f32_16x16x32_bf16 v[6:9], v[162:165], v[230:233], v[6:9]
	v_mfma_f32_16x16x32_bf16 v[70:73], v[66:69], v[198:201], v[70:73]
	v_mfma_f32_16x16x32_bf16 v[62:65], v[166:169], v[198:201], v[62:65]
	v_mfma_f32_16x16x32_bf16 v[46:49], v[66:69], v[206:209], v[46:49]
	v_mfma_f32_16x16x32_bf16 v[38:41], v[166:169], v[206:209], v[38:41]
	v_mfma_f32_16x16x32_bf16 v[30:33], v[66:69], v[226:229], v[30:33]
	v_mfma_f32_16x16x32_bf16 v[22:25], v[166:169], v[226:229], v[22:25]
	v_mfma_f32_16x16x32_bf16 v[14:17], v[66:69], v[234:237], v[14:17]
	v_mfma_f32_16x16x32_bf16 v[6:9], v[166:169], v[234:237], v[6:9]
	s_setprio 0
	s_setprio 1
	v_mfma_f32_16x16x32_bf16 v[50:53], v[170:173], v[186:189], v[50:53]
	v_mfma_f32_16x16x32_bf16 v[66:69], v[174:177], v[198:201], v[50:53]
	v_mfma_f32_16x16x32_bf16 v[50:53], v[178:181], v[186:189], v[54:57]
	v_mfma_f32_16x16x32_bf16 v[42:45], v[170:173], v[202:205], v[42:45]
	v_mfma_f32_16x16x32_bf16 v[34:37], v[178:181], v[202:205], v[34:37]
	v_mfma_f32_16x16x32_bf16 v[26:29], v[170:173], v[222:225], v[26:29]
	v_mfma_f32_16x16x32_bf16 v[18:21], v[178:181], v[222:225], v[18:21]
	v_mfma_f32_16x16x32_bf16 v[10:13], v[170:173], v[230:233], v[10:13]
	v_mfma_f32_16x16x32_bf16 v[2:5], v[178:181], v[230:233], v[2:5]
	v_mfma_f32_16x16x32_bf16 v[58:61], v[182:185], v[198:201], v[50:53]
	v_mfma_f32_16x16x32_bf16 v[42:45], v[174:177], v[206:209], v[42:45]
	v_mfma_f32_16x16x32_bf16 v[34:37], v[182:185], v[206:209], v[34:37]
	v_mfma_f32_16x16x32_bf16 v[26:29], v[174:177], v[226:229], v[26:29]
	v_mfma_f32_16x16x32_bf16 v[18:21], v[182:185], v[226:229], v[18:21]
	v_mfma_f32_16x16x32_bf16 v[10:13], v[174:177], v[234:237], v[10:13]
	v_mfma_f32_16x16x32_bf16 v[2:5], v[182:185], v[234:237], v[2:5]
	s_setprio 0
	s_add_i32 s64, s64, 2
	s_add_u32 s46, s46, 0x100
	s_addc_u32 s47, s47, 0
	s_add_u32 s62, s62, 0x100
	s_addc_u32 s63, s63, 0
	s_cmp_gt_u32 s64, 13
	s_cbranch_scc1 .Lrot_exit_peel_p4
	s_add_u32 s30, s46, 0xfffc0080
	s_addc_u32 s31, s47, -1
	s_add_i32 s65, 0, 0x10000
	s_cmp_eq_u32 s64, 12
	s_cselect_b32 s51, s15, s31
	s_cselect_b32 s50, s60, s30
	v_add_u32_e32 v152, s65, v157
	s_cselect_b32 s49, s11, s63
	s_cselect_b32 s48, s61, s62
	s_add_i32 s66, 0, 0x14000
	s_barrier
	s_branch .LBB0_781

; #define PG8_STAGE(bufoff, gbase, voff) do { _Pragma("unroll") for (int _i = 0; _i < 2; ++_i) \
;         __builtin_amdgcn_global_load_lds((const unsigned*)((const char*)(gbase) + (voff)[_i]), (PG8_LAS unsigned*)(lds + (bufoff) + ldsw + _i * 8192), 16, 0, 0); } while (0)
; #define PG8_LDA(dst, b, h) do { _Pragma("unroll") for (int m = 0; m < 4; ++m) _Pragma("unroll") for (int k = 0; k < 2; ++k) dst[m][k] = *(const PG8_LAS bf16x8*)(lds + PG8_SA(b, h) + aoff + m * 2048 + k * 1024); } while (0)
; #define PG8_LDB(dst, b, h) do { _Pragma("unroll") for (int n = 0; n < 2; ++n) _Pragma("unroll") for (int k = 0; k < 2; ++k) dst[n][k] = *(const PG8_LAS bf16x8*)(lds + PG8_SB(b, h) + boff + n * 2048 + k * 1024); } while (0)
; #define PG8_MMA(ai, bj, At, Bt) do { __builtin_amdgcn_s_setprio(1); _Pragma("unroll") for (int m = 0; m < 4; ++m) _Pragma("unroll") for (int n = 0; n < 2; ++n) _Pragma("unroll") for (int k = 0; k < 2; ++k) \
;         acc[ai][bj][m][n] = __builtin_amdgcn_mfma_f32_16x16x32_bf16(Bt[n][k], At[m][k], acc[ai][bj][m][n], 0, 0, 0); __builtin_amdgcn_s_setprio(0); } while (0)
; #define PG8_WAIT_V(n) asm volatile("s_waitcnt vmcnt(" #n ")" ::: "memory")
; #define PG8_WAIT_L(n) asm volatile("s_waitcnt lgkmcnt(" #n ")" ::: "memory")
; #define PG8_BAR __builtin_amdgcn_s_barrier()
; #define PG8_SCHED __builtin_amdgcn_sched_barrier(0)
; template <class Epi, class Sched, bool ALIGN_EPI = false, bool SP2 = false>
; __device__ __forceinline__ void gemm_phase(PG8_LAS unsigned char* lds, const Gemm g, const Sched& S, const Epi& E) {
;     ...
;             PG8_LDB(B0, 0, 0); PG8_LDB(B1, 0, 1); PG8_SCHED; PG8_LDA(At, 0, 0); PG8_STAGE(PG8_SA(1, 1), a1 + hstep, voffA);
;             PG8_WAIT_V(8); PG8_WAIT_L(0); PG8_BAR; PG8_MMA(0, 0, At, B0); PG8_MMA(0, 1, At, B1); PG8_BAR; PG8_SCHED;
;             PG8_LDA(At, 0, 1); PG8_STAGE(PG8_SB(0, 0), b2, voffB); PG8_STAGE(PG8_SB(0, 1), b2 + hstep, voffB); PG8_STAGE(PG8_SA(0, 0), a2, voffA);
.LBB0_781:
	ds_read_b128 v[50:53], v152
	ds_read_b128 v[54:57], v152 offset:1024
	ds_read_b128 v[162:165], v152 offset:2048
	ds_read_b128 v[166:169], v152 offset:3072
	v_add_u32_e32 v152, s66, v157
	ds_read_b128 v[170:173], v152
	ds_read_b128 v[174:177], v152 offset:1024
	ds_read_b128 v[178:181], v152 offset:2048
	ds_read_b128 v[182:185], v152 offset:3072
	v_lshl_add_u64 v[152:153], s[46:47], 0, v[148:149]
	s_add_i32 m0, s52, 0xc000
	ds_read_b128 v[186:189], v160
	ds_read_b128 v[198:201], v160 offset:1024
	ds_read_b128 v[202:205], v160 offset:2048
	ds_read_b128 v[206:209], v160 offset:3072
	ds_read_b128 v[222:225], v160 offset:4096
	ds_read_b128 v[226:229], v160 offset:5120
	ds_read_b128 v[230:233], v160 offset:6144
	ds_read_b128 v[234:237], v160 offset:7168
	global_load_lds_dwordx4 v[152:153], off
	v_lshl_add_u64 v[152:153], s[46:47], 0, v[150:151]
	s_add_i32 m0, s52, 0xe000
	s_nop 0
	global_load_lds_dwordx4 v[152:153], off
	s_waitcnt vmcnt(8)
	s_waitcnt lgkmcnt(0)
	s_barrier
	s_setprio 1
	s_waitcnt lgkmcnt(0)
	v_mfma_f32_16x16x32_bf16 v[134:137], v[50:53], v[186:189], v[134:137]
	v_mfma_f32_16x16x32_bf16 v[126:129], v[162:165], v[186:189], v[126:129]
	v_mfma_f32_16x16x32_bf16 v[118:121], v[50:53], v[202:205], v[118:121]
	v_mfma_f32_16x16x32_bf16 v[110:113], v[162:165], v[202:205], v[110:113]
	v_mfma_f32_16x16x32_bf16 v[102:105], v[50:53], v[222:225], v[102:105]
	v_mfma_f32_16x16x32_bf16 v[94:97], v[162:165], v[222:225], v[94:97]
	v_mfma_f32_16x16x32_bf16 v[86:89], v[50:53], v[230:233], v[86:89]
	v_mfma_f32_16x16x32_bf16 v[78:81], v[162:165], v[230:233], v[78:81]
	v_mfma_f32_16x16x32_bf16 v[134:137], v[54:57], v[198:201], v[134:137]
	v_mfma_f32_16x16x32_bf16 v[126:129], v[166:169], v[198:201], v[126:129]
	v_mfma_f32_16x16x32_bf16 v[118:121], v[54:57], v[206:209], v[118:121]
	v_mfma_f32_16x16x32_bf16 v[110:113], v[166:169], v[206:209], v[110:113]
	v_mfma_f32_16x16x32_bf16 v[102:105], v[54:57], v[226:229], v[102:105]
	v_mfma_f32_16x16x32_bf16 v[94:97], v[166:169], v[226:229], v[94:97]
	v_mfma_f32_16x16x32_bf16 v[86:89], v[54:57], v[234:237], v[86:89]
	v_mfma_f32_16x16x32_bf16 v[78:81], v[166:169], v[234:237], v[78:81]
	s_setprio 0
	s_setprio 1
	v_mfma_f32_16x16x32_bf16 v[130:133], v[170:173], v[186:189], v[130:133]
	v_mfma_f32_16x16x32_bf16 v[122:125], v[178:181], v[186:189], v[122:125]
	v_mfma_f32_16x16x32_bf16 v[114:117], v[170:173], v[202:205], v[114:117]
	v_mfma_f32_16x16x32_bf16 v[106:109], v[178:181], v[202:205], v[106:109]
	v_mfma_f32_16x16x32_bf16 v[98:101], v[170:173], v[222:225], v[98:101]
	v_mfma_f32_16x16x32_bf16 v[90:93], v[178:181], v[222:225], v[90:93]
	v_mfma_f32_16x16x32_bf16 v[82:85], v[170:173], v[230:233], v[82:85]
	v_mfma_f32_16x16x32_bf16 v[74:77], v[178:181], v[230:233], v[74:77]
	v_mfma_f32_16x16x32_bf16 v[130:133], v[174:177], v[198:201], v[130:133]
	v_mfma_f32_16x16x32_bf16 v[122:125], v[182:185], v[198:201], v[122:125]
	v_mfma_f32_16x16x32_bf16 v[114:117], v[174:177], v[206:209], v[114:117]
	v_mfma_f32_16x16x32_bf16 v[106:109], v[182:185], v[206:209], v[106:109]
	v_mfma_f32_16x16x32_bf16 v[98:101], v[174:177], v[226:229], v[98:101]
	v_mfma_f32_16x16x32_bf16 v[90:93], v[182:185], v[226:229], v[90:93]
	v_mfma_f32_16x16x32_bf16 v[82:85], v[174:177], v[234:237], v[82:85]
	v_mfma_f32_16x16x32_bf16 v[74:77], v[182:185], v[234:237], v[74:77]
	s_setprio 0
	s_barrier
	s_add_i32 s30, s65, s33
	v_lshl_add_u64 v[152:153], s[48:49], 0, v[140:141]
	s_mov_b32 m0, s30
	ds_read_b128 v[186:189], v160 offset:16384
	ds_read_b128 v[198:201], v160 offset:17408
	ds_read_b128 v[202:205], v160 offset:18432
	ds_read_b128 v[206:209], v160 offset:19456
	ds_read_b128 v[222:225], v160 offset:20480
	ds_read_b128 v[226:229], v160 offset:21504
	ds_read_b128 v[230:233], v160 offset:22528
	ds_read_b128 v[234:237], v160 offset:23552
	global_load_lds_dwordx4 v[152:153], off
	s_add_i32 m0, s30, 0x2000
	s_add_u32 s30, s48, 0x40000
	v_lshl_add_u64 v[190:191], s[48:49], 0, v[144:145]
	s_addc_u32 s31, s49, 0
	s_add_i32 s65, s66, s33
	global_load_lds_dwordx4 v[190:191], off
	v_lshl_add_u64 v[210:211], s[30:31], 0, v[140:141]
	s_mov_b32 m0, s65
	v_lshl_add_u64 v[238:239], s[50:51], 0, v[142:143]
	global_load_lds_dwordx4 v[210:211], off
	v_lshl_add_u64 v[210:211], s[30:31], 0, v[144:145]
	s_add_i32 m0, s65, 0x2000
	s_nop 0
	global_load_lds_dwordx4 v[210:211], off
	v_lshl_add_u64 v[210:211], s[50:51], 0, v[138:139]
	s_mov_b32 m0, s52
	s_nop 0
	global_load_lds_dwordx4 v[210:211], off
	s_mov_b32 m0, s53
	s_nop 0
	global_load_lds_dwordx4 v[238:239], off
	s_waitcnt vmcnt(8)
	s_waitcnt lgkmcnt(0)
	s_barrier
; #define PG8_STAGE(bufoff, gbase, voff) do { _Pragma("unroll") for (int _i = 0; _i < 2; ++_i) \
;         __builtin_amdgcn_global_load_lds((const unsigned*)((const char*)(gbase) + (voff)[_i]), (PG8_LAS unsigned*)(lds + (bufoff) + ldsw + _i * 8192), 16, 0, 0); } while (0)
; #define PG8_LDA(dst, b, h) do { _Pragma("unroll") for (int m = 0; m < 4; ++m) _Pragma("unroll") for (int k = 0; k < 2; ++k) dst[m][k] = *(const PG8_LAS bf16x8*)(lds + PG8_SA(b, h) + aoff + m * 2048 + k * 1024); } while (0)
; #define PG8_LDB(dst, b, h) do { _Pragma("unroll") for (int n = 0; n < 2; ++n) _Pragma("unroll") for (int k = 0; k < 2; ++k) dst[n][k] = *(const PG8_LAS bf16x8*)(lds + PG8_SB(b, h) + boff + n * 2048 + k * 1024); } while (0)
; #define PG8_MMA(ai, bj, At, Bt) do { __builtin_amdgcn_s_setprio(1); _Pragma("unroll") for (int m = 0; m < 4; ++m) _Pragma("unroll") for (int n = 0; n < 2; ++n) _Pragma("unroll") for (int k = 0; k < 2; ++k) \
;         acc[ai][bj][m][n] = __builtin_amdgcn_mfma_f32_16x16x32_bf16(Bt[n][k], At[m][k], acc[ai][bj][m][n], 0, 0, 0); __builtin_amdgcn_s_setprio(0); } while (0)
; #define PG8_WAIT_V(n) asm volatile("s_waitcnt vmcnt(" #n ")" ::: "memory")
; #define PG8_WAIT_L(n) asm volatile("s_waitcnt lgkmcnt(" #n ")" ::: "memory")
; #define PG8_BAR __builtin_amdgcn_s_barrier()
; #define PG8_SCHED __builtin_amdgcn_sched_barrier(0)
; template <class Epi, class Sched, bool ALIGN_EPI = false, bool SP2 = false>
; __device__ __forceinline__ void gemm_phase(PG8_LAS unsigned char* lds, const Gemm g, const Sched& S, const Epi& E) {
;     ...
;             PG8_WAIT_V(8); PG8_WAIT_L(0); PG8_BAR; PG8_MMA(1, 0, At, B0); PG8_MMA(1, 1, At, B1); PG8_BAR; PG8_SCHED;
;             PG8_LDB(B0, 1, 0); PG8_LDB(B1, 1, 1); PG8_SCHED; PG8_LDA(At, 1, 0); PG8_STAGE(PG8_SA(0, 1), a2 + hstep, voffA);
;             PG8_WAIT_V(8); PG8_WAIT_L(0); PG8_BAR; PG8_MMA(0, 0, At, B0); PG8_MMA(0, 1, At, B1); PG8_BAR; PG8_SCHED;
	s_setprio 1
	s_waitcnt lgkmcnt(0)
	v_mfma_f32_16x16x32_bf16 v[70:73], v[50:53], v[186:189], v[70:73]
	v_mfma_f32_16x16x32_bf16 v[62:65], v[162:165], v[186:189], v[62:65]
	v_mfma_f32_16x16x32_bf16 v[46:49], v[50:53], v[202:205], v[46:49]
	v_mfma_f32_16x16x32_bf16 v[38:41], v[162:165], v[202:205], v[38:41]
	v_mfma_f32_16x16x32_bf16 v[30:33], v[50:53], v[222:225], v[30:33]
	v_mfma_f32_16x16x32_bf16 v[22:25], v[162:165], v[222:225], v[22:25]
	v_mfma_f32_16x16x32_bf16 v[14:17], v[50:53], v[230:233], v[14:17]
	v_mfma_f32_16x16x32_bf16 v[6:9], v[162:165], v[230:233], v[6:9]
	v_mfma_f32_16x16x32_bf16 v[70:73], v[54:57], v[198:201], v[70:73]
	v_mfma_f32_16x16x32_bf16 v[62:65], v[166:169], v[198:201], v[62:65]
	v_mfma_f32_16x16x32_bf16 v[46:49], v[54:57], v[206:209], v[46:49]
	v_mfma_f32_16x16x32_bf16 v[38:41], v[166:169], v[206:209], v[38:41]
	v_mfma_f32_16x16x32_bf16 v[30:33], v[54:57], v[226:229], v[30:33]
	v_mfma_f32_16x16x32_bf16 v[22:25], v[166:169], v[226:229], v[22:25]
	v_mfma_f32_16x16x32_bf16 v[14:17], v[54:57], v[234:237], v[14:17]
	v_mfma_f32_16x16x32_bf16 v[6:9], v[166:169], v[234:237], v[6:9]
	s_setprio 0
	s_setprio 1
	v_mfma_f32_16x16x32_bf16 v[42:45], v[170:173], v[202:205], v[42:45]
	v_mfma_f32_16x16x32_bf16 v[34:37], v[178:181], v[202:205], v[34:37]
	v_mfma_f32_16x16x32_bf16 v[26:29], v[170:173], v[222:225], v[26:29]
	v_mfma_f32_16x16x32_bf16 v[18:21], v[178:181], v[222:225], v[18:21]
	v_mfma_f32_16x16x32_bf16 v[10:13], v[170:173], v[230:233], v[10:13]
	v_mfma_f32_16x16x32_bf16 v[2:5], v[178:181], v[230:233], v[2:5]
	v_mfma_f32_16x16x32_bf16 v[50:53], v[170:173], v[186:189], v[66:69]
	v_mfma_f32_16x16x32_bf16 v[54:57], v[178:181], v[186:189], v[58:61]
	v_mfma_f32_16x16x32_bf16 v[42:45], v[174:177], v[206:209], v[42:45]
	v_mfma_f32_16x16x32_bf16 v[34:37], v[182:185], v[206:209], v[34:37]
	v_mfma_f32_16x16x32_bf16 v[26:29], v[174:177], v[226:229], v[26:29]
	v_mfma_f32_16x16x32_bf16 v[18:21], v[182:185], v[226:229], v[18:21]
	v_mfma_f32_16x16x32_bf16 v[10:13], v[174:177], v[234:237], v[10:13]
	v_mfma_f32_16x16x32_bf16 v[2:5], v[182:185], v[234:237], v[2:5]
	v_mfma_f32_16x16x32_bf16 v[50:53], v[174:177], v[198:201], v[50:53]
	v_mfma_f32_16x16x32_bf16 v[54:57], v[182:185], v[198:201], v[54:57]
	s_setprio 0
	s_barrier
	s_add_i32 s65, 0, 0x18000
	v_add_u32_e32 v161, s65, v157
	s_add_i32 s66, 0, 0x1c000
	ds_read_b128 v[58:61], v161
	ds_read_b128 v[66:69], v161 offset:1024
	ds_read_b128 v[162:165], v161 offset:2048
	ds_read_b128 v[166:169], v161 offset:3072
	v_add_u32_e32 v161, s66, v157
	ds_read_b128 v[170:173], v161
	ds_read_b128 v[174:177], v161 offset:1024
	ds_read_b128 v[178:181], v161 offset:2048
	ds_read_b128 v[182:185], v161 offset:3072
	s_add_u32 s30, s50, 0x40000
	s_addc_u32 s31, s51, 0
	s_mov_b32 m0, s54
	v_lshl_add_u64 v[240:241], s[30:31], 0, v[138:139]
	ds_read_b128 v[186:189], v160 offset:32768
	ds_read_b128 v[198:201], v160 offset:33792
	ds_read_b128 v[202:205], v160 offset:34816
	ds_read_b128 v[206:209], v160 offset:35840
	ds_read_b128 v[222:225], v160 offset:36864
	ds_read_b128 v[226:229], v160 offset:37888
	ds_read_b128 v[230:233], v160 offset:38912
	ds_read_b128 v[234:237], v160 offset:39936
	global_load_lds_dwordx4 v[240:241], off
	v_lshl_add_u64 v[240:241], s[30:31], 0, v[142:143]
	s_mov_b32 m0, s55
	s_nop 0
	global_load_lds_dwordx4 v[240:241], off
	s_waitcnt vmcnt(8)
	s_waitcnt lgkmcnt(0)
	s_barrier
	s_setprio 1
	s_waitcnt lgkmcnt(0)
	v_mfma_f32_16x16x32_bf16 v[134:137], v[58:61], v[186:189], v[134:137]
	v_mfma_f32_16x16x32_bf16 v[126:129], v[162:165], v[186:189], v[126:129]
	v_mfma_f32_16x16x32_bf16 v[118:121], v[58:61], v[202:205], v[118:121]
	v_mfma_f32_16x16x32_bf16 v[110:113], v[162:165], v[202:205], v[110:113]
	v_mfma_f32_16x16x32_bf16 v[102:105], v[58:61], v[222:225], v[102:105]
	v_mfma_f32_16x16x32_bf16 v[94:97], v[162:165], v[222:225], v[94:97]
	v_mfma_f32_16x16x32_bf16 v[86:89], v[58:61], v[230:233], v[86:89]
	v_mfma_f32_16x16x32_bf16 v[78:81], v[162:165], v[230:233], v[78:81]
	v_mfma_f32_16x16x32_bf16 v[134:137], v[66:69], v[198:201], v[134:137]
	v_mfma_f32_16x16x32_bf16 v[126:129], v[166:169], v[198:201], v[126:129]
	v_mfma_f32_16x16x32_bf16 v[118:121], v[66:69], v[206:209], v[118:121]
	v_mfma_f32_16x16x32_bf16 v[110:113], v[166:169], v[206:209], v[110:113]
	v_mfma_f32_16x16x32_bf16 v[102:105], v[66:69], v[226:229], v[102:105]
	v_mfma_f32_16x16x32_bf16 v[94:97], v[166:169], v[226:229], v[94:97]
	v_mfma_f32_16x16x32_bf16 v[86:89], v[66:69], v[234:237], v[86:89]
	v_mfma_f32_16x16x32_bf16 v[78:81], v[166:169], v[234:237], v[78:81]
	s_setprio 0
	s_setprio 1
	v_mfma_f32_16x16x32_bf16 v[130:133], v[170:173], v[186:189], v[130:133]
	v_mfma_f32_16x16x32_bf16 v[122:125], v[178:181], v[186:189], v[122:125]
	v_mfma_f32_16x16x32_bf16 v[114:117], v[170:173], v[202:205], v[114:117]
	v_mfma_f32_16x16x32_bf16 v[106:109], v[178:181], v[202:205], v[106:109]
	v_mfma_f32_16x16x32_bf16 v[98:101], v[170:173], v[222:225], v[98:101]
	v_mfma_f32_16x16x32_bf16 v[90:93], v[178:181], v[222:225], v[90:93]
	v_mfma_f32_16x16x32_bf16 v[82:85], v[170:173], v[230:233], v[82:85]
	v_mfma_f32_16x16x32_bf16 v[74:77], v[178:181], v[230:233], v[74:77]
	v_mfma_f32_16x16x32_bf16 v[130:133], v[174:177], v[198:201], v[130:133]
	v_mfma_f32_16x16x32_bf16 v[122:125], v[182:185], v[198:201], v[122:125]
	v_mfma_f32_16x16x32_bf16 v[114:117], v[174:177], v[206:209], v[114:117]
	v_mfma_f32_16x16x32_bf16 v[106:109], v[182:185], v[206:209], v[106:109]
	v_mfma_f32_16x16x32_bf16 v[98:101], v[174:177], v[226:229], v[98:101]
	v_mfma_f32_16x16x32_bf16 v[90:93], v[182:185], v[226:229], v[90:93]
	v_mfma_f32_16x16x32_bf16 v[82:85], v[174:177], v[234:237], v[82:85]
	v_mfma_f32_16x16x32_bf16 v[74:77], v[182:185], v[234:237], v[74:77]
	s_setprio 0
	s_barrier
; #define PG8_STAGE(bufoff, gbase, voff) do { _Pragma("unroll") for (int _i = 0; _i < 2; ++_i) \
;         __builtin_amdgcn_global_load_lds((const unsigned*)((const char*)(gbase) + (voff)[_i]), (PG8_LAS unsigned*)(lds + (bufoff) + ldsw + _i * 8192), 16, 0, 0); } while (0)
; #define PG8_LDA(dst, b, h) do { _Pragma("unroll") for (int m = 0; m < 4; ++m) _Pragma("unroll") for (int k = 0; k < 2; ++k) dst[m][k] = *(const PG8_LAS bf16x8*)(lds + PG8_SA(b, h) + aoff + m * 2048 + k * 1024); } while (0)
; #define PG8_MMA(ai, bj, At, Bt) do { __builtin_amdgcn_s_setprio(1); _Pragma("unroll") for (int m = 0; m < 4; ++m) _Pragma("unroll") for (int n = 0; n < 2; ++n) _Pragma("unroll") for (int k = 0; k < 2; ++k) \
;         acc[ai][bj][m][n] = __builtin_amdgcn_mfma_f32_16x16x32_bf16(Bt[n][k], At[m][k], acc[ai][bj][m][n], 0, 0, 0); __builtin_amdgcn_s_setprio(0); } while (0)
; #define PG8_WAIT_V(n) asm volatile("s_waitcnt vmcnt(" #n ")" ::: "memory")
; #define PG8_WAIT_L(n) asm volatile("s_waitcnt lgkmcnt(" #n ")" ::: "memory")
; #define PG8_BAR __builtin_amdgcn_s_barrier()
; #define PG8_SCHED __builtin_amdgcn_sched_barrier(0)
; template <class Epi, class Sched, bool ALIGN_EPI = false, bool SP2 = false>
; __device__ __forceinline__ void gemm_phase(PG8_LAS unsigned char* lds, const Gemm g, const Sched& S, const Epi& E) {
;     ...
;         for (int t = 0; t < nt; t += 2) {
;             const bool last = (t == nt - 2);
;             const char* a1 = cA + (size_t)(t + 1) * kstep;
;             const char* a2 = last ? nA : cA + (size_t)(t + 2) * kstep; const char* b2 = last ? nB : cB + (size_t)(t + 2) * kstep;
;             const char* a3 = a2 + kstep; const char* b3 = b2 + kstep;
;     ...
;             PG8_LDA(At, 1, 1); PG8_STAGE(PG8_SB(1, 0), b3, voffB); PG8_STAGE(PG8_SB(1, 1), b3 + hstep, voffB); PG8_STAGE(PG8_SA(1, 0), a3, voffA);
;             PG8_WAIT_V(8); PG8_WAIT_L(0); PG8_BAR; PG8_MMA(1, 0, At, B0); PG8_MMA(1, 1, At, B1); PG8_BAR; PG8_SCHED;
	s_add_i32 s30, s65, s33
	v_lshl_add_u64 v[152:153], v[152:153], 0, s[0:1]
	s_mov_b32 m0, s30
	ds_read_b128 v[186:189], v160 offset:49152
	ds_read_b128 v[198:201], v160 offset:50176
	ds_read_b128 v[202:205], v160 offset:51200
	ds_read_b128 v[206:209], v160 offset:52224
	ds_read_b128 v[222:225], v160 offset:53248
	ds_read_b128 v[226:229], v160 offset:54272
	ds_read_b128 v[230:233], v160 offset:55296
	ds_read_b128 v[234:237], v160 offset:56320
	global_load_lds_dwordx4 v[152:153], off
	s_add_i32 m0, s30, 0x2000
	s_add_u32 s30, s48, 0x40080
	v_lshl_add_u64 v[152:153], v[190:191], 0, s[0:1]
	s_addc_u32 s31, s49, 0
	s_add_i32 s48, s66, s33
	global_load_lds_dwordx4 v[152:153], off
	v_lshl_add_u64 v[152:153], s[30:31], 0, v[140:141]
	s_mov_b32 m0, s48
	s_nop 0
	global_load_lds_dwordx4 v[152:153], off
	v_lshl_add_u64 v[152:153], s[30:31], 0, v[144:145]
	s_add_i32 m0, s48, 0x2000
	s_nop 0
	global_load_lds_dwordx4 v[152:153], off
	v_lshl_add_u64 v[152:153], v[210:211], 0, s[0:1]
	s_mov_b32 m0, s56
	s_nop 0
	global_load_lds_dwordx4 v[152:153], off
	v_lshl_add_u64 v[152:153], v[238:239], 0, s[0:1]
	s_mov_b32 m0, s57
	s_nop 0
	global_load_lds_dwordx4 v[152:153], off
	s_waitcnt vmcnt(8)
	s_waitcnt lgkmcnt(0)
	s_barrier
	s_setprio 1
	s_waitcnt lgkmcnt(0)
	v_mfma_f32_16x16x32_bf16 v[70:73], v[58:61], v[186:189], v[70:73]
	v_mfma_f32_16x16x32_bf16 v[62:65], v[162:165], v[186:189], v[62:65]
	v_mfma_f32_16x16x32_bf16 v[46:49], v[58:61], v[202:205], v[46:49]
	v_mfma_f32_16x16x32_bf16 v[38:41], v[162:165], v[202:205], v[38:41]
	v_mfma_f32_16x16x32_bf16 v[30:33], v[58:61], v[222:225], v[30:33]
	v_mfma_f32_16x16x32_bf16 v[22:25], v[162:165], v[222:225], v[22:25]
	v_mfma_f32_16x16x32_bf16 v[14:17], v[58:61], v[230:233], v[14:17]
	v_mfma_f32_16x16x32_bf16 v[6:9], v[162:165], v[230:233], v[6:9]
	v_mfma_f32_16x16x32_bf16 v[70:73], v[66:69], v[198:201], v[70:73]
	v_mfma_f32_16x16x32_bf16 v[62:65], v[166:169], v[198:201], v[62:65]
	v_mfma_f32_16x16x32_bf16 v[46:49], v[66:69], v[206:209], v[46:49]
	v_mfma_f32_16x16x32_bf16 v[38:41], v[166:169], v[206:209], v[38:41]
	v_mfma_f32_16x16x32_bf16 v[30:33], v[66:69], v[226:229], v[30:33]
	v_mfma_f32_16x16x32_bf16 v[22:25], v[166:169], v[226:229], v[22:25]
	v_mfma_f32_16x16x32_bf16 v[14:17], v[66:69], v[234:237], v[14:17]
	v_mfma_f32_16x16x32_bf16 v[6:9], v[166:169], v[234:237], v[6:9]
	s_setprio 0
	s_setprio 1
	v_mfma_f32_16x16x32_bf16 v[50:53], v[170:173], v[186:189], v[50:53]
	v_mfma_f32_16x16x32_bf16 v[66:69], v[174:177], v[198:201], v[50:53]
	v_mfma_f32_16x16x32_bf16 v[50:53], v[178:181], v[186:189], v[54:57]
	v_mfma_f32_16x16x32_bf16 v[42:45], v[170:173], v[202:205], v[42:45]
	v_mfma_f32_16x16x32_bf16 v[34:37], v[178:181], v[202:205], v[34:37]
	v_mfma_f32_16x16x32_bf16 v[26:29], v[170:173], v[222:225], v[26:29]
	v_mfma_f32_16x16x32_bf16 v[18:21], v[178:181], v[222:225], v[18:21]
	v_mfma_f32_16x16x32_bf16 v[10:13], v[170:173], v[230:233], v[10:13]
	v_mfma_f32_16x16x32_bf16 v[2:5], v[178:181], v[230:233], v[2:5]
	v_mfma_f32_16x16x32_bf16 v[58:61], v[182:185], v[198:201], v[50:53]
	v_mfma_f32_16x16x32_bf16 v[42:45], v[174:177], v[206:209], v[42:45]
	v_mfma_f32_16x16x32_bf16 v[34:37], v[182:185], v[206:209], v[34:37]
	v_mfma_f32_16x16x32_bf16 v[26:29], v[174:177], v[226:229], v[26:29]
	v_mfma_f32_16x16x32_bf16 v[18:21], v[182:185], v[226:229], v[18:21]
	v_mfma_f32_16x16x32_bf16 v[10:13], v[174:177], v[234:237], v[10:13]
	v_mfma_f32_16x16x32_bf16 v[2:5], v[182:185], v[234:237], v[2:5]
	s_setprio 0
	s_add_i32 s64, s64, 2
	s_add_u32 s46, s46, 0x100
	s_addc_u32 s47, s47, 0
	s_add_u32 s62, s62, 0x100
	s_addc_u32 s63, s63, 0
	s_cmp_gt_u32 s64, 13
	s_cbranch_scc1 .Lrot_exit_p4
	s_add_u32 s30, s46, 0xfffc0080
	s_addc_u32 s31, s47, -1
	s_add_i32 s65, 0, 0x10000
	s_cmp_eq_u32 s64, 12
	s_cselect_b32 s51, s15, s31
	s_cselect_b32 s50, s60, s30
	v_add_u32_e32 v152, s65, v157
	s_cselect_b32 s49, s11, s63
	s_cselect_b32 s48, s61, s62
	s_add_i32 s66, 0, 0x14000
	s_barrier
	s_branch .LBB0_781

; #define PG8_STAGE(bufoff, gbase, voff) do { _Pragma("unroll") for (int _i = 0; _i < 2; ++_i) \
;         __builtin_amdgcn_global_load_lds((const unsigned*)((const char*)(gbase) + (voff)[_i]), (PG8_LAS unsigned*)(lds + (bufoff) + ldsw + _i * 8192), 16, 0, 0); } while (0)
; #define PG8_LDA(dst, b, h) do { _Pragma("unroll") for (int m = 0; m < 4; ++m) _Pragma("unroll") for (int k = 0; k < 2; ++k) dst[m][k] = *(const PG8_LAS bf16x8*)(lds + PG8_SA(b, h) + aoff + m * 2048 + k * 1024); } while (0)
; #define PG8_LDB(dst, b, h) do { _Pragma("unroll") for (int n = 0; n < 2; ++n) _Pragma("unroll") for (int k = 0; k < 2; ++k) dst[n][k] = *(const PG8_LAS bf16x8*)(lds + PG8_SB(b, h) + boff + n * 2048 + k * 1024); } while (0)
; #define PG8_MMA(ai, bj, At, Bt) do { __builtin_amdgcn_s_setprio(1); _Pragma("unroll") for (int m = 0; m < 4; ++m) _Pragma("unroll") for (int n = 0; n < 2; ++n) _Pragma("unroll") for (int k = 0; k < 2; ++k) \
;         acc[ai][bj][m][n] = __builtin_amdgcn_mfma_f32_16x16x32_bf16(Bt[n][k], At[m][k], acc[ai][bj][m][n], 0, 0, 0); __builtin_amdgcn_s_setprio(0); } while (0)
; #define PG8_WAIT_V(n) asm volatile("s_waitcnt vmcnt(" #n ")" ::: "memory")
; #define PG8_WAIT_L(n) asm volatile("s_waitcnt lgkmcnt(" #n ")" ::: "memory")
; #define PG8_BAR __builtin_amdgcn_s_barrier()
; #define PG8_SCHED __builtin_amdgcn_sched_barrier(0)
; template <class Epi, class Sched, bool ALIGN_EPI = false, bool SP2 = false>
; __device__ __forceinline__ void gemm_phase(PG8_LAS unsigned char* lds, const Gemm g, const Sched& S, const Epi& E) {
;     ...
;         for (int t = 0; t < nt; t += 2) {
;             const bool last = (t == nt - 2);
;             const char* a1 = cA + (size_t)(t + 1) * kstep;
;             const char* a2 = last ? nA : cA + (size_t)(t + 2) * kstep; const char* b2 = last ? nB : cB + (size_t)(t + 2) * kstep;
;             const char* a3 = a2 + kstep; const char* b3 = b2 + kstep;
;             if (last && has_next) S.a_ready(nxt);
;             if constexpr (SP2) {
;             PG8_LDB(B0, 0, 0); PG8_LDB(B1, 0, 1); PG8_SCHED; PG8_LDA(At, 0, 0); PG8_STAGE(PG8_SA(1, 1), a1 + hstep, voffA);
;             PG8_WAIT_V(8); PG8_WAIT_L(0); PG8_BAR; PG8_MMA(0, 0, At, B0); PG8_MMA(0, 1, At, B1); PG8_BAR; PG8_SCHED;
;             PG8_LDA(At, 0, 1); PG8_STAGE(PG8_SB(0, 0), b2, voffB); PG8_STAGE(PG8_SB(0, 1), b2 + hstep, voffB); PG8_STAGE(PG8_SA(0, 0), a2, voffA);
.Lpeel_p5:
	s_add_u32 s42, s20, 0x100
	s_addc_u32 s43, s21, 0
	s_add_i32 s30, 0, 0x10000
	s_cmp_eq_u32 s59, 40
	s_cselect_b32 s47, s11, s43
	s_cselect_b32 s46, s10, s42
	s_cselect_b32 s45, s15, s35
	s_cselect_b32 s44, s14, s34
	s_add_i32 s31, 0, 0x14000
	v_add_u32_e32 v134, s30, v191
	v_add_u32_e32 v168, s31, v191
	ds_read_b128 v[114:117], v134
	ds_read_b128 v[126:129], v134 offset:1024
	ds_read_b128 v[130:133], v134 offset:2048
	ds_read_b128 v[134:137], v134 offset:3072
	ds_read_b128 v[146:149], v168
	ds_read_b128 v[150:153], v168 offset:1024
	ds_read_b128 v[154:157], v168 offset:2048
	ds_read_b128 v[168:171], v168 offset:3072
	v_lshl_add_u64 v[188:189], s[20:21], 0, v[164:165]
	s_add_i32 m0, s48, 0xc000
	ds_read_b128 v[172:175], v202
	ds_read_b128 v[176:179], v202 offset:1024
	ds_read_b128 v[180:183], v202 offset:2048
	ds_read_b128 v[184:187], v202 offset:3072
	ds_read_b128 v[198:201], v202 offset:4096
	ds_read_b128 v[204:207], v202 offset:5120
	ds_read_b128 v[208:211], v202 offset:6144
	ds_read_b128 v[222:225], v202 offset:7168
	global_load_lds_dwordx4 v[188:189], off
	v_lshl_add_u64 v[188:189], s[20:21], 0, v[166:167]
	s_add_i32 m0, s48, 0xe000
	s_nop 0
	global_load_lds_dwordx4 v[188:189], off
	s_waitcnt vmcnt(8)
	s_waitcnt lgkmcnt(0)
	s_barrier
	s_setprio 1
	s_waitcnt lgkmcnt(0)
	v_mfma_f32_16x16x32_bf16 v[142:145], v[114:117], v[172:175], 0
	v_mfma_f32_16x16x32_bf16 v[138:141], v[130:133], v[172:175], 0
	v_mfma_f32_16x16x32_bf16 v[110:113], v[114:117], v[180:183], 0
	v_mfma_f32_16x16x32_bf16 v[106:109], v[130:133], v[180:183], 0
	v_mfma_f32_16x16x32_bf16 v[94:97], v[114:117], v[198:201], 0
	v_mfma_f32_16x16x32_bf16 v[90:93], v[130:133], v[198:201], 0
	v_mfma_f32_16x16x32_bf16 v[78:81], v[114:117], v[208:211], 0
	v_mfma_f32_16x16x32_bf16 v[74:77], v[130:133], v[208:211], 0
	v_mfma_f32_16x16x32_bf16 v[142:145], v[126:129], v[176:179], v[142:145]
	v_mfma_f32_16x16x32_bf16 v[138:141], v[134:137], v[176:179], v[138:141]
	v_mfma_f32_16x16x32_bf16 v[110:113], v[126:129], v[184:187], v[110:113]
	v_mfma_f32_16x16x32_bf16 v[106:109], v[134:137], v[184:187], v[106:109]
	v_mfma_f32_16x16x32_bf16 v[94:97], v[126:129], v[204:207], v[94:97]
	v_mfma_f32_16x16x32_bf16 v[90:93], v[134:137], v[204:207], v[90:93]
	v_mfma_f32_16x16x32_bf16 v[78:81], v[126:129], v[222:225], v[78:81]
	v_mfma_f32_16x16x32_bf16 v[74:77], v[134:137], v[222:225], v[74:77]
	s_setprio 0
	s_setprio 1
	v_mfma_f32_16x16x32_bf16 v[122:125], v[146:149], v[172:175], 0
	v_mfma_f32_16x16x32_bf16 v[118:121], v[154:157], v[172:175], 0
	v_mfma_f32_16x16x32_bf16 v[102:105], v[146:149], v[180:183], 0
	v_mfma_f32_16x16x32_bf16 v[98:101], v[154:157], v[180:183], 0
	v_mfma_f32_16x16x32_bf16 v[86:89], v[146:149], v[198:201], 0
	v_mfma_f32_16x16x32_bf16 v[82:85], v[154:157], v[198:201], 0
	v_mfma_f32_16x16x32_bf16 v[70:73], v[146:149], v[208:211], 0
	v_mfma_f32_16x16x32_bf16 v[66:69], v[154:157], v[208:211], 0
	v_mfma_f32_16x16x32_bf16 v[122:125], v[150:153], v[176:179], v[122:125]
	v_mfma_f32_16x16x32_bf16 v[118:121], v[168:171], v[176:179], v[118:121]
	v_mfma_f32_16x16x32_bf16 v[102:105], v[150:153], v[184:187], v[102:105]
	v_mfma_f32_16x16x32_bf16 v[98:101], v[168:171], v[184:187], v[98:101]
	v_mfma_f32_16x16x32_bf16 v[86:89], v[150:153], v[204:207], v[86:89]
	v_mfma_f32_16x16x32_bf16 v[82:85], v[168:171], v[204:207], v[82:85]
	v_mfma_f32_16x16x32_bf16 v[70:73], v[150:153], v[222:225], v[70:73]
	v_mfma_f32_16x16x32_bf16 v[66:69], v[168:171], v[222:225], v[66:69]
	s_setprio 0
	s_barrier
	s_add_i32 s20, s30, s33
	v_lshl_add_u64 v[188:189], s[44:45], 0, v[0:1]
	s_mov_b32 m0, s20
	ds_read_b128 v[172:175], v202 offset:16384
	ds_read_b128 v[176:179], v202 offset:17408
	ds_read_b128 v[180:183], v202 offset:18432
	ds_read_b128 v[184:187], v202 offset:19456
	ds_read_b128 v[198:201], v202 offset:20480
	ds_read_b128 v[204:207], v202 offset:21504
	ds_read_b128 v[208:211], v202 offset:22528
	ds_read_b128 v[222:225], v202 offset:23552
	global_load_lds_dwordx4 v[188:189], off
	s_add_i32 m0, s20, 0x2000
	s_add_u32 s20, s44, 0xb0000
	v_lshl_add_u64 v[226:227], s[44:45], 0, v[158:159]
	s_addc_u32 s21, s45, 0
	s_add_i32 s30, s31, s33
	global_load_lds_dwordx4 v[226:227], off
	v_lshl_add_u64 v[228:229], s[20:21], 0, v[0:1]
	s_mov_b32 m0, s30
	v_lshl_add_u64 v[230:231], s[46:47], 0, v[160:161]
	global_load_lds_dwordx4 v[228:229], off
	v_lshl_add_u64 v[228:229], s[20:21], 0, v[158:159]
	s_add_i32 m0, s30, 0x2000
	s_nop 0
	global_load_lds_dwordx4 v[228:229], off
	v_lshl_add_u64 v[228:229], s[46:47], 0, v[162:163]
	s_mov_b32 m0, s48
	s_nop 0
	global_load_lds_dwordx4 v[228:229], off
	s_mov_b32 m0, s49
	s_nop 0
	global_load_lds_dwordx4 v[230:231], off
	s_waitcnt vmcnt(8)
	s_waitcnt lgkmcnt(0)
	s_barrier
; #define PG8_STAGE(bufoff, gbase, voff) do { _Pragma("unroll") for (int _i = 0; _i < 2; ++_i) \
;         __builtin_amdgcn_global_load_lds((const unsigned*)((const char*)(gbase) + (voff)[_i]), (PG8_LAS unsigned*)(lds + (bufoff) + ldsw + _i * 8192), 16, 0, 0); } while (0)
; #define PG8_LDA(dst, b, h) do { _Pragma("unroll") for (int m = 0; m < 4; ++m) _Pragma("unroll") for (int k = 0; k < 2; ++k) dst[m][k] = *(const PG8_LAS bf16x8*)(lds + PG8_SA(b, h) + aoff + m * 2048 + k * 1024); } while (0)
; #define PG8_LDB(dst, b, h) do { _Pragma("unroll") for (int n = 0; n < 2; ++n) _Pragma("unroll") for (int k = 0; k < 2; ++k) dst[n][k] = *(const PG8_LAS bf16x8*)(lds + PG8_SB(b, h) + boff + n * 2048 + k * 1024); } while (0)
; #define PG8_MMA(ai, bj, At, Bt) do { __builtin_amdgcn_s_setprio(1); _Pragma("unroll") for (int m = 0; m < 4; ++m) _Pragma("unroll") for (int n = 0; n < 2; ++n) _Pragma("unroll") for (int k = 0; k < 2; ++k) \
;         acc[ai][bj][m][n] = __builtin_amdgcn_mfma_f32_16x16x32_bf16(Bt[n][k], At[m][k], acc[ai][bj][m][n], 0, 0, 0); __builtin_amdgcn_s_setprio(0); } while (0)
; #define PG8_WAIT_V(n) asm volatile("s_waitcnt vmcnt(" #n ")" ::: "memory")
; #define PG8_WAIT_L(n) asm volatile("s_waitcnt lgkmcnt(" #n ")" ::: "memory")
; #define PG8_BAR __builtin_amdgcn_s_barrier()
; #define PG8_SCHED __builtin_amdgcn_sched_barrier(0)
; template <class Epi, class Sched, bool ALIGN_EPI = false, bool SP2 = false>
; __device__ __forceinline__ void gemm_phase(PG8_LAS unsigned char* lds, const Gemm g, const Sched& S, const Epi& E) {
;     ...
;             PG8_WAIT_V(8); PG8_WAIT_L(0); PG8_BAR; PG8_MMA(1, 0, At, B0); PG8_MMA(1, 1, At, B1); PG8_BAR; PG8_SCHED;
;             PG8_LDB(B0, 1, 0); PG8_LDB(B1, 1, 1); PG8_SCHED; PG8_LDA(At, 1, 0); PG8_STAGE(PG8_SA(0, 1), a2 + hstep, voffA);
;             PG8_WAIT_V(8); PG8_WAIT_L(0); PG8_BAR; PG8_MMA(0, 0, At, B0); PG8_MMA(0, 1, At, B1); PG8_BAR; PG8_SCHED;
	s_setprio 1
	s_waitcnt lgkmcnt(0)
	v_mfma_f32_16x16x32_bf16 v[62:65], v[114:117], v[172:175], 0
	v_mfma_f32_16x16x32_bf16 v[58:61], v[130:133], v[172:175], 0
	v_mfma_f32_16x16x32_bf16 v[46:49], v[114:117], v[180:183], 0
	v_mfma_f32_16x16x32_bf16 v[42:45], v[130:133], v[180:183], 0
	v_mfma_f32_16x16x32_bf16 v[30:33], v[114:117], v[198:201], 0
	v_mfma_f32_16x16x32_bf16 v[26:29], v[130:133], v[198:201], 0
	v_mfma_f32_16x16x32_bf16 v[14:17], v[114:117], v[208:211], 0
	v_mfma_f32_16x16x32_bf16 v[10:13], v[130:133], v[208:211], 0
	v_mfma_f32_16x16x32_bf16 v[62:65], v[126:129], v[176:179], v[62:65]
	v_mfma_f32_16x16x32_bf16 v[58:61], v[134:137], v[176:179], v[58:61]
	v_mfma_f32_16x16x32_bf16 v[46:49], v[126:129], v[184:187], v[46:49]
	v_mfma_f32_16x16x32_bf16 v[42:45], v[134:137], v[184:187], v[42:45]
	v_mfma_f32_16x16x32_bf16 v[30:33], v[126:129], v[204:207], v[30:33]
	v_mfma_f32_16x16x32_bf16 v[26:29], v[134:137], v[204:207], v[26:29]
	v_mfma_f32_16x16x32_bf16 v[14:17], v[126:129], v[222:225], v[14:17]
	v_mfma_f32_16x16x32_bf16 v[10:13], v[134:137], v[222:225], v[10:13]
	s_setprio 0
	s_setprio 1
	v_mfma_f32_16x16x32_bf16 v[54:57], v[146:149], v[172:175], 0
	v_mfma_f32_16x16x32_bf16 v[50:53], v[154:157], v[172:175], 0
	v_mfma_f32_16x16x32_bf16 v[38:41], v[146:149], v[180:183], 0
	v_mfma_f32_16x16x32_bf16 v[34:37], v[154:157], v[180:183], 0
	v_mfma_f32_16x16x32_bf16 v[22:25], v[146:149], v[198:201], 0
	v_mfma_f32_16x16x32_bf16 v[18:21], v[154:157], v[198:201], 0
	v_mfma_f32_16x16x32_bf16 v[6:9], v[146:149], v[208:211], 0
	v_mfma_f32_16x16x32_bf16 v[2:5], v[154:157], v[208:211], 0
	v_mfma_f32_16x16x32_bf16 v[54:57], v[150:153], v[176:179], v[54:57]
	v_mfma_f32_16x16x32_bf16 v[50:53], v[168:171], v[176:179], v[50:53]
	v_mfma_f32_16x16x32_bf16 v[38:41], v[150:153], v[184:187], v[38:41]
	v_mfma_f32_16x16x32_bf16 v[34:37], v[168:171], v[184:187], v[34:37]
	v_mfma_f32_16x16x32_bf16 v[22:25], v[150:153], v[204:207], v[22:25]
	v_mfma_f32_16x16x32_bf16 v[18:21], v[168:171], v[204:207], v[18:21]
	v_mfma_f32_16x16x32_bf16 v[6:9], v[150:153], v[222:225], v[6:9]
	v_mfma_f32_16x16x32_bf16 v[2:5], v[168:171], v[222:225], v[2:5]
	s_setprio 0
	s_barrier
	s_add_i32 s30, 0, 0x18000
	s_add_i32 s31, 0, 0x1c000
	v_add_u32_e32 v134, s30, v191
	v_add_u32_e32 v168, s31, v191
	ds_read_b128 v[114:117], v134
	ds_read_b128 v[126:129], v134 offset:1024
	ds_read_b128 v[130:133], v134 offset:2048
	ds_read_b128 v[134:137], v134 offset:3072
	ds_read_b128 v[146:149], v168
	ds_read_b128 v[150:153], v168 offset:1024
	ds_read_b128 v[154:157], v168 offset:2048
	ds_read_b128 v[168:171], v168 offset:3072
	s_add_u32 s20, s46, 0xb0000
	s_addc_u32 s21, s47, 0
	s_mov_b32 m0, s50
	v_lshl_add_u64 v[232:233], s[20:21], 0, v[162:163]
	ds_read_b128 v[172:175], v202 offset:32768
	ds_read_b128 v[176:179], v202 offset:33792
	ds_read_b128 v[180:183], v202 offset:34816
	ds_read_b128 v[184:187], v202 offset:35840
	ds_read_b128 v[198:201], v202 offset:36864
	ds_read_b128 v[204:207], v202 offset:37888
	ds_read_b128 v[208:211], v202 offset:38912
	ds_read_b128 v[222:225], v202 offset:39936
	global_load_lds_dwordx4 v[232:233], off
	v_lshl_add_u64 v[232:233], s[20:21], 0, v[160:161]
	s_mov_b32 m0, s51
	s_nop 0
	global_load_lds_dwordx4 v[232:233], off
	s_waitcnt vmcnt(8)
	s_waitcnt lgkmcnt(0)
	s_barrier
	s_setprio 1
	s_waitcnt lgkmcnt(0)
	v_mfma_f32_16x16x32_bf16 v[142:145], v[114:117], v[172:175], v[142:145]
	v_mfma_f32_16x16x32_bf16 v[138:141], v[130:133], v[172:175], v[138:141]
	v_mfma_f32_16x16x32_bf16 v[110:113], v[114:117], v[180:183], v[110:113]
	v_mfma_f32_16x16x32_bf16 v[106:109], v[130:133], v[180:183], v[106:109]
	v_mfma_f32_16x16x32_bf16 v[94:97], v[114:117], v[198:201], v[94:97]
	v_mfma_f32_16x16x32_bf16 v[90:93], v[130:133], v[198:201], v[90:93]
	v_mfma_f32_16x16x32_bf16 v[78:81], v[114:117], v[208:211], v[78:81]
	v_mfma_f32_16x16x32_bf16 v[74:77], v[130:133], v[208:211], v[74:77]
	v_mfma_f32_16x16x32_bf16 v[142:145], v[126:129], v[176:179], v[142:145]
	v_mfma_f32_16x16x32_bf16 v[138:141], v[134:137], v[176:179], v[138:141]
	v_mfma_f32_16x16x32_bf16 v[110:113], v[126:129], v[184:187], v[110:113]
	v_mfma_f32_16x16x32_bf16 v[106:109], v[134:137], v[184:187], v[106:109]
	v_mfma_f32_16x16x32_bf16 v[94:97], v[126:129], v[204:207], v[94:97]
	v_mfma_f32_16x16x32_bf16 v[90:93], v[134:137], v[204:207], v[90:93]
	v_mfma_f32_16x16x32_bf16 v[78:81], v[126:129], v[222:225], v[78:81]
	v_mfma_f32_16x16x32_bf16 v[74:77], v[134:137], v[222:225], v[74:77]
	s_setprio 0
	s_setprio 1
	v_mfma_f32_16x16x32_bf16 v[122:125], v[146:149], v[172:175], v[122:125]
	v_mfma_f32_16x16x32_bf16 v[118:121], v[154:157], v[172:175], v[118:121]
	v_mfma_f32_16x16x32_bf16 v[102:105], v[146:149], v[180:183], v[102:105]
	v_mfma_f32_16x16x32_bf16 v[98:101], v[154:157], v[180:183], v[98:101]
	v_mfma_f32_16x16x32_bf16 v[86:89], v[146:149], v[198:201], v[86:89]
	v_mfma_f32_16x16x32_bf16 v[82:85], v[154:157], v[198:201], v[82:85]
	v_mfma_f32_16x16x32_bf16 v[70:73], v[146:149], v[208:211], v[70:73]
	v_mfma_f32_16x16x32_bf16 v[66:69], v[154:157], v[208:211], v[66:69]
	v_mfma_f32_16x16x32_bf16 v[122:125], v[150:153], v[176:179], v[122:125]
	v_mfma_f32_16x16x32_bf16 v[118:121], v[168:171], v[176:179], v[118:121]
	v_mfma_f32_16x16x32_bf16 v[102:105], v[150:153], v[184:187], v[102:105]
	v_mfma_f32_16x16x32_bf16 v[98:101], v[168:171], v[184:187], v[98:101]
	v_mfma_f32_16x16x32_bf16 v[86:89], v[150:153], v[204:207], v[86:89]
	v_mfma_f32_16x16x32_bf16 v[82:85], v[168:171], v[204:207], v[82:85]
	v_mfma_f32_16x16x32_bf16 v[70:73], v[150:153], v[222:225], v[70:73]
	v_mfma_f32_16x16x32_bf16 v[66:69], v[168:171], v[222:225], v[66:69]
	s_setprio 0
	s_barrier
; #define PG8_STAGE(bufoff, gbase, voff) do { _Pragma("unroll") for (int _i = 0; _i < 2; ++_i) \
;         __builtin_amdgcn_global_load_lds((const unsigned*)((const char*)(gbase) + (voff)[_i]), (PG8_LAS unsigned*)(lds + (bufoff) + ldsw + _i * 8192), 16, 0, 0); } while (0)
; #define PG8_LDA(dst, b, h) do { _Pragma("unroll") for (int m = 0; m < 4; ++m) _Pragma("unroll") for (int k = 0; k < 2; ++k) dst[m][k] = *(const PG8_LAS bf16x8*)(lds + PG8_SA(b, h) + aoff + m * 2048 + k * 1024); } while (0)
; #define PG8_MMA(ai, bj, At, Bt) do { __builtin_amdgcn_s_setprio(1); _Pragma("unroll") for (int m = 0; m < 4; ++m) _Pragma("unroll") for (int n = 0; n < 2; ++n) _Pragma("unroll") for (int k = 0; k < 2; ++k) \
;         acc[ai][bj][m][n] = __builtin_amdgcn_mfma_f32_16x16x32_bf16(Bt[n][k], At[m][k], acc[ai][bj][m][n], 0, 0, 0); __builtin_amdgcn_s_setprio(0); } while (0)
; #define PG8_WAIT_V(n) asm volatile("s_waitcnt vmcnt(" #n ")" ::: "memory")
; #define PG8_WAIT_L(n) asm volatile("s_waitcnt lgkmcnt(" #n ")" ::: "memory")
; #define PG8_BAR __builtin_amdgcn_s_barrier()
; #define PG8_SCHED __builtin_amdgcn_sched_barrier(0)
; template <class Epi, class Sched, bool ALIGN_EPI = false, bool SP2 = false>
; __device__ __forceinline__ void gemm_phase(PG8_LAS unsigned char* lds, const Gemm g, const Sched& S, const Epi& E) {
;     ...
;         for (int t = 0; t < nt; t += 2) {
;             const bool last = (t == nt - 2);
;             const char* a1 = cA + (size_t)(t + 1) * kstep;
;             const char* a2 = last ? nA : cA + (size_t)(t + 2) * kstep; const char* b2 = last ? nB : cB + (size_t)(t + 2) * kstep;
;             const char* a3 = a2 + kstep; const char* b3 = b2 + kstep;
;     ...
;             PG8_LDA(At, 1, 1); PG8_STAGE(PG8_SB(1, 0), b3, voffB); PG8_STAGE(PG8_SB(1, 1), b3 + hstep, voffB); PG8_STAGE(PG8_SA(1, 0), a3, voffA);
;             PG8_WAIT_V(8); PG8_WAIT_L(0); PG8_BAR; PG8_MMA(1, 0, At, B0); PG8_MMA(1, 1, At, B1); PG8_BAR; PG8_SCHED;
	s_add_i32 s20, s30, s33
	v_lshl_add_u64 v[188:189], v[188:189], 0, s[0:1]
	s_mov_b32 m0, s20
	ds_read_b128 v[172:175], v202 offset:49152
	ds_read_b128 v[176:179], v202 offset:50176
	ds_read_b128 v[180:183], v202 offset:51200
	ds_read_b128 v[184:187], v202 offset:52224
	ds_read_b128 v[198:201], v202 offset:53248
	ds_read_b128 v[204:207], v202 offset:54272
	ds_read_b128 v[208:211], v202 offset:55296
	ds_read_b128 v[222:225], v202 offset:56320
	global_load_lds_dwordx4 v[188:189], off
	s_add_i32 m0, s20, 0x2000
	s_add_u32 s20, s44, 0xb0080
	v_lshl_add_u64 v[188:189], v[226:227], 0, s[0:1]
	s_addc_u32 s21, s45, 0
	s_add_i32 s30, s31, s33
	global_load_lds_dwordx4 v[188:189], off
	v_lshl_add_u64 v[188:189], s[20:21], 0, v[0:1]
	s_mov_b32 m0, s30
	s_nop 0
	global_load_lds_dwordx4 v[188:189], off
	v_lshl_add_u64 v[188:189], s[20:21], 0, v[158:159]
	s_add_i32 m0, s30, 0x2000
	s_nop 0
	global_load_lds_dwordx4 v[188:189], off
	v_lshl_add_u64 v[188:189], v[228:229], 0, s[0:1]
	s_mov_b32 m0, s54
	s_nop 0
	global_load_lds_dwordx4 v[188:189], off
	v_lshl_add_u64 v[188:189], v[230:231], 0, s[0:1]
	s_mov_b32 m0, s55
	s_nop 0
	global_load_lds_dwordx4 v[188:189], off
	s_waitcnt vmcnt(8)
	s_waitcnt lgkmcnt(0)
	s_barrier
	s_setprio 1
	s_waitcnt lgkmcnt(0)
	v_mfma_f32_16x16x32_bf16 v[62:65], v[114:117], v[172:175], v[62:65]
	v_mfma_f32_16x16x32_bf16 v[58:61], v[130:133], v[172:175], v[58:61]
	v_mfma_f32_16x16x32_bf16 v[46:49], v[114:117], v[180:183], v[46:49]
	v_mfma_f32_16x16x32_bf16 v[42:45], v[130:133], v[180:183], v[42:45]
	v_mfma_f32_16x16x32_bf16 v[30:33], v[114:117], v[198:201], v[30:33]
	v_mfma_f32_16x16x32_bf16 v[26:29], v[130:133], v[198:201], v[26:29]
	v_mfma_f32_16x16x32_bf16 v[14:17], v[114:117], v[208:211], v[14:17]
	v_mfma_f32_16x16x32_bf16 v[10:13], v[130:133], v[208:211], v[10:13]
	v_mfma_f32_16x16x32_bf16 v[62:65], v[126:129], v[176:179], v[62:65]
	v_mfma_f32_16x16x32_bf16 v[58:61], v[134:137], v[176:179], v[58:61]
	v_mfma_f32_16x16x32_bf16 v[46:49], v[126:129], v[184:187], v[46:49]
	v_mfma_f32_16x16x32_bf16 v[42:45], v[134:137], v[184:187], v[42:45]
	v_mfma_f32_16x16x32_bf16 v[30:33], v[126:129], v[204:207], v[30:33]
	v_mfma_f32_16x16x32_bf16 v[26:29], v[134:137], v[204:207], v[26:29]
	v_mfma_f32_16x16x32_bf16 v[14:17], v[126:129], v[222:225], v[14:17]
	v_mfma_f32_16x16x32_bf16 v[10:13], v[134:137], v[222:225], v[10:13]
	s_setprio 0
	s_setprio 1
	v_mfma_f32_16x16x32_bf16 v[54:57], v[146:149], v[172:175], v[54:57]
	v_mfma_f32_16x16x32_bf16 v[50:53], v[154:157], v[172:175], v[50:53]
	v_mfma_f32_16x16x32_bf16 v[38:41], v[146:149], v[180:183], v[38:41]
	v_mfma_f32_16x16x32_bf16 v[34:37], v[154:157], v[180:183], v[34:37]
	v_mfma_f32_16x16x32_bf16 v[22:25], v[146:149], v[198:201], v[22:25]
	v_mfma_f32_16x16x32_bf16 v[18:21], v[154:157], v[198:201], v[18:21]
	v_mfma_f32_16x16x32_bf16 v[6:9], v[146:149], v[208:211], v[6:9]
	v_mfma_f32_16x16x32_bf16 v[2:5], v[154:157], v[208:211], v[2:5]
	v_mfma_f32_16x16x32_bf16 v[54:57], v[150:153], v[176:179], v[54:57]
	v_mfma_f32_16x16x32_bf16 v[50:53], v[168:171], v[176:179], v[50:53]
	v_mfma_f32_16x16x32_bf16 v[38:41], v[150:153], v[184:187], v[38:41]
	v_mfma_f32_16x16x32_bf16 v[34:37], v[168:171], v[184:187], v[34:37]
	v_mfma_f32_16x16x32_bf16 v[22:25], v[150:153], v[204:207], v[22:25]
	v_mfma_f32_16x16x32_bf16 v[18:21], v[168:171], v[204:207], v[18:21]
	v_mfma_f32_16x16x32_bf16 v[6:9], v[150:153], v[222:225], v[6:9]
	v_mfma_f32_16x16x32_bf16 v[2:5], v[168:171], v[222:225], v[2:5]
	s_setprio 0
	s_add_i32 s59, s59, 2
	s_add_u32 s34, s34, 0x100
	s_addc_u32 s35, s35, 0
	s_mov_b64 s[20:21], s[42:43]
	s_cmp_gt_u32 s59, 41
	s_cbranch_scc1 .Lrot_exit_peel_p5
	s_add_u32 s42, s20, 0x100
	s_addc_u32 s43, s21, 0
	s_add_i32 s30, 0, 0x10000
	s_cmp_eq_u32 s59, 40
	s_cselect_b32 s47, s11, s43
	s_cselect_b32 s46, s10, s42
	s_cselect_b32 s45, s15, s35
	s_cselect_b32 s44, s14, s34
	s_add_i32 s31, 0, 0x14000
	v_add_u32_e32 v134, s30, v191
	v_add_u32_e32 v168, s31, v191
	s_barrier
	s_branch .LBB0_868

; #define PG8_STAGE(bufoff, gbase, voff) do { _Pragma("unroll") for (int _i = 0; _i < 2; ++_i) \
;         __builtin_amdgcn_global_load_lds((const unsigned*)((const char*)(gbase) + (voff)[_i]), (PG8_LAS unsigned*)(lds + (bufoff) + ldsw + _i * 8192), 16, 0, 0); } while (0)
; #define PG8_LDA(dst, b, h) do { _Pragma("unroll") for (int m = 0; m < 4; ++m) _Pragma("unroll") for (int k = 0; k < 2; ++k) dst[m][k] = *(const PG8_LAS bf16x8*)(lds + PG8_SA(b, h) + aoff + m * 2048 + k * 1024); } while (0)
; #define PG8_LDB(dst, b, h) do { _Pragma("unroll") for (int n = 0; n < 2; ++n) _Pragma("unroll") for (int k = 0; k < 2; ++k) dst[n][k] = *(const PG8_LAS bf16x8*)(lds + PG8_SB(b, h) + boff + n * 2048 + k * 1024); } while (0)
; #define PG8_MMA(ai, bj, At, Bt) do { __builtin_amdgcn_s_setprio(1); _Pragma("unroll") for (int m = 0; m < 4; ++m) _Pragma("unroll") for (int n = 0; n < 2; ++n) _Pragma("unroll") for (int k = 0; k < 2; ++k) \
;         acc[ai][bj][m][n] = __builtin_amdgcn_mfma_f32_16x16x32_bf16(Bt[n][k], At[m][k], acc[ai][bj][m][n], 0, 0, 0); __builtin_amdgcn_s_setprio(0); } while (0)
; #define PG8_WAIT_V(n) asm volatile("s_waitcnt vmcnt(" #n ")" ::: "memory")
; #define PG8_WAIT_L(n) asm volatile("s_waitcnt lgkmcnt(" #n ")" ::: "memory")
; #define PG8_BAR __builtin_amdgcn_s_barrier()
; #define PG8_SCHED __builtin_amdgcn_sched_barrier(0)
; template <class Epi, class Sched, bool ALIGN_EPI = false, bool SP2 = false>
; __device__ __forceinline__ void gemm_phase(PG8_LAS unsigned char* lds, const Gemm g, const Sched& S, const Epi& E) {
;     ...
;             PG8_LDB(B0, 0, 0); PG8_LDB(B1, 0, 1); PG8_SCHED; PG8_LDA(At, 0, 0); PG8_STAGE(PG8_SA(1, 1), a1 + hstep, voffA);
;             PG8_WAIT_V(8); PG8_WAIT_L(0); PG8_BAR; PG8_MMA(0, 0, At, B0); PG8_MMA(0, 1, At, B1); PG8_BAR; PG8_SCHED;
;             PG8_LDA(At, 0, 1); PG8_STAGE(PG8_SB(0, 0), b2, voffB); PG8_STAGE(PG8_SB(0, 1), b2 + hstep, voffB); PG8_STAGE(PG8_SA(0, 0), a2, voffA);
.LBB0_868:
	ds_read_b128 v[114:117], v134
	ds_read_b128 v[126:129], v134 offset:1024
	ds_read_b128 v[130:133], v134 offset:2048
	ds_read_b128 v[134:137], v134 offset:3072
	ds_read_b128 v[146:149], v168
	ds_read_b128 v[150:153], v168 offset:1024
	ds_read_b128 v[154:157], v168 offset:2048
	ds_read_b128 v[168:171], v168 offset:3072
	v_lshl_add_u64 v[188:189], s[20:21], 0, v[164:165]
	s_add_i32 m0, s48, 0xc000
	ds_read_b128 v[172:175], v202
	ds_read_b128 v[176:179], v202 offset:1024
	ds_read_b128 v[180:183], v202 offset:2048
	ds_read_b128 v[184:187], v202 offset:3072
	ds_read_b128 v[198:201], v202 offset:4096
	ds_read_b128 v[204:207], v202 offset:5120
	ds_read_b128 v[208:211], v202 offset:6144
	ds_read_b128 v[222:225], v202 offset:7168
	global_load_lds_dwordx4 v[188:189], off
	v_lshl_add_u64 v[188:189], s[20:21], 0, v[166:167]
	s_add_i32 m0, s48, 0xe000
	s_nop 0
	global_load_lds_dwordx4 v[188:189], off
	s_waitcnt vmcnt(8)
	s_waitcnt lgkmcnt(0)
	s_barrier
	s_setprio 1
	s_waitcnt lgkmcnt(0)
	v_mfma_f32_16x16x32_bf16 v[142:145], v[114:117], v[172:175], v[142:145]
	v_mfma_f32_16x16x32_bf16 v[138:141], v[130:133], v[172:175], v[138:141]
	v_mfma_f32_16x16x32_bf16 v[110:113], v[114:117], v[180:183], v[110:113]
	v_mfma_f32_16x16x32_bf16 v[106:109], v[130:133], v[180:183], v[106:109]
	v_mfma_f32_16x16x32_bf16 v[94:97], v[114:117], v[198:201], v[94:97]
	v_mfma_f32_16x16x32_bf16 v[90:93], v[130:133], v[198:201], v[90:93]
	v_mfma_f32_16x16x32_bf16 v[78:81], v[114:117], v[208:211], v[78:81]
	v_mfma_f32_16x16x32_bf16 v[74:77], v[130:133], v[208:211], v[74:77]
	v_mfma_f32_16x16x32_bf16 v[142:145], v[126:129], v[176:179], v[142:145]
	v_mfma_f32_16x16x32_bf16 v[138:141], v[134:137], v[176:179], v[138:141]
	v_mfma_f32_16x16x32_bf16 v[110:113], v[126:129], v[184:187], v[110:113]
	v_mfma_f32_16x16x32_bf16 v[106:109], v[134:137], v[184:187], v[106:109]
	v_mfma_f32_16x16x32_bf16 v[94:97], v[126:129], v[204:207], v[94:97]
	v_mfma_f32_16x16x32_bf16 v[90:93], v[134:137], v[204:207], v[90:93]
	v_mfma_f32_16x16x32_bf16 v[78:81], v[126:129], v[222:225], v[78:81]
	v_mfma_f32_16x16x32_bf16 v[74:77], v[134:137], v[222:225], v[74:77]
	s_setprio 0
	s_setprio 1
	v_mfma_f32_16x16x32_bf16 v[122:125], v[146:149], v[172:175], v[122:125]
	v_mfma_f32_16x16x32_bf16 v[118:121], v[154:157], v[172:175], v[118:121]
	v_mfma_f32_16x16x32_bf16 v[102:105], v[146:149], v[180:183], v[102:105]
	v_mfma_f32_16x16x32_bf16 v[98:101], v[154:157], v[180:183], v[98:101]
	v_mfma_f32_16x16x32_bf16 v[86:89], v[146:149], v[198:201], v[86:89]
	v_mfma_f32_16x16x32_bf16 v[82:85], v[154:157], v[198:201], v[82:85]
	v_mfma_f32_16x16x32_bf16 v[70:73], v[146:149], v[208:211], v[70:73]
	v_mfma_f32_16x16x32_bf16 v[66:69], v[154:157], v[208:211], v[66:69]
	v_mfma_f32_16x16x32_bf16 v[122:125], v[150:153], v[176:179], v[122:125]
	v_mfma_f32_16x16x32_bf16 v[118:121], v[168:171], v[176:179], v[118:121]
	v_mfma_f32_16x16x32_bf16 v[102:105], v[150:153], v[184:187], v[102:105]
	v_mfma_f32_16x16x32_bf16 v[98:101], v[168:171], v[184:187], v[98:101]
	v_mfma_f32_16x16x32_bf16 v[86:89], v[150:153], v[204:207], v[86:89]
	v_mfma_f32_16x16x32_bf16 v[82:85], v[168:171], v[204:207], v[82:85]
	v_mfma_f32_16x16x32_bf16 v[70:73], v[150:153], v[222:225], v[70:73]
	v_mfma_f32_16x16x32_bf16 v[66:69], v[168:171], v[222:225], v[66:69]
	s_setprio 0
	s_barrier
	s_add_i32 s20, s30, s33
	v_lshl_add_u64 v[188:189], s[44:45], 0, v[0:1]
	s_mov_b32 m0, s20
	ds_read_b128 v[172:175], v202 offset:16384
	ds_read_b128 v[176:179], v202 offset:17408
	ds_read_b128 v[180:183], v202 offset:18432
	ds_read_b128 v[184:187], v202 offset:19456
	ds_read_b128 v[198:201], v202 offset:20480
	ds_read_b128 v[204:207], v202 offset:21504
	ds_read_b128 v[208:211], v202 offset:22528
	ds_read_b128 v[222:225], v202 offset:23552
	global_load_lds_dwordx4 v[188:189], off
	s_add_i32 m0, s20, 0x2000
	s_add_u32 s20, s44, 0xb0000
	v_lshl_add_u64 v[226:227], s[44:45], 0, v[158:159]
	s_addc_u32 s21, s45, 0
	s_add_i32 s30, s31, s33
	global_load_lds_dwordx4 v[226:227], off
	v_lshl_add_u64 v[228:229], s[20:21], 0, v[0:1]
	s_mov_b32 m0, s30
	v_lshl_add_u64 v[230:231], s[46:47], 0, v[160:161]
	global_load_lds_dwordx4 v[228:229], off
	v_lshl_add_u64 v[228:229], s[20:21], 0, v[158:159]
	s_add_i32 m0, s30, 0x2000
	s_nop 0
	global_load_lds_dwordx4 v[228:229], off
	v_lshl_add_u64 v[228:229], s[46:47], 0, v[162:163]
	s_mov_b32 m0, s48
	s_nop 0
	global_load_lds_dwordx4 v[228:229], off
	s_mov_b32 m0, s49
	s_nop 0
	global_load_lds_dwordx4 v[230:231], off
	s_waitcnt vmcnt(8)
	s_waitcnt lgkmcnt(0)
	s_barrier
; #define PG8_STAGE(bufoff, gbase, voff) do { _Pragma("unroll") for (int _i = 0; _i < 2; ++_i) \
;         __builtin_amdgcn_global_load_lds((const unsigned*)((const char*)(gbase) + (voff)[_i]), (PG8_LAS unsigned*)(lds + (bufoff) + ldsw + _i * 8192), 16, 0, 0); } while (0)
; #define PG8_LDA(dst, b, h) do { _Pragma("unroll") for (int m = 0; m < 4; ++m) _Pragma("unroll") for (int k = 0; k < 2; ++k) dst[m][k] = *(const PG8_LAS bf16x8*)(lds + PG8_SA(b, h) + aoff + m * 2048 + k * 1024); } while (0)
; #define PG8_LDB(dst, b, h) do { _Pragma("unroll") for (int n = 0; n < 2; ++n) _Pragma("unroll") for (int k = 0; k < 2; ++k) dst[n][k] = *(const PG8_LAS bf16x8*)(lds + PG8_SB(b, h) + boff + n * 2048 + k * 1024); } while (0)
; #define PG8_MMA(ai, bj, At, Bt) do { __builtin_amdgcn_s_setprio(1); _Pragma("unroll") for (int m = 0; m < 4; ++m) _Pragma("unroll") for (int n = 0; n < 2; ++n) _Pragma("unroll") for (int k = 0; k < 2; ++k) \
;         acc[ai][bj][m][n] = __builtin_amdgcn_mfma_f32_16x16x32_bf16(Bt[n][k], At[m][k], acc[ai][bj][m][n], 0, 0, 0); __builtin_amdgcn_s_setprio(0); } while (0)
; #define PG8_WAIT_V(n) asm volatile("s_waitcnt vmcnt(" #n ")" ::: "memory")
; #define PG8_WAIT_L(n) asm volatile("s_waitcnt lgkmcnt(" #n ")" ::: "memory")
; #define PG8_BAR __builtin_amdgcn_s_barrier()
; #define PG8_SCHED __builtin_amdgcn_sched_barrier(0)
; template <class Epi, class Sched, bool ALIGN_EPI = false, bool SP2 = false>
; __device__ __forceinline__ void gemm_phase(PG8_LAS unsigned char* lds, const Gemm g, const Sched& S, const Epi& E) {
;     ...
;             PG8_WAIT_V(8); PG8_WAIT_L(0); PG8_BAR; PG8_MMA(1, 0, At, B0); PG8_MMA(1, 1, At, B1); PG8_BAR; PG8_SCHED;
;             PG8_LDB(B0, 1, 0); PG8_LDB(B1, 1, 1); PG8_SCHED; PG8_LDA(At, 1, 0); PG8_STAGE(PG8_SA(0, 1), a2 + hstep, voffA);
;             PG8_WAIT_V(8); PG8_WAIT_L(0); PG8_BAR; PG8_MMA(0, 0, At, B0); PG8_MMA(0, 1, At, B1); PG8_BAR; PG8_SCHED;
	s_setprio 1
	s_waitcnt lgkmcnt(0)
	v_mfma_f32_16x16x32_bf16 v[62:65], v[114:117], v[172:175], v[62:65]
	v_mfma_f32_16x16x32_bf16 v[58:61], v[130:133], v[172:175], v[58:61]
	v_mfma_f32_16x16x32_bf16 v[46:49], v[114:117], v[180:183], v[46:49]
	v_mfma_f32_16x16x32_bf16 v[42:45], v[130:133], v[180:183], v[42:45]
	v_mfma_f32_16x16x32_bf16 v[30:33], v[114:117], v[198:201], v[30:33]
	v_mfma_f32_16x16x32_bf16 v[26:29], v[130:133], v[198:201], v[26:29]
	v_mfma_f32_16x16x32_bf16 v[14:17], v[114:117], v[208:211], v[14:17]
	v_mfma_f32_16x16x32_bf16 v[10:13], v[130:133], v[208:211], v[10:13]
	v_mfma_f32_16x16x32_bf16 v[62:65], v[126:129], v[176:179], v[62:65]
	v_mfma_f32_16x16x32_bf16 v[58:61], v[134:137], v[176:179], v[58:61]
	v_mfma_f32_16x16x32_bf16 v[46:49], v[126:129], v[184:187], v[46:49]
	v_mfma_f32_16x16x32_bf16 v[42:45], v[134:137], v[184:187], v[42:45]
	v_mfma_f32_16x16x32_bf16 v[30:33], v[126:129], v[204:207], v[30:33]
	v_mfma_f32_16x16x32_bf16 v[26:29], v[134:137], v[204:207], v[26:29]
	v_mfma_f32_16x16x32_bf16 v[14:17], v[126:129], v[222:225], v[14:17]
	v_mfma_f32_16x16x32_bf16 v[10:13], v[134:137], v[222:225], v[10:13]
	s_setprio 0
	s_setprio 1
	v_mfma_f32_16x16x32_bf16 v[54:57], v[146:149], v[172:175], v[54:57]
	v_mfma_f32_16x16x32_bf16 v[50:53], v[154:157], v[172:175], v[50:53]
	v_mfma_f32_16x16x32_bf16 v[38:41], v[146:149], v[180:183], v[38:41]
	v_mfma_f32_16x16x32_bf16 v[34:37], v[154:157], v[180:183], v[34:37]
	v_mfma_f32_16x16x32_bf16 v[22:25], v[146:149], v[198:201], v[22:25]
	v_mfma_f32_16x16x32_bf16 v[18:21], v[154:157], v[198:201], v[18:21]
	v_mfma_f32_16x16x32_bf16 v[6:9], v[146:149], v[208:211], v[6:9]
	v_mfma_f32_16x16x32_bf16 v[2:5], v[154:157], v[208:211], v[2:5]
	v_mfma_f32_16x16x32_bf16 v[54:57], v[150:153], v[176:179], v[54:57]
	v_mfma_f32_16x16x32_bf16 v[50:53], v[168:171], v[176:179], v[50:53]
	v_mfma_f32_16x16x32_bf16 v[38:41], v[150:153], v[184:187], v[38:41]
	v_mfma_f32_16x16x32_bf16 v[34:37], v[168:171], v[184:187], v[34:37]
	v_mfma_f32_16x16x32_bf16 v[22:25], v[150:153], v[204:207], v[22:25]
	v_mfma_f32_16x16x32_bf16 v[18:21], v[168:171], v[204:207], v[18:21]
	v_mfma_f32_16x16x32_bf16 v[6:9], v[150:153], v[222:225], v[6:9]
	v_mfma_f32_16x16x32_bf16 v[2:5], v[168:171], v[222:225], v[2:5]
	s_setprio 0
	s_barrier
	s_add_i32 s30, 0, 0x18000
	s_add_i32 s31, 0, 0x1c000
	v_add_u32_e32 v134, s30, v191
	v_add_u32_e32 v168, s31, v191
	ds_read_b128 v[114:117], v134
	ds_read_b128 v[126:129], v134 offset:1024
	ds_read_b128 v[130:133], v134 offset:2048
	ds_read_b128 v[134:137], v134 offset:3072
	ds_read_b128 v[146:149], v168
	ds_read_b128 v[150:153], v168 offset:1024
	ds_read_b128 v[154:157], v168 offset:2048
	ds_read_b128 v[168:171], v168 offset:3072
	s_add_u32 s20, s46, 0xb0000
	s_addc_u32 s21, s47, 0
	s_mov_b32 m0, s50
	v_lshl_add_u64 v[232:233], s[20:21], 0, v[162:163]
	ds_read_b128 v[172:175], v202 offset:32768
	ds_read_b128 v[176:179], v202 offset:33792
	ds_read_b128 v[180:183], v202 offset:34816
	ds_read_b128 v[184:187], v202 offset:35840
	ds_read_b128 v[198:201], v202 offset:36864
	ds_read_b128 v[204:207], v202 offset:37888
	ds_read_b128 v[208:211], v202 offset:38912
	ds_read_b128 v[222:225], v202 offset:39936
	global_load_lds_dwordx4 v[232:233], off
	v_lshl_add_u64 v[232:233], s[20:21], 0, v[160:161]
	s_mov_b32 m0, s51
	s_nop 0
	global_load_lds_dwordx4 v[232:233], off
	s_waitcnt vmcnt(8)
	s_waitcnt lgkmcnt(0)
	s_barrier
	s_setprio 1
	s_waitcnt lgkmcnt(0)
	v_mfma_f32_16x16x32_bf16 v[142:145], v[114:117], v[172:175], v[142:145]
	v_mfma_f32_16x16x32_bf16 v[138:141], v[130:133], v[172:175], v[138:141]
	v_mfma_f32_16x16x32_bf16 v[110:113], v[114:117], v[180:183], v[110:113]
	v_mfma_f32_16x16x32_bf16 v[106:109], v[130:133], v[180:183], v[106:109]
	v_mfma_f32_16x16x32_bf16 v[94:97], v[114:117], v[198:201], v[94:97]
	v_mfma_f32_16x16x32_bf16 v[90:93], v[130:133], v[198:201], v[90:93]
	v_mfma_f32_16x16x32_bf16 v[78:81], v[114:117], v[208:211], v[78:81]
	v_mfma_f32_16x16x32_bf16 v[74:77], v[130:133], v[208:211], v[74:77]
	v_mfma_f32_16x16x32_bf16 v[142:145], v[126:129], v[176:179], v[142:145]
	v_mfma_f32_16x16x32_bf16 v[138:141], v[134:137], v[176:179], v[138:141]
	v_mfma_f32_16x16x32_bf16 v[110:113], v[126:129], v[184:187], v[110:113]
	v_mfma_f32_16x16x32_bf16 v[106:109], v[134:137], v[184:187], v[106:109]
	v_mfma_f32_16x16x32_bf16 v[94:97], v[126:129], v[204:207], v[94:97]
	v_mfma_f32_16x16x32_bf16 v[90:93], v[134:137], v[204:207], v[90:93]
	v_mfma_f32_16x16x32_bf16 v[78:81], v[126:129], v[222:225], v[78:81]
	v_mfma_f32_16x16x32_bf16 v[74:77], v[134:137], v[222:225], v[74:77]
	s_setprio 0
	s_setprio 1
	v_mfma_f32_16x16x32_bf16 v[122:125], v[146:149], v[172:175], v[122:125]
	v_mfma_f32_16x16x32_bf16 v[118:121], v[154:157], v[172:175], v[118:121]
	v_mfma_f32_16x16x32_bf16 v[102:105], v[146:149], v[180:183], v[102:105]
	v_mfma_f32_16x16x32_bf16 v[98:101], v[154:157], v[180:183], v[98:101]
	v_mfma_f32_16x16x32_bf16 v[86:89], v[146:149], v[198:201], v[86:89]
	v_mfma_f32_16x16x32_bf16 v[82:85], v[154:157], v[198:201], v[82:85]
	v_mfma_f32_16x16x32_bf16 v[70:73], v[146:149], v[208:211], v[70:73]
	v_mfma_f32_16x16x32_bf16 v[66:69], v[154:157], v[208:211], v[66:69]
	v_mfma_f32_16x16x32_bf16 v[122:125], v[150:153], v[176:179], v[122:125]
	v_mfma_f32_16x16x32_bf16 v[118:121], v[168:171], v[176:179], v[118:121]
	v_mfma_f32_16x16x32_bf16 v[102:105], v[150:153], v[184:187], v[102:105]
	v_mfma_f32_16x16x32_bf16 v[98:101], v[168:171], v[184:187], v[98:101]
	v_mfma_f32_16x16x32_bf16 v[86:89], v[150:153], v[204:207], v[86:89]
	v_mfma_f32_16x16x32_bf16 v[82:85], v[168:171], v[204:207], v[82:85]
	v_mfma_f32_16x16x32_bf16 v[70:73], v[150:153], v[222:225], v[70:73]
	v_mfma_f32_16x16x32_bf16 v[66:69], v[168:171], v[222:225], v[66:69]
	s_setprio 0
	s_barrier
; #define PG8_STAGE(bufoff, gbase, voff) do { _Pragma("unroll") for (int _i = 0; _i < 2; ++_i) \
;         __builtin_amdgcn_global_load_lds((const unsigned*)((const char*)(gbase) + (voff)[_i]), (PG8_LAS unsigned*)(lds + (bufoff) + ldsw + _i * 8192), 16, 0, 0); } while (0)
; #define PG8_LDA(dst, b, h) do { _Pragma("unroll") for (int m = 0; m < 4; ++m) _Pragma("unroll") for (int k = 0; k < 2; ++k) dst[m][k] = *(const PG8_LAS bf16x8*)(lds + PG8_SA(b, h) + aoff + m * 2048 + k * 1024); } while (0)
; #define PG8_MMA(ai, bj, At, Bt) do { __builtin_amdgcn_s_setprio(1); _Pragma("unroll") for (int m = 0; m < 4; ++m) _Pragma("unroll") for (int n = 0; n < 2; ++n) _Pragma("unroll") for (int k = 0; k < 2; ++k) \
;         acc[ai][bj][m][n] = __builtin_amdgcn_mfma_f32_16x16x32_bf16(Bt[n][k], At[m][k], acc[ai][bj][m][n], 0, 0, 0); __builtin_amdgcn_s_setprio(0); } while (0)
; #define PG8_WAIT_V(n) asm volatile("s_waitcnt vmcnt(" #n ")" ::: "memory")
; #define PG8_WAIT_L(n) asm volatile("s_waitcnt lgkmcnt(" #n ")" ::: "memory")
; #define PG8_BAR __builtin_amdgcn_s_barrier()
; #define PG8_SCHED __builtin_amdgcn_sched_barrier(0)
; template <class Epi, class Sched, bool ALIGN_EPI = false, bool SP2 = false>
; __device__ __forceinline__ void gemm_phase(PG8_LAS unsigned char* lds, const Gemm g, const Sched& S, const Epi& E) {
;     ...
;         for (int t = 0; t < nt; t += 2) {
;             const bool last = (t == nt - 2);
;             const char* a1 = cA + (size_t)(t + 1) * kstep;
;             const char* a2 = last ? nA : cA + (size_t)(t + 2) * kstep; const char* b2 = last ? nB : cB + (size_t)(t + 2) * kstep;
;             const char* a3 = a2 + kstep; const char* b3 = b2 + kstep;
;     ...
;             PG8_LDA(At, 1, 1); PG8_STAGE(PG8_SB(1, 0), b3, voffB); PG8_STAGE(PG8_SB(1, 1), b3 + hstep, voffB); PG8_STAGE(PG8_SA(1, 0), a3, voffA);
;             PG8_WAIT_V(8); PG8_WAIT_L(0); PG8_BAR; PG8_MMA(1, 0, At, B0); PG8_MMA(1, 1, At, B1); PG8_BAR; PG8_SCHED;
	s_add_i32 s20, s30, s33
	v_lshl_add_u64 v[188:189], v[188:189], 0, s[0:1]
	s_mov_b32 m0, s20
	ds_read_b128 v[172:175], v202 offset:49152
	ds_read_b128 v[176:179], v202 offset:50176
	ds_read_b128 v[180:183], v202 offset:51200
	ds_read_b128 v[184:187], v202 offset:52224
	ds_read_b128 v[198:201], v202 offset:53248
	ds_read_b128 v[204:207], v202 offset:54272
	ds_read_b128 v[208:211], v202 offset:55296
	ds_read_b128 v[222:225], v202 offset:56320
	global_load_lds_dwordx4 v[188:189], off
	s_add_i32 m0, s20, 0x2000
	s_add_u32 s20, s44, 0xb0080
	v_lshl_add_u64 v[188:189], v[226:227], 0, s[0:1]
	s_addc_u32 s21, s45, 0
	s_add_i32 s30, s31, s33
	global_load_lds_dwordx4 v[188:189], off
	v_lshl_add_u64 v[188:189], s[20:21], 0, v[0:1]
	s_mov_b32 m0, s30
	s_nop 0
	global_load_lds_dwordx4 v[188:189], off
	v_lshl_add_u64 v[188:189], s[20:21], 0, v[158:159]
	s_add_i32 m0, s30, 0x2000
	s_nop 0
	global_load_lds_dwordx4 v[188:189], off
	v_lshl_add_u64 v[188:189], v[228:229], 0, s[0:1]
	s_mov_b32 m0, s54
	s_nop 0
	global_load_lds_dwordx4 v[188:189], off
	v_lshl_add_u64 v[188:189], v[230:231], 0, s[0:1]
	s_mov_b32 m0, s55
	s_nop 0
	global_load_lds_dwordx4 v[188:189], off
	s_waitcnt vmcnt(8)
	s_waitcnt lgkmcnt(0)
	s_barrier
	s_setprio 1
	s_waitcnt lgkmcnt(0)
	v_mfma_f32_16x16x32_bf16 v[62:65], v[114:117], v[172:175], v[62:65]
	v_mfma_f32_16x16x32_bf16 v[58:61], v[130:133], v[172:175], v[58:61]
	v_mfma_f32_16x16x32_bf16 v[46:49], v[114:117], v[180:183], v[46:49]
	v_mfma_f32_16x16x32_bf16 v[42:45], v[130:133], v[180:183], v[42:45]
	v_mfma_f32_16x16x32_bf16 v[30:33], v[114:117], v[198:201], v[30:33]
	v_mfma_f32_16x16x32_bf16 v[26:29], v[130:133], v[198:201], v[26:29]
	v_mfma_f32_16x16x32_bf16 v[14:17], v[114:117], v[208:211], v[14:17]
	v_mfma_f32_16x16x32_bf16 v[10:13], v[130:133], v[208:211], v[10:13]
	v_mfma_f32_16x16x32_bf16 v[62:65], v[126:129], v[176:179], v[62:65]
	v_mfma_f32_16x16x32_bf16 v[58:61], v[134:137], v[176:179], v[58:61]
	v_mfma_f32_16x16x32_bf16 v[46:49], v[126:129], v[184:187], v[46:49]
	v_mfma_f32_16x16x32_bf16 v[42:45], v[134:137], v[184:187], v[42:45]
	v_mfma_f32_16x16x32_bf16 v[30:33], v[126:129], v[204:207], v[30:33]
	v_mfma_f32_16x16x32_bf16 v[26:29], v[134:137], v[204:207], v[26:29]
	v_mfma_f32_16x16x32_bf16 v[14:17], v[126:129], v[222:225], v[14:17]
	v_mfma_f32_16x16x32_bf16 v[10:13], v[134:137], v[222:225], v[10:13]
	s_setprio 0
	s_setprio 1
	v_mfma_f32_16x16x32_bf16 v[54:57], v[146:149], v[172:175], v[54:57]
	v_mfma_f32_16x16x32_bf16 v[50:53], v[154:157], v[172:175], v[50:53]
	v_mfma_f32_16x16x32_bf16 v[38:41], v[146:149], v[180:183], v[38:41]
	v_mfma_f32_16x16x32_bf16 v[34:37], v[154:157], v[180:183], v[34:37]
	v_mfma_f32_16x16x32_bf16 v[22:25], v[146:149], v[198:201], v[22:25]
	v_mfma_f32_16x16x32_bf16 v[18:21], v[154:157], v[198:201], v[18:21]
	v_mfma_f32_16x16x32_bf16 v[6:9], v[146:149], v[208:211], v[6:9]
	v_mfma_f32_16x16x32_bf16 v[2:5], v[154:157], v[208:211], v[2:5]
	v_mfma_f32_16x16x32_bf16 v[54:57], v[150:153], v[176:179], v[54:57]
	v_mfma_f32_16x16x32_bf16 v[50:53], v[168:171], v[176:179], v[50:53]
	v_mfma_f32_16x16x32_bf16 v[38:41], v[150:153], v[184:187], v[38:41]
	v_mfma_f32_16x16x32_bf16 v[34:37], v[168:171], v[184:187], v[34:37]
	v_mfma_f32_16x16x32_bf16 v[22:25], v[150:153], v[204:207], v[22:25]
	v_mfma_f32_16x16x32_bf16 v[18:21], v[168:171], v[204:207], v[18:21]
	v_mfma_f32_16x16x32_bf16 v[6:9], v[150:153], v[222:225], v[6:9]
	v_mfma_f32_16x16x32_bf16 v[2:5], v[168:171], v[222:225], v[2:5]
	s_setprio 0
	s_add_i32 s59, s59, 2
	s_add_u32 s34, s34, 0x100
	s_addc_u32 s35, s35, 0
	s_mov_b64 s[20:21], s[42:43]
	s_cmp_gt_u32 s59, 41
	s_cbranch_scc1 .Lrot_exit_p5
	s_add_u32 s42, s20, 0x100
	s_addc_u32 s43, s21, 0
	s_add_i32 s30, 0, 0x10000
	s_cmp_eq_u32 s59, 40
	s_cselect_b32 s47, s11, s43
	s_cselect_b32 s46, s10, s42
	s_cselect_b32 s45, s15, s35
	s_cselect_b32 s44, s14, s34
	s_add_i32 s31, 0, 0x14000
	v_add_u32_e32 v134, s30, v191
	v_add_u32_e32 v168, s31, v191
	s_barrier
	s_branch .LBB0_868
